# v78 + nt (streaming) policy on P0's once-read f32 weight and x-row loads
# baseline (speedup 1.0000x reference)
.LBB0_17:
	v_lshl_add_u64 v[2:3], s[6:7], 0, v[202:203]
	global_load_dwordx4 v[86:89], v[2:3], off nt
	global_load_dwordx4 v[66:69], v[2:3], off offset:1024 nt
	global_load_dwordx4 v[54:57], v[2:3], off offset:2048 nt
	global_load_dwordx4 v[50:53], v[2:3], off offset:3072 nt
	v_add_co_u32_e32 v4, vcc, 0x1000, v2
	s_waitcnt vmcnt(17)
	v_lshl_add_u64 v[6:7], s[6:7], 0, v[172:173]
	v_addc_co_u32_e32 v5, vcc, 0, v3, vcc
	global_load_dwordx4 v[46:49], v[4:5], off nt
	global_load_dwordx4 v[42:45], v[4:5], off offset:1024 nt
	global_load_dwordx4 v[38:41], v[4:5], off offset:2048 nt
	global_load_dwordx4 v[34:37], v[4:5], off offset:3072 nt
	v_add_co_u32_e32 v4, vcc, 0x2000, v2
	s_mov_b32 s0, 0xf800000
	s_nop 0
	v_addc_co_u32_e32 v5, vcc, 0, v3, vcc
	global_load_dwordx4 v[30:33], v[4:5], off nt
	global_load_dwordx4 v[26:29], v[4:5], off offset:1024 nt
	global_load_dwordx4 v[22:25], v[4:5], off offset:2048 nt
	global_load_dwordx4 v[18:21], v[4:5], off offset:3072 nt
	v_add_co_u32_e32 v2, vcc, 0x3000, v2
	s_add_i32 s13, s13, s12
	s_nop 0
	v_addc_co_u32_e32 v3, vcc, 0, v3, vcc
	global_load_dwordx4 v[14:17], v[2:3], off nt
	global_load_dwordx4 v[10:13], v[2:3], off offset:1024 nt
	s_nop 0
	global_load_dwordx4 v[2:5], v[2:3], off offset:2048 nt
	s_nop 0
	global_load_dwordx4 v[6:9], v[6:7], off nt
	s_nop 0
	global_load_dwordx4 v[90:93], v[174:175], off
	global_load_dwordx4 v[94:97], v[176:177], off
	global_load_dwordx4 v[78:81], v[174:175], off offset:1024
	global_load_dwordx4 v[82:85], v[176:177], off offset:1024
	global_load_dwordx4 v[70:73], v[174:175], off offset:2048
	global_load_dwordx4 v[74:77], v[176:177], off offset:2048
	global_load_dwordx4 v[58:61], v[174:175], off offset:3072
	global_load_dwordx4 v[62:65], v[176:177], off offset:3072
	s_add_u32 s6, s6, s36
	s_addc_u32 s7, s7, s37
	s_cmpk_lt_i32 s13, 0x4000
	s_waitcnt vmcnt(23)
	v_mov_b32_e32 v98, v87
	v_mov_b32_e32 v99, v88
	v_mov_b32_e32 v100, v86
	v_mov_b32_e32 v101, v89
	v_pk_add_f32 v[98:99], v[98:99], v[100:101]
	s_waitcnt vmcnt(22)
	v_mov_b32_e32 v100, v67
	v_mov_b32_e32 v101, v68
	v_mov_b32_e32 v102, v66
	v_mov_b32_e32 v103, v69
	v_pk_add_f32 v[100:101], v[100:101], v[102:103]
	v_add_f32_e32 v98, v98, v99
	v_pk_add_f32 v[100:101], v[100:101], v[100:101] op_sel:[0,1] op_sel_hi:[1,0]
	v_add_f32_e32 v98, 0, v98
	s_waitcnt vmcnt(21)
	v_add_f32_e32 v102, v54, v55
	v_add_f32_e32 v104, v56, v57
	s_waitcnt vmcnt(20)
	v_mov_b32_e32 v99, v50
	v_mov_b32_e32 v101, v51
	v_mov_b32_e32 v103, v52
	v_mov_b32_e32 v105, v53
	v_pk_add_f32 v[98:99], v[98:99], v[100:101]
	v_pk_add_f32 v[100:101], v[102:103], v[104:105]
	s_waitcnt vmcnt(19)
	v_mov_b32_e32 v102, v46
	v_pk_add_f32 v[98:99], v[98:99], v[100:101]
	v_mov_b32_e32 v100, v47
	v_mov_b32_e32 v101, v48
	v_mov_b32_e32 v103, v49
	v_pk_add_f32 v[100:101], v[100:101], v[102:103]
	v_pk_add_f32 v[98:99], v[98:99], v[98:99] op_sel:[0,1] op_sel_hi:[1,0]
	v_pk_add_f32 v[100:101], v[100:101], v[100:101] op_sel:[0,1] op_sel_hi:[1,0]
	s_waitcnt vmcnt(18)
	v_add_f32_e32 v102, v42, v43
	v_add_f32_e32 v104, v44, v45
	s_waitcnt vmcnt(17)
	v_mov_b32_e32 v99, v38
	v_mov_b32_e32 v101, v39
	v_mov_b32_e32 v103, v40
	v_mov_b32_e32 v105, v41
	v_pk_add_f32 v[98:99], v[98:99], v[100:101]
	v_pk_add_f32 v[100:101], v[102:103], v[104:105]
	s_waitcnt vmcnt(16)
	v_mov_b32_e32 v102, v34
	v_pk_add_f32 v[98:99], v[98:99], v[100:101]
	v_mov_b32_e32 v100, v35
	v_mov_b32_e32 v101, v36
	v_mov_b32_e32 v103, v37
	v_pk_add_f32 v[100:101], v[100:101], v[102:103]
	v_pk_add_f32 v[98:99], v[98:99], v[98:99] op_sel:[0,1] op_sel_hi:[1,0]
	v_pk_add_f32 v[100:101], v[100:101], v[100:101] op_sel:[0,1] op_sel_hi:[1,0]
	s_waitcnt vmcnt(15)
	v_add_f32_e32 v102, v30, v31
	v_add_f32_e32 v104, v32, v33
	s_waitcnt vmcnt(14)
	v_mov_b32_e32 v99, v26
	v_mov_b32_e32 v101, v27
	v_mov_b32_e32 v103, v28
	v_mov_b32_e32 v105, v29
	v_pk_add_f32 v[98:99], v[98:99], v[100:101]
	v_pk_add_f32 v[100:101], v[102:103], v[104:105]
	s_waitcnt vmcnt(13)
	v_mov_b32_e32 v102, v22
	v_pk_add_f32 v[98:99], v[98:99], v[100:101]
	v_mov_b32_e32 v100, v23
	v_mov_b32_e32 v101, v24
	v_mov_b32_e32 v103, v25
	v_pk_add_f32 v[100:101], v[100:101], v[102:103]
	v_pk_add_f32 v[98:99], v[98:99], v[98:99] op_sel:[0,1] op_sel_hi:[1,0]
	v_pk_add_f32 v[100:101], v[100:101], v[100:101] op_sel:[0,1] op_sel_hi:[1,0]
	s_waitcnt vmcnt(12)
	v_add_f32_e32 v102, v18, v19
	v_add_f32_e32 v104, v20, v21
	s_waitcnt vmcnt(11)
	v_mov_b32_e32 v99, v14
	v_mov_b32_e32 v101, v15
	v_mov_b32_e32 v103, v16
	v_mov_b32_e32 v105, v17
	v_pk_add_f32 v[98:99], v[98:99], v[100:101]
	v_pk_add_f32 v[100:101], v[102:103], v[104:105]
	s_waitcnt vmcnt(10)
	v_mov_b32_e32 v102, v10
	v_pk_add_f32 v[98:99], v[98:99], v[100:101]
	v_mov_b32_e32 v100, v11
	v_mov_b32_e32 v101, v12
	v_mov_b32_e32 v103, v13
	v_pk_add_f32 v[100:101], v[100:101], v[102:103]
	v_pk_add_f32 v[98:99], v[98:99], v[98:99] op_sel:[0,1] op_sel_hi:[1,0]
	v_pk_add_f32 v[100:101], v[100:101], v[100:101] op_sel:[0,1] op_sel_hi:[1,0]
	s_waitcnt vmcnt(9)
	v_add_f32_e32 v102, v2, v3
	v_add_f32_e32 v104, v4, v5
	s_waitcnt vmcnt(8)
	v_mov_b32_e32 v99, v6
	v_mov_b32_e32 v101, v7
	v_mov_b32_e32 v103, v8
	v_mov_b32_e32 v105, v9
	v_pk_add_f32 v[98:99], v[98:99], v[100:101]
	v_pk_add_f32 v[100:101], v[102:103], v[104:105]
	s_nop 0
	v_pk_add_f32 v[98:99], v[98:99], v[100:101]
	s_nop 0
	v_add_f32_e32 v98, v98, v99
	ds_bpermute_b32 v99, v125, v98
	s_waitcnt lgkmcnt(0)
	v_add_f32_e32 v98, v98, v99
	ds_bpermute_b32 v99, v207, v98
	s_waitcnt lgkmcnt(0)
	v_add_f32_e32 v98, v98, v99
	ds_bpermute_b32 v99, v216, v98
	s_waitcnt lgkmcnt(0)
	v_add_f32_e32 v98, v98, v99
	ds_bpermute_b32 v99, v233, v98
	s_waitcnt lgkmcnt(0)
	v_add_f32_e32 v98, v98, v99
	ds_bpermute_b32 v99, v234, v98
	s_waitcnt lgkmcnt(0)
	v_add_f32_e32 v98, v98, v99
	ds_bpermute_b32 v99, v235, v98
	s_waitcnt lgkmcnt(0)
	v_add_f32_e32 v104, v98, v99
	v_fmamk_f32 v227, v104, 0xb9800000, v87
	v_fmamk_f32 v226, v104, 0xb9800000, v86
	v_fmamk_f32 v89, v104, 0xb9800000, v89
	v_fmac_f32_e32 v88, 0xb9800000, v104
	v_pk_mul_f32 v[86:87], v[88:89], v[88:89]
	v_pk_mul_f32 v[98:99], v[226:227], v[226:227]
	v_fmamk_f32 v225, v104, 0xb9800000, v67
	v_pk_mov_b32 v[100:101], v[98:99], v[86:87] op_sel:[1,0]
	v_mov_b32_e32 v99, v87
	v_pk_add_f32 v[86:87], v[100:101], v[98:99]
	v_fmamk_f32 v224, v104, 0xb9800000, v66
	v_fmamk_f32 v69, v104, 0xb9800000, v69
	v_fmac_f32_e32 v68, 0xb9800000, v104
	v_pk_add_f32 v[98:99], v[86:87], v[86:87] op_sel_hi:[0,1]
	v_pk_mul_f32 v[66:67], v[68:69], v[68:69]
	v_pk_mul_f32 v[86:87], v[224:225], v[224:225]
	v_fmac_f32_e32 v56, 0xb9800000, v104
	v_pk_mov_b32 v[100:101], v[86:87], v[66:67] op_sel:[1,0]
	v_mov_b32_e32 v87, v67
	v_pk_add_f32 v[66:67], v[100:101], v[86:87]
	v_fmamk_f32 v86, v104, 0xb9800000, v54
	v_fmamk_f32 v87, v104, 0xb9800000, v55
	v_mul_f32_e32 v54, v86, v86
	v_pk_fma_f32 v[54:55], v[86:87], v[86:87], v[54:55] op_sel_hi:[1,1,0]
	v_fmamk_f32 v57, v104, 0xb9800000, v57
	v_mul_f32_e32 v54, v56, v56
	v_pk_add_f32 v[100:101], v[66:67], v[66:67] op_sel_hi:[0,1]
	v_pk_fma_f32 v[102:103], v[56:57], v[56:57], v[54:55] op_sel_hi:[1,1,0]
	v_fmamk_f32 v67, v104, 0xb9800000, v53
	v_fmamk_f32 v66, v104, 0xb9800000, v52
	v_fmamk_f32 v51, v104, 0xb9800000, v51
	v_fmac_f32_e32 v50, 0xb9800000, v104
	v_mul_f32_e32 v54, v50, v50
	v_mul_f32_e32 v102, v51, v51
	v_mul_f32_e32 v98, v66, v66
	v_mul_f32_e32 v100, v67, v67
	v_pk_add_f32 v[52:53], v[54:55], v[102:103]
	v_pk_add_f32 v[54:55], v[98:99], v[100:101]
	v_fmamk_f32 v223, v104, 0xb9800000, v47
	v_fmamk_f32 v222, v104, 0xb9800000, v46
	v_fmamk_f32 v49, v104, 0xb9800000, v49
	v_fmac_f32_e32 v48, 0xb9800000, v104
	v_fmamk_f32 v220, v104, 0xb9800000, v42
	v_pk_add_f32 v[52:53], v[52:53], v[54:55]
	v_pk_mul_f32 v[46:47], v[48:49], v[48:49]
	v_pk_mul_f32 v[54:55], v[222:223], v[222:223]
	v_fmamk_f32 v221, v104, 0xb9800000, v43
	v_mul_f32_e32 v42, v220, v220
	v_pk_mov_b32 v[98:99], v[54:55], v[46:47] op_sel:[1,0]
	v_mov_b32_e32 v55, v47
	v_fmac_f32_e32 v44, 0xb9800000, v104
	v_pk_fma_f32 v[42:43], v[220:221], v[220:221], v[42:43] op_sel_hi:[1,1,0]
	v_pk_add_f32 v[46:47], v[98:99], v[54:55]
	v_fmamk_f32 v45, v104, 0xb9800000, v45
	v_mul_f32_e32 v42, v44, v44
	v_pk_add_f32 v[52:53], v[52:53], v[52:53] op_sel_hi:[0,1]
	v_pk_add_f32 v[54:55], v[46:47], v[46:47] op_sel_hi:[0,1]
	v_pk_fma_f32 v[98:99], v[44:45], v[44:45], v[42:43] op_sel_hi:[1,1,0]
	v_fmamk_f32 v47, v104, 0xb9800000, v41
	v_fmamk_f32 v46, v104, 0xb9800000, v40
	v_fmamk_f32 v39, v104, 0xb9800000, v39
	v_fmac_f32_e32 v38, 0xb9800000, v104
	v_mul_f32_e32 v42, v38, v38
	v_mul_f32_e32 v98, v39, v39
	v_mul_f32_e32 v54, v46, v46
	v_mul_f32_e32 v52, v47, v47
	v_pk_add_f32 v[40:41], v[42:43], v[98:99]
	v_pk_add_f32 v[42:43], v[54:55], v[52:53]
	v_fmamk_f32 v35, v104, 0xb9800000, v35
	v_fmamk_f32 v34, v104, 0xb9800000, v34
	v_fmamk_f32 v37, v104, 0xb9800000, v37
	v_fmac_f32_e32 v36, 0xb9800000, v104
	v_fmamk_f32 v218, v104, 0xb9800000, v30
	v_pk_add_f32 v[40:41], v[40:41], v[42:43]
	v_pk_mul_f32 v[42:43], v[36:37], v[36:37]
	v_pk_mul_f32 v[52:53], v[34:35], v[34:35]
	v_fmamk_f32 v219, v104, 0xb9800000, v31
	v_mul_f32_e32 v30, v218, v218
	v_pk_mov_b32 v[54:55], v[52:53], v[42:43] op_sel:[1,0]
	v_mov_b32_e32 v53, v43
	v_fmac_f32_e32 v32, 0xb9800000, v104
	v_pk_fma_f32 v[30:31], v[218:219], v[218:219], v[30:31] op_sel_hi:[1,1,0]
	v_pk_add_f32 v[42:43], v[54:55], v[52:53]
	v_fmamk_f32 v33, v104, 0xb9800000, v33
	v_mul_f32_e32 v30, v32, v32
	v_pk_add_f32 v[40:41], v[40:41], v[40:41] op_sel_hi:[0,1]
	v_pk_add_f32 v[42:43], v[42:43], v[42:43] op_sel_hi:[0,1]
	v_pk_fma_f32 v[52:53], v[32:33], v[32:33], v[30:31] op_sel_hi:[1,1,0]
	v_fmamk_f32 v129, v104, 0xb9800000, v29
	v_fmamk_f32 v128, v104, 0xb9800000, v28
	v_fmamk_f32 v27, v104, 0xb9800000, v27
	v_fmac_f32_e32 v26, 0xb9800000, v104
	v_mul_f32_e32 v30, v26, v26
	v_mul_f32_e32 v52, v27, v27
	v_mul_f32_e32 v42, v128, v128
	v_mul_f32_e32 v40, v129, v129
	v_pk_add_f32 v[28:29], v[30:31], v[52:53]
	v_pk_add_f32 v[30:31], v[42:43], v[40:41]
	v_fmamk_f32 v127, v104, 0xb9800000, v23
	v_fmamk_f32 v126, v104, 0xb9800000, v22
	v_fmamk_f32 v25, v104, 0xb9800000, v25
	v_fmac_f32_e32 v24, 0xb9800000, v104
	v_fmamk_f32 v122, v104, 0xb9800000, v18
	v_pk_add_f32 v[28:29], v[28:29], v[30:31]
	v_pk_mul_f32 v[22:23], v[24:25], v[24:25]
	v_pk_mul_f32 v[30:31], v[126:127], v[126:127]
	v_fmamk_f32 v123, v104, 0xb9800000, v19
	v_mul_f32_e32 v18, v122, v122
	v_pk_mov_b32 v[40:41], v[30:31], v[22:23] op_sel:[1,0]
	v_mov_b32_e32 v31, v23
	v_fmac_f32_e32 v20, 0xb9800000, v104
	v_pk_fma_f32 v[18:19], v[122:123], v[122:123], v[18:19] op_sel_hi:[1,1,0]
	v_pk_add_f32 v[22:23], v[40:41], v[30:31]
	v_fmamk_f32 v21, v104, 0xb9800000, v21
	v_mul_f32_e32 v18, v20, v20
	v_pk_add_f32 v[28:29], v[28:29], v[28:29] op_sel_hi:[0,1]
	v_pk_add_f32 v[22:23], v[22:23], v[22:23] op_sel_hi:[0,1]
	v_pk_fma_f32 v[30:31], v[20:21], v[20:21], v[18:19] op_sel_hi:[1,1,0]
	v_fmamk_f32 v121, v104, 0xb9800000, v17
	v_fmamk_f32 v120, v104, 0xb9800000, v16
	v_fmamk_f32 v15, v104, 0xb9800000, v15
	v_fmac_f32_e32 v14, 0xb9800000, v104
	v_mul_f32_e32 v18, v14, v14
	v_mul_f32_e32 v30, v15, v15
	v_mul_f32_e32 v22, v120, v120
	v_mul_f32_e32 v28, v121, v121
	v_pk_add_f32 v[16:17], v[18:19], v[30:31]
	v_pk_add_f32 v[18:19], v[22:23], v[28:29]
	v_fmamk_f32 v119, v104, 0xb9800000, v11
	v_fmamk_f32 v118, v104, 0xb9800000, v10
	v_fmamk_f32 v13, v104, 0xb9800000, v13
	v_fmac_f32_e32 v12, 0xb9800000, v104
	v_pk_add_f32 v[16:17], v[16:17], v[18:19]
	v_pk_mul_f32 v[10:11], v[12:13], v[12:13]
	v_pk_mul_f32 v[18:19], v[118:119], v[118:119]
	v_fmac_f32_e32 v4, 0xb9800000, v104
	v_pk_mov_b32 v[22:23], v[18:19], v[10:11] op_sel:[1,0]
	v_mov_b32_e32 v19, v11
	v_pk_add_f32 v[10:11], v[22:23], v[18:19]
	v_fmamk_f32 v22, v104, 0xb9800000, v2
	v_fmamk_f32 v23, v104, 0xb9800000, v3
	v_mul_f32_e32 v2, v22, v22
	v_fmamk_f32 v5, v104, 0xb9800000, v5
	v_pk_fma_f32 v[18:19], v[22:23], v[22:23], v[2:3] op_sel_hi:[1,1,0]
	v_mul_f32_e32 v2, v4, v4
	v_pk_add_f32 v[16:17], v[16:17], v[16:17] op_sel_hi:[0,1]
	v_pk_add_f32 v[10:11], v[10:11], v[10:11] op_sel_hi:[0,1]
	v_pk_fma_f32 v[28:29], v[4:5], v[4:5], v[2:3] op_sel_hi:[1,1,0]
	v_fmamk_f32 v3, v104, 0xb9800000, v9
	v_fmamk_f32 v2, v104, 0xb9800000, v8
	v_fmamk_f32 v7, v104, 0xb9800000, v7
	v_fmac_f32_e32 v6, 0xb9800000, v104
	v_mul_f32_e32 v18, v6, v6
	v_mul_f32_e32 v28, v7, v7
	v_mul_f32_e32 v10, v2, v2
	v_mul_f32_e32 v16, v3, v3
	v_pk_add_f32 v[8:9], v[18:19], v[28:29]
	v_pk_add_f32 v[10:11], v[10:11], v[16:17]
	s_nop 0
	v_pk_add_f32 v[8:9], v[8:9], v[10:11]
	s_nop 0
	v_add_f32_e32 v8, v8, v9
	ds_bpermute_b32 v9, v125, v8
	s_waitcnt lgkmcnt(0)
	v_add_f32_e32 v8, v8, v9
	ds_bpermute_b32 v9, v207, v8
	s_waitcnt lgkmcnt(0)
	v_add_f32_e32 v8, v8, v9
	ds_bpermute_b32 v9, v216, v8
	s_waitcnt lgkmcnt(0)
	v_add_f32_e32 v8, v8, v9
	ds_bpermute_b32 v9, v233, v8
	s_waitcnt lgkmcnt(0)
	v_add_f32_e32 v8, v8, v9
	ds_bpermute_b32 v9, v234, v8
	s_waitcnt lgkmcnt(0)
	v_add_f32_e32 v8, v8, v9
	ds_bpermute_b32 v9, v235, v8
	s_waitcnt lgkmcnt(0)
	v_add_f32_e32 v8, v8, v9
	v_fmamk_f32 v8, v8, 0x39800000, v191
	v_cmp_gt_f32_e32 vcc, s0, v8
	v_mul_f32_e32 v9, 0x4f800000, v8
	s_nop 0
	v_cndmask_b32_e32 v8, v8, v9, vcc
	v_sqrt_f32_e32 v9, v8
	s_nop 0
	v_add_u32_e32 v10, -1, v9
	v_fma_f32 v11, -v10, v9, v8
	v_cmp_ge_f32_e64 s[4:5], 0, v11
	v_add_u32_e32 v11, 1, v9
	s_nop 0
	v_cndmask_b32_e64 v10, v9, v10, s[4:5]
	v_fma_f32 v9, -v11, v9, v8
	v_cmp_lt_f32_e64 s[4:5], 0, v9
	s_nop 1
	v_cndmask_b32_e64 v9, v10, v11, s[4:5]
	v_mul_f32_e32 v10, 0x37800000, v9
	v_cndmask_b32_e32 v9, v9, v10, vcc
	v_cmp_class_f32_e32 vcc, v8, v193
	s_nop 1
	v_cndmask_b32_e32 v8, v9, v8, vcc
	v_div_scale_f32 v9, s[0:1], v8, v8, 1.0
	v_rcp_f32_e32 v10, v9
	s_mov_b32 s0, 0x1aa00000
	v_fma_f32 v11, -v9, v10, 1.0
	v_fmac_f32_e32 v10, v11, v10
	v_div_scale_f32 v11, vcc, 1.0, v8, 1.0
	v_mul_f32_e32 v16, v11, v10
	v_fma_f32 v17, -v9, v16, v11
	v_fmac_f32_e32 v16, v17, v10
	v_fma_f32 v9, -v9, v16, v11
	v_div_fmas_f32 v9, v9, v10, v16
	v_div_fixup_f32 v124, v9, v8, 1.0
	v_pk_mul_f32 v[226:227], v[226:227], v[124:125] op_sel_hi:[1,0]
	v_pk_mul_f32 v[88:89], v[88:89], v[124:125] op_sel_hi:[1,0]
	s_waitcnt vmcnt(6)
	v_pk_fma_f32 v[226:227], v[90:91], v[226:227], v[94:95]
	v_pk_fma_f32 v[96:97], v[92:93], v[88:89], v[96:97]
	v_mul_f32_e32 v91, 0x41fe0000, v227
	v_mul_f32_e32 v90, 0x41fe0000, v226
	v_mul_f32_e32 v92, 0x41fe0000, v96
	v_mul_f32_e32 v93, 0x41fe0000, v97
	v_med3_f32 v91, v91, s81, v195
	v_med3_f32 v90, v90, s81, v195
	v_rndne_f32_e32 v91, v91
	v_med3_f32 v92, v92, s81, v195
	v_med3_f32 v93, v93, s81, v195
	v_rndne_f32_e32 v90, v90
	v_cvt_i32_f32_e32 v91, v91
	v_rndne_f32_e32 v92, v92
	v_rndne_f32_e32 v93, v93
	v_cvt_i32_f32_e32 v90, v90
	v_cvt_i32_f32_sdwa v92, v92 dst_sel:WORD_1 dst_unused:UNUSED_PAD src0_sel:DWORD
	v_cvt_i32_f32_e32 v93, v93
	v_lshl_add_u64 v[88:89], s[94:95], 0, v[112:113]
	v_add_co_u32_e32 v94, vcc, s0, v88
	s_mov_b32 s0, 0x1aa01000
	s_nop 0
	v_addc_co_u32_e32 v95, vcc, 0, v89, vcc
	v_lshlrev_b32_e32 v91, 8, v91
	v_add_co_u32_e32 v88, vcc, s0, v88
	v_and_b32_e32 v91, 0xff00, v91
	v_and_b32_e32 v92, 0xff0000, v92
	v_perm_b32 v90, v93, v90, s82
	v_addc_co_u32_e32 v89, vcc, 0, v89, vcc
	v_or3_b32 v238, v90, v91, v92
	v_lshl_add_u64 v[92:93], s[94:95], 0, v[114:115]
	v_add_co_u32_e32 v90, vcc, s83, v92
	global_load_dwordx4 v[102:105], v[130:131], off
	global_load_dwordx4 v[106:109], v[132:133], off
	global_load_dwordx4 v[52:55], v[134:135], off
	global_load_dwordx4 v[98:101], v[136:137], off
	global_load_dwordx4 v[28:31], v[138:139], off
	global_load_dwordx4 v[40:43], v[140:141], off
	global_load_dwordx4 v[8:11], v[142:143], off
	global_load_dwordx4 v[16:19], v[144:145], off
	s_nop 0
	v_cvt_pk_bf16_f32 v236, v226, v227
	v_addc_co_u32_e32 v91, vcc, 0, v93, vcc
	v_bfe_u32 v239, v236, 7, 8
	s_nop 0
	v_cvt_pk_bf16_f32 v237, v96, v97
	global_store_dwordx2 v[88:89], v[236:237], off offset:-4096
	global_store_dword v[90:91], v238, off
	v_lshlrev_b32_e32 v238, 16, v236
	v_lshlrev_b32_e32 v240, 23, v239
	v_sub_u32_e32 v240, 0x82800000, v240
	v_add_u32_e32 v239, -16, v239
	v_sub_f32_e32 v226, v226, v238
	v_and_b32_e32 v238, 0xffff0000, v236
	v_bfe_u32 v236, v236, 23, 8
	v_cmp_gt_u32_e32 vcc, s84, v239
	v_mul_f32_e32 v226, v226, v240
	v_lshlrev_b32_e32 v239, 23, v236
	v_mul_f32_e32 v226, 0x437e0000, v226
	v_sub_u32_e32 v239, 0x82800000, v239
	v_add_u32_e32 v236, -16, v236
	v_sub_f32_e32 v227, v227, v238
	v_cndmask_b32_e32 v226, 0, v226, vcc
	v_cmp_gt_u32_e32 vcc, s84, v236
	v_mul_f32_e32 v227, v227, v239
	v_lshlrev_b32_e32 v236, 16, v237
	v_bfe_u32 v238, v237, 7, 8
	v_mul_f32_e32 v227, 0x437e0000, v227
	v_lshlrev_b32_e32 v239, 23, v238
	v_add_u32_e32 v238, -16, v238
	v_sub_f32_e32 v96, v96, v236
	v_and_b32_e32 v236, 0xffff0000, v237
	v_bfe_u32 v237, v237, 23, 8
	v_cndmask_b32_e32 v227, 0, v227, vcc
	v_sub_u32_e32 v239, 0x82800000, v239
	v_cmp_gt_u32_e32 vcc, s84, v238
	v_lshlrev_b32_e32 v238, 23, v237
	v_mul_f32_e32 v96, v96, v239
	v_sub_u32_e32 v238, 0x82800000, v238
	v_sub_f32_e32 v97, v97, v236
	v_mul_f32_e32 v96, 0x437e0000, v96
	v_add_u32_e32 v237, -16, v237
	v_mul_f32_e32 v97, v97, v238
	v_cndmask_b32_e32 v96, 0, v96, vcc
	v_cmp_gt_u32_e32 vcc, s84, v237
	v_mul_f32_e32 v97, 0x437e0000, v97
	v_med3_f32 v227, v227, s81, v195
	v_cndmask_b32_e32 v97, 0, v97, vcc
	v_med3_f32 v226, v226, s81, v195
	v_rndne_f32_e32 v227, v227
	v_med3_f32 v96, v96, s81, v195
	v_rndne_f32_e32 v226, v226
	v_cvt_i32_f32_e32 v227, v227
	v_rndne_f32_e32 v96, v96
	v_med3_f32 v97, v97, s81, v195
	v_cvt_i32_f32_e32 v226, v226
	v_cvt_i32_f32_sdwa v96, v96 dst_sel:WORD_1 dst_unused:UNUSED_PAD src0_sel:DWORD
	v_rndne_f32_e32 v97, v97
	v_cvt_i32_f32_sdwa v97, v97 dst_sel:BYTE_3 dst_unused:UNUSED_PAD src0_sel:DWORD
	v_lshlrev_b32_e32 v227, 8, v227
	v_perm_b32 v226, v227, v226, s85
	v_and_b32_e32 v96, 0xff0000, v96
	v_add_co_u32_e32 v92, vcc, s86, v92
	v_or3_b32 v96, v226, v97, v96
	s_nop 0
	v_addc_co_u32_e32 v93, vcc, 0, v93, vcc
	global_store_dword v[92:93], v96, off
	v_pk_mul_f32 v[96:97], v[224:225], v[124:125] op_sel_hi:[1,0]
	v_pk_mul_f32 v[68:69], v[68:69], v[124:125] op_sel_hi:[1,0]
	s_waitcnt vmcnt(15)
	v_pk_fma_f32 v[78:79], v[78:79], v[96:97], v[82:83]
	v_pk_fma_f32 v[68:69], v[80:81], v[68:69], v[84:85]
	v_mul_f32_e32 v83, 0x41fe0000, v79
	v_mul_f32_e32 v82, 0x41fe0000, v78
	v_mul_f32_e32 v84, 0x41fe0000, v68
	v_mul_f32_e32 v85, 0x41fe0000, v69
	v_med3_f32 v83, v83, s81, v195
	v_med3_f32 v82, v82, s81, v195
	v_rndne_f32_e32 v83, v83
	v_med3_f32 v84, v84, s81, v195
	v_med3_f32 v85, v85, s81, v195
	v_rndne_f32_e32 v82, v82
	v_cvt_i32_f32_e32 v83, v83
	v_rndne_f32_e32 v84, v84
	v_rndne_f32_e32 v85, v85
	v_cvt_i32_f32_e32 v82, v82
	v_cvt_i32_f32_sdwa v84, v84 dst_sel:WORD_1 dst_unused:UNUSED_PAD src0_sel:DWORD
	v_cvt_i32_f32_e32 v85, v85
	v_lshlrev_b32_e32 v83, 8, v83
	v_and_b32_e32 v83, 0xff00, v83
	v_and_b32_e32 v84, 0xff0000, v84
	v_perm_b32 v82, v85, v82, s82
	s_nop 0
	v_cvt_pk_bf16_f32 v80, v78, v79
	v_or3_b32 v82, v82, v83, v84
	v_bfe_u32 v83, v80, 7, 8
	s_nop 0
	v_cvt_pk_bf16_f32 v81, v68, v69
	global_store_dwordx2 v[94:95], v[80:81], off offset:512
	global_store_dword v[90:91], v82, off offset:256
	v_lshlrev_b32_e32 v82, 16, v80
	v_lshlrev_b32_e32 v84, 23, v83
	v_sub_u32_e32 v84, 0x82800000, v84
	v_add_u32_e32 v83, -16, v83
	v_sub_f32_e32 v78, v78, v82
	v_and_b32_e32 v82, 0xffff0000, v80
	v_bfe_u32 v80, v80, 23, 8
	v_cmp_gt_u32_e32 vcc, s84, v83
	v_mul_f32_e32 v78, v78, v84
	v_lshlrev_b32_e32 v83, 23, v80
	v_mul_f32_e32 v78, 0x437e0000, v78
	v_sub_u32_e32 v83, 0x82800000, v83
	v_add_u32_e32 v80, -16, v80
	v_sub_f32_e32 v79, v79, v82
	v_cndmask_b32_e32 v78, 0, v78, vcc
	v_cmp_gt_u32_e32 vcc, s84, v80
	v_mul_f32_e32 v79, v79, v83
	v_lshlrev_b32_e32 v80, 16, v81
	v_bfe_u32 v82, v81, 7, 8
	v_mul_f32_e32 v79, 0x437e0000, v79
	v_lshlrev_b32_e32 v83, 23, v82
	v_add_u32_e32 v82, -16, v82
	v_sub_f32_e32 v68, v68, v80
	v_and_b32_e32 v80, 0xffff0000, v81
	v_bfe_u32 v81, v81, 23, 8
	v_cndmask_b32_e32 v79, 0, v79, vcc
	v_sub_u32_e32 v83, 0x82800000, v83
	v_cmp_gt_u32_e32 vcc, s84, v82
	v_lshlrev_b32_e32 v82, 23, v81
	v_mul_f32_e32 v68, v68, v83
	v_sub_u32_e32 v82, 0x82800000, v82
	v_sub_f32_e32 v69, v69, v80
	v_mul_f32_e32 v68, 0x437e0000, v68
	v_add_u32_e32 v81, -16, v81
	v_mul_f32_e32 v69, v69, v82
	v_cndmask_b32_e32 v68, 0, v68, vcc
	v_cmp_gt_u32_e32 vcc, s84, v81
	v_mul_f32_e32 v69, 0x437e0000, v69
	v_med3_f32 v79, v79, s81, v195
	v_cndmask_b32_e32 v69, 0, v69, vcc
	v_med3_f32 v78, v78, s81, v195
	v_rndne_f32_e32 v79, v79
	v_med3_f32 v68, v68, s81, v195
	v_rndne_f32_e32 v78, v78
	v_cvt_i32_f32_e32 v79, v79
	v_rndne_f32_e32 v68, v68
	v_med3_f32 v69, v69, s81, v195
	v_cvt_i32_f32_e32 v78, v78
	v_cvt_i32_f32_sdwa v68, v68 dst_sel:WORD_1 dst_unused:UNUSED_PAD src0_sel:DWORD
	v_rndne_f32_e32 v69, v69
	v_cvt_i32_f32_sdwa v69, v69 dst_sel:BYTE_3 dst_unused:UNUSED_PAD src0_sel:DWORD
	v_lshlrev_b32_e32 v79, 8, v79
	v_perm_b32 v78, v79, v78, s85
	v_and_b32_e32 v68, 0xff0000, v68
	v_or3_b32 v68, v78, v69, v68
	global_store_dword v[92:93], v68, off offset:256
	v_pk_mul_f32 v[68:69], v[86:87], v[124:125] op_sel_hi:[1,0]
	v_pk_mul_f32 v[56:57], v[56:57], v[124:125] op_sel_hi:[1,0]
	s_waitcnt vmcnt(16)
	v_pk_fma_f32 v[68:69], v[70:71], v[68:69], v[74:75]
	v_pk_fma_f32 v[56:57], v[72:73], v[56:57], v[76:77]
	v_mul_f32_e32 v73, 0x41fe0000, v69
	v_mul_f32_e32 v72, 0x41fe0000, v68
	v_mul_f32_e32 v74, 0x41fe0000, v56
	v_mul_f32_e32 v75, 0x41fe0000, v57
	v_med3_f32 v73, v73, s81, v195
	v_med3_f32 v72, v72, s81, v195
	v_rndne_f32_e32 v73, v73
	v_med3_f32 v74, v74, s81, v195
	v_med3_f32 v75, v75, s81, v195
	v_rndne_f32_e32 v72, v72
	v_cvt_i32_f32_e32 v73, v73
	v_rndne_f32_e32 v74, v74
	v_rndne_f32_e32 v75, v75
	v_cvt_i32_f32_e32 v72, v72
	v_cvt_i32_f32_sdwa v74, v74 dst_sel:WORD_1 dst_unused:UNUSED_PAD src0_sel:DWORD
	v_cvt_i32_f32_e32 v75, v75
	v_lshlrev_b32_e32 v73, 8, v73
	v_and_b32_e32 v73, 0xff00, v73
	v_and_b32_e32 v74, 0xff0000, v74
	v_perm_b32 v72, v75, v72, s82
	s_nop 0
	v_cvt_pk_bf16_f32 v70, v68, v69
	v_or3_b32 v72, v72, v73, v74
	v_bfe_u32 v73, v70, 7, 8
	s_nop 0
	v_cvt_pk_bf16_f32 v71, v56, v57
	global_store_dwordx2 v[94:95], v[70:71], off offset:1024
	global_store_dword v[90:91], v72, off offset:512
	v_lshlrev_b32_e32 v72, 16, v70
	v_lshlrev_b32_e32 v74, 23, v73
	v_sub_u32_e32 v74, 0x82800000, v74
	v_add_u32_e32 v73, -16, v73
	v_sub_f32_e32 v68, v68, v72
	v_and_b32_e32 v72, 0xffff0000, v70
	v_bfe_u32 v70, v70, 23, 8
	v_cmp_gt_u32_e32 vcc, s84, v73
	v_mul_f32_e32 v68, v68, v74
	v_lshlrev_b32_e32 v73, 23, v70
	v_mul_f32_e32 v68, 0x437e0000, v68
	v_sub_u32_e32 v73, 0x82800000, v73
	v_add_u32_e32 v70, -16, v70
	v_sub_f32_e32 v69, v69, v72
	v_cndmask_b32_e32 v68, 0, v68, vcc
	v_cmp_gt_u32_e32 vcc, s84, v70
	v_mul_f32_e32 v69, v69, v73
	v_lshlrev_b32_e32 v70, 16, v71
	v_bfe_u32 v72, v71, 7, 8
	v_mul_f32_e32 v69, 0x437e0000, v69
	v_lshlrev_b32_e32 v73, 23, v72
	v_add_u32_e32 v72, -16, v72
	v_sub_f32_e32 v56, v56, v70
	v_and_b32_e32 v70, 0xffff0000, v71
	v_bfe_u32 v71, v71, 23, 8
	v_cndmask_b32_e32 v69, 0, v69, vcc
	v_sub_u32_e32 v73, 0x82800000, v73
	v_cmp_gt_u32_e32 vcc, s84, v72
	v_lshlrev_b32_e32 v72, 23, v71
	v_mul_f32_e32 v56, v56, v73
	v_sub_u32_e32 v72, 0x82800000, v72
	v_sub_f32_e32 v57, v57, v70
	v_mul_f32_e32 v56, 0x437e0000, v56
	v_add_u32_e32 v71, -16, v71
	v_mul_f32_e32 v57, v57, v72
	v_cndmask_b32_e32 v56, 0, v56, vcc
	v_cmp_gt_u32_e32 vcc, s84, v71
	v_mul_f32_e32 v57, 0x437e0000, v57
	v_med3_f32 v69, v69, s81, v195
	v_cndmask_b32_e32 v57, 0, v57, vcc
	v_med3_f32 v68, v68, s81, v195
	v_rndne_f32_e32 v69, v69
	v_med3_f32 v56, v56, s81, v195
	v_rndne_f32_e32 v68, v68
	v_cvt_i32_f32_e32 v69, v69
	v_rndne_f32_e32 v56, v56
	v_med3_f32 v57, v57, s81, v195
	v_cvt_i32_f32_e32 v68, v68
	v_cvt_i32_f32_sdwa v56, v56 dst_sel:WORD_1 dst_unused:UNUSED_PAD src0_sel:DWORD
	v_rndne_f32_e32 v57, v57
	v_cvt_i32_f32_sdwa v57, v57 dst_sel:BYTE_3 dst_unused:UNUSED_PAD src0_sel:DWORD
	v_lshlrev_b32_e32 v69, 8, v69
	v_perm_b32 v68, v69, v68, s85
	v_and_b32_e32 v56, 0xff0000, v56
	v_or3_b32 v56, v68, v57, v56
	v_pk_mul_f32 v[50:51], v[50:51], v[124:125] op_sel_hi:[1,0]
	global_store_dword v[92:93], v56, off offset:512
	v_pk_mul_f32 v[56:57], v[66:67], v[124:125] op_sel_hi:[1,0]
	s_waitcnt vmcnt(17)
	v_pk_fma_f32 v[50:51], v[58:59], v[50:51], v[62:63]
	v_pk_fma_f32 v[56:57], v[60:61], v[56:57], v[64:65]
	v_mul_f32_e32 v61, 0x41fe0000, v51
	v_mul_f32_e32 v60, 0x41fe0000, v50
	v_mul_f32_e32 v62, 0x41fe0000, v56
	v_mul_f32_e32 v63, 0x41fe0000, v57
	v_med3_f32 v61, v61, s81, v195
	v_med3_f32 v60, v60, s81, v195
	v_rndne_f32_e32 v61, v61
	v_med3_f32 v62, v62, s81, v195
	v_med3_f32 v63, v63, s81, v195
	v_rndne_f32_e32 v60, v60
	v_cvt_i32_f32_e32 v61, v61
	v_rndne_f32_e32 v62, v62
	v_rndne_f32_e32 v63, v63
	v_cvt_i32_f32_e32 v60, v60
	v_cvt_i32_f32_sdwa v62, v62 dst_sel:WORD_1 dst_unused:UNUSED_PAD src0_sel:DWORD
	v_cvt_i32_f32_e32 v63, v63
	v_lshlrev_b32_e32 v61, 8, v61
	v_and_b32_e32 v61, 0xff00, v61
	v_and_b32_e32 v62, 0xff0000, v62
	v_perm_b32 v60, v63, v60, s82
	s_nop 0
	v_cvt_pk_bf16_f32 v58, v50, v51
	v_or3_b32 v60, v60, v61, v62
	v_bfe_u32 v61, v58, 7, 8
	s_nop 0
	v_cvt_pk_bf16_f32 v59, v56, v57
	global_store_dwordx2 v[94:95], v[58:59], off offset:1536
	global_store_dword v[90:91], v60, off offset:768
	v_lshlrev_b32_e32 v60, 16, v58
	v_lshlrev_b32_e32 v62, 23, v61
	v_sub_u32_e32 v62, 0x82800000, v62
	v_add_u32_e32 v61, -16, v61
	v_sub_f32_e32 v50, v50, v60
	v_and_b32_e32 v60, 0xffff0000, v58
	v_bfe_u32 v58, v58, 23, 8
	v_cmp_gt_u32_e32 vcc, s84, v61
	v_mul_f32_e32 v50, v50, v62
	v_lshlrev_b32_e32 v61, 23, v58
	v_mul_f32_e32 v50, 0x437e0000, v50
	v_sub_u32_e32 v61, 0x82800000, v61
	v_add_u32_e32 v58, -16, v58
	v_sub_f32_e32 v51, v51, v60
	v_cndmask_b32_e32 v50, 0, v50, vcc
	v_cmp_gt_u32_e32 vcc, s84, v58
	v_mul_f32_e32 v51, v51, v61
	v_lshlrev_b32_e32 v58, 16, v59
	v_bfe_u32 v60, v59, 7, 8
	v_mul_f32_e32 v51, 0x437e0000, v51
	v_lshlrev_b32_e32 v61, 23, v60
	v_add_u32_e32 v60, -16, v60
	v_sub_f32_e32 v56, v56, v58
	v_and_b32_e32 v58, 0xffff0000, v59
	v_bfe_u32 v59, v59, 23, 8
	v_cndmask_b32_e32 v51, 0, v51, vcc
	v_sub_u32_e32 v61, 0x82800000, v61
	v_cmp_gt_u32_e32 vcc, s84, v60
	v_lshlrev_b32_e32 v60, 23, v59
	v_mul_f32_e32 v56, v56, v61
	v_sub_u32_e32 v60, 0x82800000, v60
	v_sub_f32_e32 v57, v57, v58
	v_mul_f32_e32 v56, 0x437e0000, v56
	v_add_u32_e32 v59, -16, v59
	v_mul_f32_e32 v57, v57, v60
	v_cndmask_b32_e32 v56, 0, v56, vcc
	v_cmp_gt_u32_e32 vcc, s84, v59
	v_mul_f32_e32 v57, 0x437e0000, v57
	v_med3_f32 v51, v51, s81, v195
	v_cndmask_b32_e32 v57, 0, v57, vcc
	v_med3_f32 v50, v50, s81, v195
	v_rndne_f32_e32 v51, v51
	v_med3_f32 v56, v56, s81, v195
	v_rndne_f32_e32 v50, v50
	v_cvt_i32_f32_e32 v51, v51
	v_rndne_f32_e32 v56, v56
	v_med3_f32 v57, v57, s81, v195
	v_cvt_i32_f32_e32 v50, v50
	v_cvt_i32_f32_sdwa v56, v56 dst_sel:WORD_1 dst_unused:UNUSED_PAD src0_sel:DWORD
	v_rndne_f32_e32 v57, v57
	v_cvt_i32_f32_sdwa v57, v57 dst_sel:BYTE_3 dst_unused:UNUSED_PAD src0_sel:DWORD
	v_lshlrev_b32_e32 v51, 8, v51
	v_perm_b32 v50, v51, v50, s85
	v_and_b32_e32 v51, 0xff0000, v56
	v_or3_b32 v50, v50, v57, v51
	global_store_dword v[92:93], v50, off offset:768
	v_pk_mul_f32 v[50:51], v[222:223], v[124:125] op_sel_hi:[1,0]
	v_pk_mul_f32 v[48:49], v[48:49], v[124:125] op_sel_hi:[1,0]
	s_waitcnt vmcnt(18)
	v_pk_fma_f32 v[50:51], v[102:103], v[50:51], v[106:107]
	v_pk_fma_f32 v[48:49], v[104:105], v[48:49], v[108:109]
	v_mul_f32_e32 v103, 0x41fe0000, v51
	v_mul_f32_e32 v102, 0x41fe0000, v50
	v_mul_f32_e32 v104, 0x41fe0000, v48
	v_mul_f32_e32 v105, 0x41fe0000, v49
	v_med3_f32 v103, v103, s81, v195
	v_med3_f32 v102, v102, s81, v195
	v_rndne_f32_e32 v103, v103
	v_med3_f32 v104, v104, s81, v195
	v_med3_f32 v105, v105, s81, v195
	v_rndne_f32_e32 v102, v102
	v_cvt_i32_f32_e32 v103, v103
	v_rndne_f32_e32 v104, v104
	v_rndne_f32_e32 v105, v105
	v_cvt_i32_f32_e32 v102, v102
	v_cvt_i32_f32_sdwa v104, v104 dst_sel:WORD_1 dst_unused:UNUSED_PAD src0_sel:DWORD
	v_cvt_i32_f32_e32 v105, v105
	v_lshlrev_b32_e32 v103, 8, v103
	v_and_b32_e32 v103, 0xff00, v103
	v_and_b32_e32 v104, 0xff0000, v104
	v_perm_b32 v102, v105, v102, s82
	global_load_dwordx4 v[80:83], v[146:147], off
	global_load_dwordx4 v[84:87], v[148:149], off
	global_load_dwordx4 v[72:75], v[150:151], off
	global_load_dwordx4 v[76:79], v[152:153], off
	global_load_dwordx4 v[64:67], v[156:157], off
	global_load_dwordx4 v[68:71], v[158:159], off
	global_load_dwordx4 v[56:59], v[160:161], off
	global_load_dwordx4 v[60:63], v[162:163], off
	s_nop 0
	v_cvt_pk_bf16_f32 v96, v50, v51
	v_or3_b32 v102, v102, v103, v104
	v_bfe_u32 v103, v96, 7, 8
	s_nop 0
	v_cvt_pk_bf16_f32 v97, v48, v49
	global_store_dwordx2 v[94:95], v[96:97], off offset:2048
	global_store_dword v[90:91], v102, off offset:1024
	v_lshlrev_b32_e32 v102, 16, v96
	v_lshlrev_b32_e32 v104, 23, v103
	v_sub_u32_e32 v104, 0x82800000, v104
	v_add_u32_e32 v103, -16, v103
	v_sub_f32_e32 v50, v50, v102
	v_and_b32_e32 v102, 0xffff0000, v96
	v_bfe_u32 v96, v96, 23, 8
	v_cmp_gt_u32_e32 vcc, s84, v103
	v_mul_f32_e32 v50, v50, v104
	v_lshlrev_b32_e32 v103, 23, v96
	v_mul_f32_e32 v50, 0x437e0000, v50
	v_sub_u32_e32 v103, 0x82800000, v103
	v_add_u32_e32 v96, -16, v96
	v_sub_f32_e32 v51, v51, v102
	v_cndmask_b32_e32 v50, 0, v50, vcc
	v_cmp_gt_u32_e32 vcc, s84, v96
	v_mul_f32_e32 v51, v51, v103
	v_lshlrev_b32_e32 v96, 16, v97
	v_bfe_u32 v102, v97, 7, 8
	v_mul_f32_e32 v51, 0x437e0000, v51
	v_lshlrev_b32_e32 v103, 23, v102
	v_add_u32_e32 v102, -16, v102
	v_sub_f32_e32 v48, v48, v96
	v_and_b32_e32 v96, 0xffff0000, v97
	v_bfe_u32 v97, v97, 23, 8
	v_cndmask_b32_e32 v51, 0, v51, vcc
	v_sub_u32_e32 v103, 0x82800000, v103
	v_cmp_gt_u32_e32 vcc, s84, v102
	v_lshlrev_b32_e32 v102, 23, v97
	v_mul_f32_e32 v48, v48, v103
	v_sub_u32_e32 v102, 0x82800000, v102
	v_sub_f32_e32 v49, v49, v96
	v_mul_f32_e32 v48, 0x437e0000, v48
	v_add_u32_e32 v97, -16, v97
	v_mul_f32_e32 v49, v49, v102
	v_cndmask_b32_e32 v48, 0, v48, vcc
	v_cmp_gt_u32_e32 vcc, s84, v97
	v_mul_f32_e32 v49, 0x437e0000, v49
	v_med3_f32 v51, v51, s81, v195
	v_cndmask_b32_e32 v49, 0, v49, vcc
	v_med3_f32 v50, v50, s81, v195
	v_rndne_f32_e32 v51, v51
	v_med3_f32 v48, v48, s81, v195
	v_rndne_f32_e32 v50, v50
	v_cvt_i32_f32_e32 v51, v51
	v_rndne_f32_e32 v48, v48
	v_med3_f32 v49, v49, s81, v195
	v_cvt_i32_f32_e32 v50, v50
	v_cvt_i32_f32_sdwa v48, v48 dst_sel:WORD_1 dst_unused:UNUSED_PAD src0_sel:DWORD
	v_rndne_f32_e32 v49, v49
	v_cvt_i32_f32_sdwa v49, v49 dst_sel:BYTE_3 dst_unused:UNUSED_PAD src0_sel:DWORD
	v_lshlrev_b32_e32 v51, 8, v51
	v_perm_b32 v50, v51, v50, s85
	v_and_b32_e32 v48, 0xff0000, v48
	v_or3_b32 v48, v50, v49, v48
	global_store_dword v[92:93], v48, off offset:1024
	v_pk_mul_f32 v[48:49], v[220:221], v[124:125] op_sel_hi:[1,0]
	v_pk_mul_f32 v[44:45], v[44:45], v[124:125] op_sel_hi:[1,0]
	s_waitcnt vmcnt(27)
	v_pk_fma_f32 v[48:49], v[52:53], v[48:49], v[98:99]
	v_pk_fma_f32 v[44:45], v[54:55], v[44:45], v[100:101]
	v_mul_f32_e32 v53, 0x41fe0000, v49
	v_mul_f32_e32 v52, 0x41fe0000, v48
	v_mul_f32_e32 v54, 0x41fe0000, v44
	v_mul_f32_e32 v55, 0x41fe0000, v45
	v_med3_f32 v53, v53, s81, v195
	v_med3_f32 v52, v52, s81, v195
	v_rndne_f32_e32 v53, v53
	v_med3_f32 v54, v54, s81, v195
	v_med3_f32 v55, v55, s81, v195
	v_rndne_f32_e32 v52, v52
	v_cvt_i32_f32_e32 v53, v53
	v_rndne_f32_e32 v54, v54
	v_rndne_f32_e32 v55, v55
	v_cvt_i32_f32_e32 v52, v52
	v_cvt_i32_f32_sdwa v54, v54 dst_sel:WORD_1 dst_unused:UNUSED_PAD src0_sel:DWORD
	v_cvt_i32_f32_e32 v55, v55
	v_lshlrev_b32_e32 v53, 8, v53
	v_and_b32_e32 v53, 0xff00, v53
	v_and_b32_e32 v54, 0xff0000, v54
	v_perm_b32 v52, v55, v52, s82
	s_nop 0
	v_cvt_pk_bf16_f32 v50, v48, v49
	v_or3_b32 v52, v52, v53, v54
	v_bfe_u32 v53, v50, 7, 8
	s_nop 0
	v_cvt_pk_bf16_f32 v51, v44, v45
	global_store_dwordx2 v[94:95], v[50:51], off offset:2560
	global_store_dword v[90:91], v52, off offset:1280
	v_lshlrev_b32_e32 v52, 16, v50
	v_lshlrev_b32_e32 v54, 23, v53
	v_sub_u32_e32 v54, 0x82800000, v54
	v_add_u32_e32 v53, -16, v53
	v_sub_f32_e32 v48, v48, v52
	v_and_b32_e32 v52, 0xffff0000, v50
	v_bfe_u32 v50, v50, 23, 8
	v_cmp_gt_u32_e32 vcc, s84, v53
	v_mul_f32_e32 v48, v48, v54
	v_lshlrev_b32_e32 v53, 23, v50
	v_mul_f32_e32 v48, 0x437e0000, v48
	v_sub_u32_e32 v53, 0x82800000, v53
	v_add_u32_e32 v50, -16, v50
	v_sub_f32_e32 v49, v49, v52
	v_cndmask_b32_e32 v48, 0, v48, vcc
	v_cmp_gt_u32_e32 vcc, s84, v50
	v_mul_f32_e32 v49, v49, v53
	v_lshlrev_b32_e32 v50, 16, v51
	v_bfe_u32 v52, v51, 7, 8
	v_mul_f32_e32 v49, 0x437e0000, v49
	v_lshlrev_b32_e32 v53, 23, v52
	v_add_u32_e32 v52, -16, v52
	v_sub_f32_e32 v44, v44, v50
	v_and_b32_e32 v50, 0xffff0000, v51
	v_bfe_u32 v51, v51, 23, 8
	v_cndmask_b32_e32 v49, 0, v49, vcc
	v_sub_u32_e32 v53, 0x82800000, v53
	v_cmp_gt_u32_e32 vcc, s84, v52
	v_lshlrev_b32_e32 v52, 23, v51
	v_mul_f32_e32 v44, v44, v53
	v_sub_u32_e32 v52, 0x82800000, v52
	v_sub_f32_e32 v45, v45, v50
	v_mul_f32_e32 v44, 0x437e0000, v44
	v_add_u32_e32 v51, -16, v51
	v_mul_f32_e32 v45, v45, v52
	v_cndmask_b32_e32 v44, 0, v44, vcc
	v_cmp_gt_u32_e32 vcc, s84, v51
	v_mul_f32_e32 v45, 0x437e0000, v45
	v_med3_f32 v49, v49, s81, v195
	v_cndmask_b32_e32 v45, 0, v45, vcc
	v_med3_f32 v48, v48, s81, v195
	v_rndne_f32_e32 v49, v49
	v_med3_f32 v44, v44, s81, v195
	v_rndne_f32_e32 v48, v48
	v_cvt_i32_f32_e32 v49, v49
	v_rndne_f32_e32 v44, v44
	v_med3_f32 v45, v45, s81, v195
	v_cvt_i32_f32_e32 v48, v48
	v_cvt_i32_f32_sdwa v44, v44 dst_sel:WORD_1 dst_unused:UNUSED_PAD src0_sel:DWORD
	v_rndne_f32_e32 v45, v45
	v_cvt_i32_f32_sdwa v45, v45 dst_sel:BYTE_3 dst_unused:UNUSED_PAD src0_sel:DWORD
	v_lshlrev_b32_e32 v49, 8, v49
	v_perm_b32 v48, v49, v48, s85
	v_and_b32_e32 v44, 0xff0000, v44
	v_or3_b32 v44, v48, v45, v44
	v_pk_mul_f32 v[38:39], v[38:39], v[124:125] op_sel_hi:[1,0]
	global_store_dword v[92:93], v44, off offset:1280
	v_pk_mul_f32 v[44:45], v[46:47], v[124:125] op_sel_hi:[1,0]
	s_waitcnt vmcnt(28)
	v_pk_fma_f32 v[28:29], v[28:29], v[38:39], v[40:41]
	v_pk_fma_f32 v[30:31], v[30:31], v[44:45], v[42:43]
	v_mul_f32_e32 v41, 0x41fe0000, v29
	v_mul_f32_e32 v40, 0x41fe0000, v28
	v_mul_f32_e32 v42, 0x41fe0000, v30
	v_mul_f32_e32 v43, 0x41fe0000, v31
	v_med3_f32 v41, v41, s81, v195
	v_med3_f32 v40, v40, s81, v195
	v_rndne_f32_e32 v41, v41
	v_med3_f32 v42, v42, s81, v195
	v_med3_f32 v43, v43, s81, v195
	v_rndne_f32_e32 v40, v40
	v_cvt_i32_f32_e32 v41, v41
	v_rndne_f32_e32 v42, v42
	v_rndne_f32_e32 v43, v43
	v_cvt_i32_f32_e32 v40, v40
	v_cvt_i32_f32_sdwa v42, v42 dst_sel:WORD_1 dst_unused:UNUSED_PAD src0_sel:DWORD
	v_cvt_i32_f32_e32 v43, v43
	v_lshlrev_b32_e32 v41, 8, v41
	v_and_b32_e32 v41, 0xff00, v41
	v_and_b32_e32 v42, 0xff0000, v42
	v_perm_b32 v40, v43, v40, s82
	s_nop 0
	v_cvt_pk_bf16_f32 v38, v28, v29
	v_or3_b32 v40, v40, v41, v42
	v_bfe_u32 v41, v38, 7, 8
	s_nop 0
	v_cvt_pk_bf16_f32 v39, v30, v31
	global_store_dwordx2 v[94:95], v[38:39], off offset:3072
	global_store_dword v[90:91], v40, off offset:1536
	v_lshlrev_b32_e32 v40, 16, v38
	v_lshlrev_b32_e32 v42, 23, v41
	v_sub_u32_e32 v42, 0x82800000, v42
	v_add_u32_e32 v41, -16, v41
	v_sub_f32_e32 v28, v28, v40
	v_and_b32_e32 v40, 0xffff0000, v38
	v_bfe_u32 v38, v38, 23, 8
	v_cmp_gt_u32_e32 vcc, s84, v41
	v_mul_f32_e32 v28, v28, v42
	v_lshlrev_b32_e32 v41, 23, v38
	v_mul_f32_e32 v28, 0x437e0000, v28
	v_sub_u32_e32 v41, 0x82800000, v41
	v_add_u32_e32 v38, -16, v38
	v_sub_f32_e32 v29, v29, v40
	v_cndmask_b32_e32 v28, 0, v28, vcc
	v_cmp_gt_u32_e32 vcc, s84, v38
	v_mul_f32_e32 v29, v29, v41
	v_lshlrev_b32_e32 v38, 16, v39
	v_bfe_u32 v40, v39, 7, 8
	v_mul_f32_e32 v29, 0x437e0000, v29
	v_lshlrev_b32_e32 v41, 23, v40
	v_add_u32_e32 v40, -16, v40
	v_sub_f32_e32 v30, v30, v38
	v_and_b32_e32 v38, 0xffff0000, v39
	v_bfe_u32 v39, v39, 23, 8
	v_cndmask_b32_e32 v29, 0, v29, vcc
	v_sub_u32_e32 v41, 0x82800000, v41
	v_cmp_gt_u32_e32 vcc, s84, v40
	v_lshlrev_b32_e32 v40, 23, v39
	v_mul_f32_e32 v30, v30, v41
	v_sub_u32_e32 v40, 0x82800000, v40
	v_sub_f32_e32 v31, v31, v38
	v_mul_f32_e32 v30, 0x437e0000, v30
	v_add_u32_e32 v39, -16, v39
	v_mul_f32_e32 v31, v31, v40
	v_cndmask_b32_e32 v30, 0, v30, vcc
	v_cmp_gt_u32_e32 vcc, s84, v39
	v_mul_f32_e32 v31, 0x437e0000, v31
	v_med3_f32 v29, v29, s81, v195
	v_cndmask_b32_e32 v31, 0, v31, vcc
	v_med3_f32 v28, v28, s81, v195
	v_rndne_f32_e32 v29, v29
	v_med3_f32 v30, v30, s81, v195
	v_rndne_f32_e32 v28, v28
	v_cvt_i32_f32_e32 v29, v29
	v_rndne_f32_e32 v30, v30
	v_med3_f32 v31, v31, s81, v195
	v_cvt_i32_f32_e32 v28, v28
	v_cvt_i32_f32_sdwa v30, v30 dst_sel:WORD_1 dst_unused:UNUSED_PAD src0_sel:DWORD
	v_rndne_f32_e32 v31, v31
	v_cvt_i32_f32_sdwa v31, v31 dst_sel:BYTE_3 dst_unused:UNUSED_PAD src0_sel:DWORD
	v_lshlrev_b32_e32 v29, 8, v29
	v_perm_b32 v28, v29, v28, s85
	v_and_b32_e32 v29, 0xff0000, v30
	v_or3_b32 v28, v28, v31, v29
	global_store_dword v[92:93], v28, off offset:1536
	v_pk_mul_f32 v[28:29], v[34:35], v[124:125] op_sel_hi:[1,0]
	v_pk_mul_f32 v[30:31], v[36:37], v[124:125] op_sel_hi:[1,0]
	s_waitcnt vmcnt(29)
	v_pk_fma_f32 v[8:9], v[8:9], v[28:29], v[16:17]
	v_pk_fma_f32 v[10:11], v[10:11], v[30:31], v[18:19]
	v_mul_f32_e32 v19, 0x41fe0000, v9
	v_mul_f32_e32 v18, 0x41fe0000, v8
	v_mul_f32_e32 v28, 0x41fe0000, v10
	v_mul_f32_e32 v29, 0x41fe0000, v11
	v_med3_f32 v19, v19, s81, v195
	v_med3_f32 v18, v18, s81, v195
	v_rndne_f32_e32 v19, v19
	v_med3_f32 v28, v28, s81, v195
	v_med3_f32 v29, v29, s81, v195
	v_rndne_f32_e32 v18, v18
	v_cvt_i32_f32_e32 v19, v19
	v_rndne_f32_e32 v28, v28
	v_rndne_f32_e32 v29, v29
	v_cvt_i32_f32_e32 v18, v18
	v_cvt_i32_f32_sdwa v28, v28 dst_sel:WORD_1 dst_unused:UNUSED_PAD src0_sel:DWORD
	v_cvt_i32_f32_e32 v29, v29
	v_lshlrev_b32_e32 v19, 8, v19
	v_and_b32_e32 v19, 0xff00, v19
	v_and_b32_e32 v28, 0xff0000, v28
	v_perm_b32 v18, v29, v18, s82
	s_nop 0
	v_cvt_pk_bf16_f32 v16, v8, v9
	v_or3_b32 v18, v18, v19, v28
	v_bfe_u32 v19, v16, 7, 8
	s_nop 0
	v_cvt_pk_bf16_f32 v17, v10, v11
	global_store_dwordx2 v[94:95], v[16:17], off offset:3584
	global_store_dword v[90:91], v18, off offset:1792
	v_lshlrev_b32_e32 v18, 16, v16
	v_lshlrev_b32_e32 v28, 23, v19
	v_sub_u32_e32 v28, 0x82800000, v28
	v_add_u32_e32 v19, -16, v19
	v_sub_f32_e32 v8, v8, v18
	v_and_b32_e32 v18, 0xffff0000, v16
	v_bfe_u32 v16, v16, 23, 8
	v_cmp_gt_u32_e32 vcc, s84, v19
	v_mul_f32_e32 v8, v8, v28
	v_lshlrev_b32_e32 v19, 23, v16
	v_mul_f32_e32 v8, 0x437e0000, v8
	v_sub_u32_e32 v19, 0x82800000, v19
	v_add_u32_e32 v16, -16, v16
	v_sub_f32_e32 v9, v9, v18
	v_cndmask_b32_e32 v8, 0, v8, vcc
	v_cmp_gt_u32_e32 vcc, s84, v16
	v_mul_f32_e32 v9, v9, v19
	v_lshlrev_b32_e32 v16, 16, v17
	v_bfe_u32 v18, v17, 7, 8
	v_mul_f32_e32 v9, 0x437e0000, v9
	v_lshlrev_b32_e32 v19, 23, v18
	v_add_u32_e32 v18, -16, v18
	v_sub_f32_e32 v10, v10, v16
	v_and_b32_e32 v16, 0xffff0000, v17
	v_bfe_u32 v17, v17, 23, 8
	v_cndmask_b32_e32 v9, 0, v9, vcc
	v_sub_u32_e32 v19, 0x82800000, v19
	v_cmp_gt_u32_e32 vcc, s84, v18
	v_lshlrev_b32_e32 v18, 23, v17
	v_mul_f32_e32 v10, v10, v19
	v_sub_u32_e32 v18, 0x82800000, v18
	v_sub_f32_e32 v11, v11, v16
	v_mul_f32_e32 v10, 0x437e0000, v10
	v_add_u32_e32 v17, -16, v17
	v_mul_f32_e32 v11, v11, v18
	v_pk_mul_f32 v[54:55], v[218:219], v[124:125] op_sel_hi:[1,0]
	v_cndmask_b32_e32 v10, 0, v10, vcc
	v_cmp_gt_u32_e32 vcc, s84, v17
	v_mul_f32_e32 v11, 0x437e0000, v11
	v_med3_f32 v9, v9, s81, v195
	v_pk_mul_f32 v[32:33], v[32:33], v[124:125] op_sel_hi:[1,0]
	s_waitcnt vmcnt(17)
	v_pk_fma_f32 v[54:55], v[80:81], v[54:55], v[84:85]
	v_cndmask_b32_e32 v11, 0, v11, vcc
	v_med3_f32 v8, v8, s81, v195
	v_rndne_f32_e32 v9, v9
	v_med3_f32 v10, v10, s81, v195
	v_pk_fma_f32 v[32:33], v[82:83], v[32:33], v[86:87]
	v_mul_f32_e32 v83, 0x41fe0000, v55
	v_rndne_f32_e32 v8, v8
	v_cvt_i32_f32_e32 v9, v9
	v_rndne_f32_e32 v10, v10
	v_med3_f32 v11, v11, s81, v195
	v_mul_f32_e32 v82, 0x41fe0000, v54
	v_mul_f32_e32 v84, 0x41fe0000, v32
	v_mul_f32_e32 v85, 0x41fe0000, v33
	v_med3_f32 v83, v83, s81, v195
	v_cvt_i32_f32_e32 v8, v8
	v_cvt_i32_f32_sdwa v10, v10 dst_sel:WORD_1 dst_unused:UNUSED_PAD src0_sel:DWORD
	v_rndne_f32_e32 v11, v11
	v_med3_f32 v82, v82, s81, v195
	v_rndne_f32_e32 v83, v83
	v_med3_f32 v84, v84, s81, v195
	v_med3_f32 v85, v85, s81, v195
	v_cvt_i32_f32_sdwa v11, v11 dst_sel:BYTE_3 dst_unused:UNUSED_PAD src0_sel:DWORD
	v_rndne_f32_e32 v82, v82
	v_cvt_i32_f32_e32 v83, v83
	v_rndne_f32_e32 v84, v84
	v_rndne_f32_e32 v85, v85
	v_cvt_i32_f32_e32 v82, v82
	v_cvt_i32_f32_sdwa v84, v84 dst_sel:WORD_1 dst_unused:UNUSED_PAD src0_sel:DWORD
	v_cvt_i32_f32_e32 v85, v85
	v_lshlrev_b32_e32 v9, 8, v9
	v_perm_b32 v8, v9, v8, s85
	v_and_b32_e32 v9, 0xff0000, v10
	v_or3_b32 v8, v8, v11, v9
	v_lshlrev_b32_e32 v83, 8, v83
	global_store_dword v[92:93], v8, off offset:1792
	v_and_b32_e32 v83, 0xff00, v83
	v_and_b32_e32 v84, 0xff0000, v84
	v_perm_b32 v82, v85, v82, s82
	global_load_dwordx4 v[46:49], v[164:165], off
	global_load_dwordx4 v[50:53], v[166:167], off
	global_load_dwordx4 v[38:41], v[168:169], off
	global_load_dwordx4 v[42:45], v[170:171], off
	global_load_dwordx4 v[28:31], v[178:179], off
	global_load_dwordx4 v[34:37], v[180:181], off
	global_load_dwordx4 v[8:11], v[182:183], off
	global_load_dwordx4 v[16:19], v[184:185], off
	s_nop 0
	v_cvt_pk_bf16_f32 v80, v54, v55
	v_or3_b32 v82, v82, v83, v84
	v_bfe_u32 v83, v80, 7, 8
	s_nop 0
	v_cvt_pk_bf16_f32 v81, v32, v33
	global_store_dwordx2 v[88:89], v[80:81], off
	global_store_dword v[90:91], v82, off offset:2048
	v_lshlrev_b32_e32 v82, 16, v80
	v_lshlrev_b32_e32 v84, 23, v83
	v_sub_u32_e32 v84, 0x82800000, v84
	v_add_u32_e32 v83, -16, v83
	v_sub_f32_e32 v54, v54, v82
	v_and_b32_e32 v82, 0xffff0000, v80
	v_bfe_u32 v80, v80, 23, 8
	v_cmp_gt_u32_e32 vcc, s84, v83
	v_mul_f32_e32 v54, v54, v84
	v_lshlrev_b32_e32 v83, 23, v80
	v_mul_f32_e32 v54, 0x437e0000, v54
	v_sub_u32_e32 v83, 0x82800000, v83
	v_add_u32_e32 v80, -16, v80
	v_sub_f32_e32 v55, v55, v82
	v_cndmask_b32_e32 v54, 0, v54, vcc
	v_cmp_gt_u32_e32 vcc, s84, v80
	v_mul_f32_e32 v55, v55, v83
	v_lshlrev_b32_e32 v80, 16, v81
	v_bfe_u32 v82, v81, 7, 8
	v_mul_f32_e32 v55, 0x437e0000, v55
	v_lshlrev_b32_e32 v83, 23, v82
	v_add_u32_e32 v82, -16, v82
	v_sub_f32_e32 v32, v32, v80
	v_and_b32_e32 v80, 0xffff0000, v81
	v_bfe_u32 v81, v81, 23, 8
	v_cndmask_b32_e32 v55, 0, v55, vcc
	v_sub_u32_e32 v83, 0x82800000, v83
	v_cmp_gt_u32_e32 vcc, s84, v82
	v_lshlrev_b32_e32 v82, 23, v81
	v_mul_f32_e32 v32, v32, v83
	v_sub_u32_e32 v82, 0x82800000, v82
	v_sub_f32_e32 v33, v33, v80
	v_mul_f32_e32 v32, 0x437e0000, v32
	v_add_u32_e32 v81, -16, v81
	v_mul_f32_e32 v33, v33, v82
	v_cndmask_b32_e32 v32, 0, v32, vcc
	v_cmp_gt_u32_e32 vcc, s84, v81
	v_mul_f32_e32 v33, 0x437e0000, v33
	v_med3_f32 v55, v55, s81, v195
	v_cndmask_b32_e32 v33, 0, v33, vcc
	v_med3_f32 v54, v54, s81, v195
	v_rndne_f32_e32 v55, v55
	v_med3_f32 v32, v32, s81, v195
	v_rndne_f32_e32 v54, v54
	v_cvt_i32_f32_e32 v55, v55
	v_rndne_f32_e32 v32, v32
	v_med3_f32 v33, v33, s81, v195
	v_cvt_i32_f32_e32 v54, v54
	v_cvt_i32_f32_sdwa v32, v32 dst_sel:WORD_1 dst_unused:UNUSED_PAD src0_sel:DWORD
	v_rndne_f32_e32 v33, v33
	v_cvt_i32_f32_sdwa v33, v33 dst_sel:BYTE_3 dst_unused:UNUSED_PAD src0_sel:DWORD
	v_lshlrev_b32_e32 v55, 8, v55
	v_perm_b32 v54, v55, v54, s85
	v_and_b32_e32 v32, 0xff0000, v32
	v_or3_b32 v32, v54, v33, v32
	v_pk_mul_f32 v[26:27], v[26:27], v[124:125] op_sel_hi:[1,0]
	global_store_dword v[92:93], v32, off offset:2048
	v_pk_mul_f32 v[32:33], v[128:129], v[124:125] op_sel_hi:[1,0]
	s_waitcnt vmcnt(27)
	v_pk_fma_f32 v[26:27], v[72:73], v[26:27], v[76:77]
	v_pk_fma_f32 v[32:33], v[74:75], v[32:33], v[78:79]
	v_mul_f32_e32 v73, 0x41fe0000, v27
	v_mul_f32_e32 v72, 0x41fe0000, v26
	v_mul_f32_e32 v74, 0x41fe0000, v32
	v_mul_f32_e32 v75, 0x41fe0000, v33
	v_med3_f32 v73, v73, s81, v195
	v_med3_f32 v72, v72, s81, v195
	v_rndne_f32_e32 v73, v73
	v_med3_f32 v74, v74, s81, v195
	v_med3_f32 v75, v75, s81, v195
	v_rndne_f32_e32 v72, v72
	v_cvt_i32_f32_e32 v73, v73
	v_rndne_f32_e32 v74, v74
	v_rndne_f32_e32 v75, v75
	v_cvt_i32_f32_e32 v72, v72
	v_cvt_i32_f32_sdwa v74, v74 dst_sel:WORD_1 dst_unused:UNUSED_PAD src0_sel:DWORD
	v_cvt_i32_f32_e32 v75, v75
	v_lshlrev_b32_e32 v73, 8, v73
	v_and_b32_e32 v73, 0xff00, v73
	v_and_b32_e32 v74, 0xff0000, v74
	v_perm_b32 v72, v75, v72, s82
	s_nop 0
	v_cvt_pk_bf16_f32 v54, v26, v27
	v_or3_b32 v72, v72, v73, v74
	v_bfe_u32 v73, v54, 7, 8
	s_nop 0
	v_cvt_pk_bf16_f32 v55, v32, v33
	global_store_dwordx2 v[88:89], v[54:55], off offset:512
	global_store_dword v[90:91], v72, off offset:2304
	v_lshlrev_b32_e32 v72, 16, v54
	v_lshlrev_b32_e32 v74, 23, v73
	v_sub_u32_e32 v74, 0x82800000, v74
	v_add_u32_e32 v73, -16, v73
	v_sub_f32_e32 v26, v26, v72
	v_and_b32_e32 v72, 0xffff0000, v54
	v_bfe_u32 v54, v54, 23, 8
	v_cmp_gt_u32_e32 vcc, s84, v73
	v_mul_f32_e32 v26, v26, v74
	v_lshlrev_b32_e32 v73, 23, v54
	v_mul_f32_e32 v26, 0x437e0000, v26
	v_sub_u32_e32 v73, 0x82800000, v73
	v_add_u32_e32 v54, -16, v54
	v_sub_f32_e32 v27, v27, v72
	v_cndmask_b32_e32 v26, 0, v26, vcc
	v_cmp_gt_u32_e32 vcc, s84, v54
	v_mul_f32_e32 v27, v27, v73
	v_lshlrev_b32_e32 v54, 16, v55
	v_bfe_u32 v72, v55, 7, 8
	v_mul_f32_e32 v27, 0x437e0000, v27
	v_lshlrev_b32_e32 v73, 23, v72
	v_add_u32_e32 v72, -16, v72
	v_sub_f32_e32 v32, v32, v54
	v_and_b32_e32 v54, 0xffff0000, v55
	v_bfe_u32 v55, v55, 23, 8
	v_cndmask_b32_e32 v27, 0, v27, vcc
	v_sub_u32_e32 v73, 0x82800000, v73
	v_cmp_gt_u32_e32 vcc, s84, v72
	v_lshlrev_b32_e32 v72, 23, v55
	v_mul_f32_e32 v32, v32, v73
	v_sub_u32_e32 v72, 0x82800000, v72
	v_sub_f32_e32 v33, v33, v54
	v_mul_f32_e32 v32, 0x437e0000, v32
	v_add_u32_e32 v55, -16, v55
	v_mul_f32_e32 v33, v33, v72
	v_cndmask_b32_e32 v32, 0, v32, vcc
	v_cmp_gt_u32_e32 vcc, s84, v55
	v_mul_f32_e32 v33, 0x437e0000, v33
	v_med3_f32 v27, v27, s81, v195
	v_cndmask_b32_e32 v33, 0, v33, vcc
	v_med3_f32 v26, v26, s81, v195
	v_rndne_f32_e32 v27, v27
	v_med3_f32 v32, v32, s81, v195
	v_rndne_f32_e32 v26, v26
	v_cvt_i32_f32_e32 v27, v27
	v_rndne_f32_e32 v32, v32
	v_med3_f32 v33, v33, s81, v195
	v_cvt_i32_f32_e32 v26, v26
	v_cvt_i32_f32_sdwa v32, v32 dst_sel:WORD_1 dst_unused:UNUSED_PAD src0_sel:DWORD
	v_rndne_f32_e32 v33, v33
	v_cvt_i32_f32_sdwa v33, v33 dst_sel:BYTE_3 dst_unused:UNUSED_PAD src0_sel:DWORD
	v_lshlrev_b32_e32 v27, 8, v27
	v_perm_b32 v26, v27, v26, s85
	v_and_b32_e32 v27, 0xff0000, v32
	v_or3_b32 v26, v26, v33, v27
	global_store_dword v[92:93], v26, off offset:2304
	v_pk_mul_f32 v[26:27], v[126:127], v[124:125] op_sel_hi:[1,0]
	v_pk_mul_f32 v[24:25], v[24:25], v[124:125] op_sel_hi:[1,0]
	s_waitcnt vmcnt(28)
	v_pk_fma_f32 v[26:27], v[26:27], v[64:65], v[68:69]
	v_pk_fma_f32 v[24:25], v[24:25], v[66:67], v[70:71]
	v_mul_f32_e32 v55, 0x41fe0000, v27
	v_mul_f32_e32 v54, 0x41fe0000, v26
	v_mul_f32_e32 v64, 0x41fe0000, v24
	v_mul_f32_e32 v65, 0x41fe0000, v25
	v_med3_f32 v55, v55, s81, v195
	v_med3_f32 v54, v54, s81, v195
	v_rndne_f32_e32 v55, v55
	v_med3_f32 v64, v64, s81, v195
	v_med3_f32 v65, v65, s81, v195
	v_rndne_f32_e32 v54, v54
	v_cvt_i32_f32_e32 v55, v55
	v_rndne_f32_e32 v64, v64
	v_rndne_f32_e32 v65, v65
	v_cvt_i32_f32_e32 v54, v54
	v_cvt_i32_f32_sdwa v64, v64 dst_sel:WORD_1 dst_unused:UNUSED_PAD src0_sel:DWORD
	v_cvt_i32_f32_e32 v65, v65
	v_lshlrev_b32_e32 v55, 8, v55
	v_and_b32_e32 v55, 0xff00, v55
	v_and_b32_e32 v64, 0xff0000, v64
	v_perm_b32 v54, v65, v54, s82
	s_nop 0
	v_cvt_pk_bf16_f32 v32, v26, v27
	v_or3_b32 v54, v54, v55, v64
	v_bfe_u32 v55, v32, 7, 8
	s_nop 0
	v_cvt_pk_bf16_f32 v33, v24, v25
	global_store_dwordx2 v[88:89], v[32:33], off offset:1024
	global_store_dword v[90:91], v54, off offset:2560
	v_lshlrev_b32_e32 v54, 16, v32
	v_lshlrev_b32_e32 v64, 23, v55
	v_sub_u32_e32 v64, 0x82800000, v64
	v_add_u32_e32 v55, -16, v55
	v_sub_f32_e32 v26, v26, v54
	v_and_b32_e32 v54, 0xffff0000, v32
	v_bfe_u32 v32, v32, 23, 8
	v_cmp_gt_u32_e32 vcc, s84, v55
	v_mul_f32_e32 v26, v26, v64
	v_lshlrev_b32_e32 v55, 23, v32
	v_mul_f32_e32 v26, 0x437e0000, v26
	v_sub_u32_e32 v55, 0x82800000, v55
	v_add_u32_e32 v32, -16, v32
	v_sub_f32_e32 v27, v27, v54
	v_cndmask_b32_e32 v26, 0, v26, vcc
	v_cmp_gt_u32_e32 vcc, s84, v32
	v_mul_f32_e32 v27, v27, v55
	v_lshlrev_b32_e32 v32, 16, v33
	v_bfe_u32 v54, v33, 7, 8
	v_mul_f32_e32 v27, 0x437e0000, v27
	v_lshlrev_b32_e32 v55, 23, v54
	v_add_u32_e32 v54, -16, v54
	v_sub_f32_e32 v24, v24, v32
	v_and_b32_e32 v32, 0xffff0000, v33
	v_bfe_u32 v33, v33, 23, 8
	v_cndmask_b32_e32 v27, 0, v27, vcc
	v_sub_u32_e32 v55, 0x82800000, v55
	v_cmp_gt_u32_e32 vcc, s84, v54
	v_lshlrev_b32_e32 v54, 23, v33
	v_mul_f32_e32 v24, v24, v55
	v_sub_u32_e32 v54, 0x82800000, v54
	v_sub_f32_e32 v25, v25, v32
	v_mul_f32_e32 v24, 0x437e0000, v24
	v_add_u32_e32 v33, -16, v33
	v_mul_f32_e32 v25, v25, v54
	v_cndmask_b32_e32 v24, 0, v24, vcc
	v_cmp_gt_u32_e32 vcc, s84, v33
	v_mul_f32_e32 v25, 0x437e0000, v25
	v_med3_f32 v27, v27, s81, v195
	v_cndmask_b32_e32 v25, 0, v25, vcc
	v_med3_f32 v26, v26, s81, v195
	v_rndne_f32_e32 v27, v27
	v_med3_f32 v24, v24, s81, v195
	v_rndne_f32_e32 v26, v26
	v_cvt_i32_f32_e32 v27, v27
	v_rndne_f32_e32 v24, v24
	v_med3_f32 v25, v25, s81, v195
	v_cvt_i32_f32_e32 v26, v26
	v_cvt_i32_f32_sdwa v24, v24 dst_sel:WORD_1 dst_unused:UNUSED_PAD src0_sel:DWORD
	v_rndne_f32_e32 v25, v25
	v_cvt_i32_f32_sdwa v25, v25 dst_sel:BYTE_3 dst_unused:UNUSED_PAD src0_sel:DWORD
	v_lshlrev_b32_e32 v27, 8, v27
	v_perm_b32 v26, v27, v26, s85
	v_and_b32_e32 v24, 0xff0000, v24
	v_or3_b32 v24, v26, v25, v24
	global_store_dword v[92:93], v24, off offset:2560
	v_pk_mul_f32 v[24:25], v[122:123], v[124:125] op_sel_hi:[1,0]
	v_pk_mul_f32 v[20:21], v[20:21], v[124:125] op_sel_hi:[1,0]
	s_waitcnt vmcnt(29)
	v_pk_fma_f32 v[24:25], v[24:25], v[56:57], v[60:61]
	v_pk_fma_f32 v[20:21], v[20:21], v[58:59], v[62:63]
	v_mul_f32_e32 v33, 0x41fe0000, v25
	v_mul_f32_e32 v32, 0x41fe0000, v24
	v_mul_f32_e32 v54, 0x41fe0000, v20
	v_mul_f32_e32 v55, 0x41fe0000, v21
	v_med3_f32 v33, v33, s81, v195
	v_med3_f32 v32, v32, s81, v195
	v_rndne_f32_e32 v33, v33
	v_med3_f32 v54, v54, s81, v195
	v_med3_f32 v55, v55, s81, v195
	v_rndne_f32_e32 v32, v32
	v_cvt_i32_f32_e32 v33, v33
	v_rndne_f32_e32 v54, v54
	v_rndne_f32_e32 v55, v55
	v_cvt_i32_f32_e32 v32, v32
	v_cvt_i32_f32_sdwa v54, v54 dst_sel:WORD_1 dst_unused:UNUSED_PAD src0_sel:DWORD
	v_cvt_i32_f32_e32 v55, v55
	v_lshlrev_b32_e32 v33, 8, v33
	v_and_b32_e32 v33, 0xff00, v33
	v_and_b32_e32 v54, 0xff0000, v54
	v_perm_b32 v32, v55, v32, s82
	s_nop 0
	v_cvt_pk_bf16_f32 v26, v24, v25
	v_or3_b32 v32, v32, v33, v54
	v_bfe_u32 v33, v26, 7, 8
	s_nop 0
	v_cvt_pk_bf16_f32 v27, v20, v21
	global_store_dwordx2 v[88:89], v[26:27], off offset:1536
	global_store_dword v[90:91], v32, off offset:2816
	v_lshlrev_b32_e32 v32, 16, v26
	v_lshlrev_b32_e32 v54, 23, v33
	v_sub_u32_e32 v54, 0x82800000, v54
	v_add_u32_e32 v33, -16, v33
	v_sub_f32_e32 v24, v24, v32
	v_and_b32_e32 v32, 0xffff0000, v26
	v_bfe_u32 v26, v26, 23, 8
	v_cmp_gt_u32_e32 vcc, s84, v33
	v_mul_f32_e32 v24, v24, v54
	v_lshlrev_b32_e32 v33, 23, v26
	v_mul_f32_e32 v24, 0x437e0000, v24
	v_sub_u32_e32 v33, 0x82800000, v33
	v_add_u32_e32 v26, -16, v26
	v_sub_f32_e32 v25, v25, v32
	v_cndmask_b32_e32 v24, 0, v24, vcc
	v_cmp_gt_u32_e32 vcc, s84, v26
	v_mul_f32_e32 v25, v25, v33
	v_lshlrev_b32_e32 v26, 16, v27
	v_bfe_u32 v32, v27, 7, 8
	v_mul_f32_e32 v25, 0x437e0000, v25
	v_lshlrev_b32_e32 v33, 23, v32
	v_add_u32_e32 v32, -16, v32
	v_sub_f32_e32 v20, v20, v26
	v_and_b32_e32 v26, 0xffff0000, v27
	v_bfe_u32 v27, v27, 23, 8
	v_cndmask_b32_e32 v25, 0, v25, vcc
	v_sub_u32_e32 v33, 0x82800000, v33
	v_cmp_gt_u32_e32 vcc, s84, v32
	v_lshlrev_b32_e32 v32, 23, v27
	v_mul_f32_e32 v20, v20, v33
	v_sub_u32_e32 v32, 0x82800000, v32
	v_sub_f32_e32 v21, v21, v26
	v_mul_f32_e32 v20, 0x437e0000, v20
	v_add_u32_e32 v27, -16, v27
	v_mul_f32_e32 v21, v21, v32
	v_cndmask_b32_e32 v20, 0, v20, vcc
	v_cmp_gt_u32_e32 vcc, s84, v27
	v_mul_f32_e32 v21, 0x437e0000, v21
	v_med3_f32 v25, v25, s81, v195
	v_cndmask_b32_e32 v21, 0, v21, vcc
	v_med3_f32 v24, v24, s81, v195
	v_rndne_f32_e32 v25, v25
	v_med3_f32 v20, v20, s81, v195
	v_rndne_f32_e32 v24, v24
	v_cvt_i32_f32_e32 v25, v25
	v_rndne_f32_e32 v20, v20
	v_med3_f32 v21, v21, s81, v195
	v_cvt_i32_f32_e32 v24, v24
	v_cvt_i32_f32_sdwa v20, v20 dst_sel:WORD_1 dst_unused:UNUSED_PAD src0_sel:DWORD
	v_rndne_f32_e32 v21, v21
	v_cvt_i32_f32_sdwa v21, v21 dst_sel:BYTE_3 dst_unused:UNUSED_PAD src0_sel:DWORD
	v_lshlrev_b32_e32 v25, 8, v25
	v_perm_b32 v24, v25, v24, s85
	v_and_b32_e32 v20, 0xff0000, v20
	v_or3_b32 v20, v24, v21, v20
	v_pk_mul_f32 v[14:15], v[14:15], v[124:125] op_sel_hi:[1,0]
	global_store_dword v[92:93], v20, off offset:2816
	v_pk_mul_f32 v[20:21], v[120:121], v[124:125] op_sel_hi:[1,0]
	s_waitcnt vmcnt(18)
	v_pk_fma_f32 v[14:15], v[14:15], v[46:47], v[50:51]
	v_pk_fma_f32 v[20:21], v[20:21], v[48:49], v[52:53]
	v_mul_f32_e32 v27, 0x41fe0000, v15
	v_mul_f32_e32 v26, 0x41fe0000, v14
	v_mul_f32_e32 v32, 0x41fe0000, v20
	v_mul_f32_e32 v33, 0x41fe0000, v21
	v_med3_f32 v27, v27, s81, v195
	v_med3_f32 v26, v26, s81, v195
	v_rndne_f32_e32 v27, v27
	v_med3_f32 v32, v32, s81, v195
	v_med3_f32 v33, v33, s81, v195
	v_rndne_f32_e32 v26, v26
	v_cvt_i32_f32_e32 v27, v27
	v_rndne_f32_e32 v32, v32
	v_rndne_f32_e32 v33, v33
	v_cvt_i32_f32_e32 v26, v26
	v_cvt_i32_f32_sdwa v32, v32 dst_sel:WORD_1 dst_unused:UNUSED_PAD src0_sel:DWORD
	v_cvt_i32_f32_e32 v33, v33
	v_lshlrev_b32_e32 v27, 8, v27
	v_and_b32_e32 v27, 0xff00, v27
	v_and_b32_e32 v32, 0xff0000, v32
	v_perm_b32 v26, v33, v26, s82
	s_nop 0
	v_cvt_pk_bf16_f32 v24, v14, v15
	v_or3_b32 v26, v26, v27, v32
	v_bfe_u32 v27, v24, 7, 8
	s_nop 0
	v_cvt_pk_bf16_f32 v25, v20, v21
	global_store_dwordx2 v[88:89], v[24:25], off offset:2048
	global_store_dword v[90:91], v26, off offset:3072
	v_lshlrev_b32_e32 v26, 16, v24
	v_lshlrev_b32_e32 v32, 23, v27
	v_sub_u32_e32 v32, 0x82800000, v32
	v_add_u32_e32 v27, -16, v27
	v_sub_f32_e32 v14, v14, v26
	v_and_b32_e32 v26, 0xffff0000, v24
	v_bfe_u32 v24, v24, 23, 8
	v_cmp_gt_u32_e32 vcc, s84, v27
	v_mul_f32_e32 v14, v14, v32
	v_lshlrev_b32_e32 v27, 23, v24
	v_mul_f32_e32 v14, 0x437e0000, v14
	v_sub_u32_e32 v27, 0x82800000, v27
	v_add_u32_e32 v24, -16, v24
	v_sub_f32_e32 v15, v15, v26
	v_cndmask_b32_e32 v14, 0, v14, vcc
	v_cmp_gt_u32_e32 vcc, s84, v24
	v_mul_f32_e32 v15, v15, v27
	v_lshlrev_b32_e32 v24, 16, v25
	v_bfe_u32 v26, v25, 7, 8
	v_mul_f32_e32 v15, 0x437e0000, v15
	v_lshlrev_b32_e32 v27, 23, v26
	v_add_u32_e32 v26, -16, v26
	v_sub_f32_e32 v20, v20, v24
	v_and_b32_e32 v24, 0xffff0000, v25
	v_bfe_u32 v25, v25, 23, 8
	v_cndmask_b32_e32 v15, 0, v15, vcc
	v_sub_u32_e32 v27, 0x82800000, v27
	v_cmp_gt_u32_e32 vcc, s84, v26
	v_lshlrev_b32_e32 v26, 23, v25
	v_mul_f32_e32 v20, v20, v27
	v_sub_u32_e32 v26, 0x82800000, v26
	v_sub_f32_e32 v21, v21, v24
	v_mul_f32_e32 v20, 0x437e0000, v20
	v_add_u32_e32 v25, -16, v25
	v_mul_f32_e32 v21, v21, v26
	v_cndmask_b32_e32 v20, 0, v20, vcc
	v_cmp_gt_u32_e32 vcc, s84, v25
	v_mul_f32_e32 v21, 0x437e0000, v21
	v_med3_f32 v15, v15, s81, v195
	v_cndmask_b32_e32 v21, 0, v21, vcc
	v_med3_f32 v14, v14, s81, v195
	v_rndne_f32_e32 v15, v15
	v_med3_f32 v20, v20, s81, v195
	v_rndne_f32_e32 v14, v14
	v_cvt_i32_f32_e32 v15, v15
	v_rndne_f32_e32 v20, v20
	v_med3_f32 v21, v21, s81, v195
	v_cvt_i32_f32_e32 v14, v14
	v_cvt_i32_f32_sdwa v20, v20 dst_sel:WORD_1 dst_unused:UNUSED_PAD src0_sel:DWORD
	v_rndne_f32_e32 v21, v21
	v_cvt_i32_f32_sdwa v21, v21 dst_sel:BYTE_3 dst_unused:UNUSED_PAD src0_sel:DWORD
	v_lshlrev_b32_e32 v15, 8, v15
	v_perm_b32 v14, v15, v14, s85
	v_and_b32_e32 v15, 0xff0000, v20
	v_or3_b32 v14, v14, v21, v15
	global_store_dword v[92:93], v14, off offset:3072
	v_pk_mul_f32 v[14:15], v[118:119], v[124:125] op_sel_hi:[1,0]
	v_pk_mul_f32 v[12:13], v[12:13], v[124:125] op_sel_hi:[1,0]
	s_waitcnt vmcnt(19)
	v_pk_fma_f32 v[14:15], v[14:15], v[38:39], v[42:43]
	v_pk_fma_f32 v[12:13], v[12:13], v[40:41], v[44:45]
	v_mul_f32_e32 v25, 0x41fe0000, v15
	v_mul_f32_e32 v24, 0x41fe0000, v14
	v_mul_f32_e32 v26, 0x41fe0000, v12
	v_mul_f32_e32 v27, 0x41fe0000, v13
	v_med3_f32 v25, v25, s81, v195
	v_med3_f32 v24, v24, s81, v195
	v_rndne_f32_e32 v25, v25
	v_med3_f32 v26, v26, s81, v195
	v_med3_f32 v27, v27, s81, v195
	v_rndne_f32_e32 v24, v24
	v_cvt_i32_f32_e32 v25, v25
	v_rndne_f32_e32 v26, v26
	v_rndne_f32_e32 v27, v27
	v_cvt_i32_f32_e32 v24, v24
	v_cvt_i32_f32_sdwa v26, v26 dst_sel:WORD_1 dst_unused:UNUSED_PAD src0_sel:DWORD
	v_cvt_i32_f32_e32 v27, v27
	v_lshlrev_b32_e32 v25, 8, v25
	v_and_b32_e32 v25, 0xff00, v25
	v_and_b32_e32 v26, 0xff0000, v26
	v_perm_b32 v24, v27, v24, s82
	s_nop 0
	v_cvt_pk_bf16_f32 v20, v14, v15
	v_or3_b32 v24, v24, v25, v26
	v_bfe_u32 v25, v20, 7, 8
	s_nop 0
	v_cvt_pk_bf16_f32 v21, v12, v13
	global_store_dwordx2 v[88:89], v[20:21], off offset:2560
	global_store_dword v[90:91], v24, off offset:3328
	v_lshlrev_b32_e32 v24, 16, v20
	v_lshlrev_b32_e32 v26, 23, v25
	v_sub_u32_e32 v26, 0x82800000, v26
	v_add_u32_e32 v25, -16, v25
	v_sub_f32_e32 v14, v14, v24
	v_and_b32_e32 v24, 0xffff0000, v20
	v_bfe_u32 v20, v20, 23, 8
	v_cmp_gt_u32_e32 vcc, s84, v25
	v_mul_f32_e32 v14, v14, v26
	v_lshlrev_b32_e32 v25, 23, v20
	v_mul_f32_e32 v14, 0x437e0000, v14
	v_sub_u32_e32 v25, 0x82800000, v25
	v_add_u32_e32 v20, -16, v20
	v_sub_f32_e32 v15, v15, v24
	v_cndmask_b32_e32 v14, 0, v14, vcc
	v_cmp_gt_u32_e32 vcc, s84, v20
	v_mul_f32_e32 v15, v15, v25
	v_lshlrev_b32_e32 v20, 16, v21
	v_bfe_u32 v24, v21, 7, 8
	v_mul_f32_e32 v15, 0x437e0000, v15
	v_lshlrev_b32_e32 v25, 23, v24
	v_add_u32_e32 v24, -16, v24
	v_sub_f32_e32 v12, v12, v20
	v_and_b32_e32 v20, 0xffff0000, v21
	v_bfe_u32 v21, v21, 23, 8
	v_cndmask_b32_e32 v15, 0, v15, vcc
	v_sub_u32_e32 v25, 0x82800000, v25
	v_cmp_gt_u32_e32 vcc, s84, v24
	v_lshlrev_b32_e32 v24, 23, v21
	v_mul_f32_e32 v12, v12, v25
	v_sub_u32_e32 v24, 0x82800000, v24
	v_sub_f32_e32 v13, v13, v20
	v_mul_f32_e32 v12, 0x437e0000, v12
	v_add_u32_e32 v21, -16, v21
	v_mul_f32_e32 v13, v13, v24
	v_cndmask_b32_e32 v12, 0, v12, vcc
	v_cmp_gt_u32_e32 vcc, s84, v21
	v_mul_f32_e32 v13, 0x437e0000, v13
	v_med3_f32 v15, v15, s81, v195
	v_cndmask_b32_e32 v13, 0, v13, vcc
	v_med3_f32 v14, v14, s81, v195
	v_rndne_f32_e32 v15, v15
	v_med3_f32 v12, v12, s81, v195
	v_rndne_f32_e32 v14, v14
	v_cvt_i32_f32_e32 v15, v15
	v_rndne_f32_e32 v12, v12
	v_med3_f32 v13, v13, s81, v195
	v_cvt_i32_f32_e32 v14, v14
	v_cvt_i32_f32_sdwa v12, v12 dst_sel:WORD_1 dst_unused:UNUSED_PAD src0_sel:DWORD
	v_rndne_f32_e32 v13, v13
	v_cvt_i32_f32_sdwa v13, v13 dst_sel:BYTE_3 dst_unused:UNUSED_PAD src0_sel:DWORD
	v_lshlrev_b32_e32 v15, 8, v15
	v_perm_b32 v14, v15, v14, s85
	v_and_b32_e32 v12, 0xff0000, v12
	v_or3_b32 v12, v14, v13, v12
	global_store_dword v[92:93], v12, off offset:3328
	v_pk_mul_f32 v[12:13], v[22:23], v[124:125] op_sel_hi:[1,0]
	v_pk_mul_f32 v[4:5], v[4:5], v[124:125] op_sel_hi:[1,0]
	s_waitcnt vmcnt(20)
	v_pk_fma_f32 v[12:13], v[12:13], v[28:29], v[34:35]
	v_pk_fma_f32 v[4:5], v[4:5], v[30:31], v[36:37]
	v_mul_f32_e32 v21, 0x41fe0000, v13
	v_mul_f32_e32 v20, 0x41fe0000, v12
	v_mul_f32_e32 v22, 0x41fe0000, v4
	v_mul_f32_e32 v23, 0x41fe0000, v5
	v_med3_f32 v21, v21, s81, v195
	v_med3_f32 v20, v20, s81, v195
	v_rndne_f32_e32 v21, v21
	v_med3_f32 v22, v22, s81, v195
	v_med3_f32 v23, v23, s81, v195
	v_rndne_f32_e32 v20, v20
	v_cvt_i32_f32_e32 v21, v21
	v_rndne_f32_e32 v22, v22
	v_rndne_f32_e32 v23, v23
	v_cvt_i32_f32_e32 v20, v20
	v_cvt_i32_f32_sdwa v22, v22 dst_sel:WORD_1 dst_unused:UNUSED_PAD src0_sel:DWORD
	v_cvt_i32_f32_e32 v23, v23
	v_lshlrev_b32_e32 v21, 8, v21
	v_and_b32_e32 v21, 0xff00, v21
	v_and_b32_e32 v22, 0xff0000, v22
	v_perm_b32 v20, v23, v20, s82
	s_nop 0
	v_cvt_pk_bf16_f32 v14, v12, v13
	v_or3_b32 v20, v20, v21, v22
	v_bfe_u32 v21, v14, 7, 8
	s_nop 0
	v_cvt_pk_bf16_f32 v15, v4, v5
	global_store_dwordx2 v[88:89], v[14:15], off offset:3072
	global_store_dword v[90:91], v20, off offset:3584
	v_lshlrev_b32_e32 v20, 16, v14
	v_lshlrev_b32_e32 v22, 23, v21
	v_sub_u32_e32 v22, 0x82800000, v22
	v_add_u32_e32 v21, -16, v21
	v_sub_f32_e32 v12, v12, v20
	v_and_b32_e32 v20, 0xffff0000, v14
	v_bfe_u32 v14, v14, 23, 8
	v_cmp_gt_u32_e32 vcc, s84, v21
	v_mul_f32_e32 v12, v12, v22
	v_lshlrev_b32_e32 v21, 23, v14
	v_mul_f32_e32 v12, 0x437e0000, v12
	v_sub_u32_e32 v21, 0x82800000, v21
	v_add_u32_e32 v14, -16, v14
	v_sub_f32_e32 v13, v13, v20
	v_cndmask_b32_e32 v12, 0, v12, vcc
	v_cmp_gt_u32_e32 vcc, s84, v14
	v_mul_f32_e32 v13, v13, v21
	v_lshlrev_b32_e32 v14, 16, v15
	v_bfe_u32 v20, v15, 7, 8
	v_mul_f32_e32 v13, 0x437e0000, v13
	v_lshlrev_b32_e32 v21, 23, v20
	v_add_u32_e32 v20, -16, v20
	v_sub_f32_e32 v4, v4, v14
	v_and_b32_e32 v14, 0xffff0000, v15
	v_bfe_u32 v15, v15, 23, 8
	v_cndmask_b32_e32 v13, 0, v13, vcc
	v_sub_u32_e32 v21, 0x82800000, v21
	v_cmp_gt_u32_e32 vcc, s84, v20
	v_lshlrev_b32_e32 v20, 23, v15
	v_mul_f32_e32 v4, v4, v21
	v_sub_u32_e32 v20, 0x82800000, v20
	v_sub_f32_e32 v5, v5, v14
	v_mul_f32_e32 v4, 0x437e0000, v4
	v_add_u32_e32 v15, -16, v15
	v_mul_f32_e32 v5, v5, v20
	v_cndmask_b32_e32 v4, 0, v4, vcc
	v_cmp_gt_u32_e32 vcc, s84, v15
	v_mul_f32_e32 v5, 0x437e0000, v5
	v_med3_f32 v13, v13, s81, v195
	v_cndmask_b32_e32 v5, 0, v5, vcc
	v_med3_f32 v12, v12, s81, v195
	v_rndne_f32_e32 v13, v13
	v_med3_f32 v4, v4, s81, v195
	v_rndne_f32_e32 v12, v12
	v_cvt_i32_f32_e32 v13, v13
	v_rndne_f32_e32 v4, v4
	v_med3_f32 v5, v5, s81, v195
	v_cvt_i32_f32_e32 v12, v12
	v_cvt_i32_f32_sdwa v4, v4 dst_sel:WORD_1 dst_unused:UNUSED_PAD src0_sel:DWORD
	v_rndne_f32_e32 v5, v5
	v_cvt_i32_f32_sdwa v5, v5 dst_sel:BYTE_3 dst_unused:UNUSED_PAD src0_sel:DWORD
	v_lshlrev_b32_e32 v13, 8, v13
	v_perm_b32 v12, v13, v12, s85
	v_and_b32_e32 v4, 0xff0000, v4
	v_or3_b32 v4, v12, v5, v4
	global_store_dword v[92:93], v4, off offset:3584
	v_pk_mul_f32 v[4:5], v[6:7], v[124:125] op_sel_hi:[1,0]
	v_pk_mul_f32 v[2:3], v[2:3], v[124:125] op_sel_hi:[1,0]
	s_waitcnt vmcnt(21)
	v_pk_fma_f32 v[6:7], v[4:5], v[8:9], v[16:17]
	v_lshl_add_u64 v[8:9], s[94:95], 0, v[110:111]
	v_pk_fma_f32 v[2:3], v[2:3], v[10:11], v[18:19]
	s_nop 0
	v_cvt_pk_bf16_f32 v4, v6, v7
	v_lshl_add_u64 v[114:115], v[114:115], 0, s[38:39]
	s_nop 0
	v_cvt_pk_bf16_f32 v5, v2, v3
	global_store_dwordx2 v[8:9], v[4:5], off
	v_mul_f32_e32 v9, 0x41fe0000, v7
	v_mul_f32_e32 v8, 0x41fe0000, v6
	v_mul_f32_e32 v10, 0x41fe0000, v2
	v_mul_f32_e32 v11, 0x41fe0000, v3
	v_med3_f32 v9, v9, s81, v195
	v_med3_f32 v8, v8, s81, v195
	v_rndne_f32_e32 v9, v9
	v_med3_f32 v10, v10, s81, v195
	v_med3_f32 v11, v11, s81, v195
	v_rndne_f32_e32 v8, v8
	v_cvt_i32_f32_e32 v9, v9
	v_rndne_f32_e32 v10, v10
	v_rndne_f32_e32 v11, v11
	v_cvt_i32_f32_e32 v8, v8
	v_cvt_i32_f32_sdwa v10, v10 dst_sel:WORD_1 dst_unused:UNUSED_PAD src0_sel:DWORD
	v_cvt_i32_f32_e32 v11, v11
	v_lshlrev_b32_e32 v9, 8, v9
	v_and_b32_e32 v9, 0xff00, v9
	v_and_b32_e32 v10, 0xff0000, v10
	v_perm_b32 v8, v11, v8, s82
	v_or3_b32 v12, v8, v9, v10
	v_lshl_add_u64 v[8:9], s[94:95], 0, v[116:117]
	v_add_co_u32_e32 v10, vcc, s83, v8
	v_lshl_add_u64 v[116:117], v[116:117], 0, s[38:39]
	s_nop 0
	v_addc_co_u32_e32 v11, vcc, 0, v9, vcc
	global_store_dword v[10:11], v12, off
	v_bfe_u32 v11, v4, 7, 8
	v_lshlrev_b32_e32 v10, 16, v4
	v_lshlrev_b32_e32 v12, 23, v11
	v_sub_u32_e32 v12, 0x82800000, v12
	v_sub_f32_e32 v6, v6, v10
	v_add_u32_e32 v11, -16, v11
	v_mul_f32_e32 v6, v6, v12
	v_and_b32_e32 v10, 0xffff0000, v4
	v_bfe_u32 v4, v4, 23, 8
	v_cmp_gt_u32_e32 vcc, s84, v11
	v_mul_f32_e32 v6, 0x437e0000, v6
	v_lshlrev_b32_e32 v11, 23, v4
	v_add_u32_e32 v4, -16, v4
	v_cndmask_b32_e32 v6, 0, v6, vcc
	v_sub_u32_e32 v11, 0x82800000, v11
	v_cmp_gt_u32_e32 vcc, s84, v4
	v_sub_f32_e32 v4, v7, v10
	v_mul_f32_e32 v4, v4, v11
	v_lshlrev_b32_e32 v7, 16, v5
	v_bfe_u32 v10, v5, 7, 8
	v_mul_f32_e32 v4, 0x437e0000, v4
	v_lshlrev_b32_e32 v11, 23, v10
	v_add_u32_e32 v10, -16, v10
	v_sub_f32_e32 v2, v2, v7
	v_and_b32_e32 v7, 0xffff0000, v5
	v_bfe_u32 v5, v5, 23, 8
	v_cndmask_b32_e32 v4, 0, v4, vcc
	v_sub_u32_e32 v11, 0x82800000, v11
	v_cmp_gt_u32_e32 vcc, s84, v10
	v_lshlrev_b32_e32 v10, 23, v5
	v_mul_f32_e32 v2, v2, v11
	v_sub_u32_e32 v10, 0x82800000, v10
	v_sub_f32_e32 v3, v3, v7
	v_mul_f32_e32 v2, 0x437e0000, v2
	v_add_u32_e32 v5, -16, v5
	v_mul_f32_e32 v3, v3, v10
	v_cndmask_b32_e32 v2, 0, v2, vcc
	v_cmp_gt_u32_e32 vcc, s84, v5
	v_mul_f32_e32 v3, 0x437e0000, v3
	v_med3_f32 v4, v4, s81, v195
	v_cndmask_b32_e32 v3, 0, v3, vcc
	v_med3_f32 v5, v6, s81, v195
	v_rndne_f32_e32 v4, v4
	v_med3_f32 v2, v2, s81, v195
	v_rndne_f32_e32 v5, v5
	v_cvt_i32_f32_e32 v4, v4
	v_rndne_f32_e32 v2, v2
	v_med3_f32 v3, v3, s81, v195
	v_cvt_i32_f32_e32 v5, v5
	v_cvt_i32_f32_sdwa v2, v2 dst_sel:WORD_1 dst_unused:UNUSED_PAD src0_sel:DWORD
	v_rndne_f32_e32 v3, v3
	v_cvt_i32_f32_sdwa v3, v3 dst_sel:BYTE_3 dst_unused:UNUSED_PAD src0_sel:DWORD
	v_lshlrev_b32_e32 v4, 8, v4
	v_perm_b32 v4, v4, v5, s85
	v_and_b32_e32 v2, 0xff0000, v2
	v_or3_b32 v4, v4, v3, v2
	v_add_co_u32_e32 v2, vcc, s86, v8
	v_lshl_add_u64 v[112:113], v[112:113], 0, s[42:43]
	s_nop 0
	v_addc_co_u32_e32 v3, vcc, 0, v9, vcc
	v_lshl_add_u64 v[110:111], v[110:111], 0, s[42:43]
	global_store_dword v[2:3], v4, off
	s_cbranch_scc1 .LBB0_17

.LBB0_38:
	v_add_u32_e32 v2, s64, v1
	v_mad_i64_i32 v[2:3], s[0:1], v2, s46, 0
	v_lshl_add_u64 v[2:3], v[2:3], 2, s[48:49]
	s_ashr_i32 s59, s58, 31
	s_ashr_i32 s47, s46, 31
	v_lshl_add_u64 v[2:3], s[58:59], 2, v[2:3]
	v_lshlrev_b32_e32 v216, 2, v198
	s_waitcnt vmcnt(13)
	v_lshl_add_u64 v[6:7], v[2:3], 0, v[216:217]
	s_lshl_b64 s[0:1], s[46:47], 5
	s_waitcnt vmcnt(11)
	v_lshl_add_u64 v[14:15], v[6:7], 0, s[0:1]
	s_waitcnt vmcnt(9)
	v_lshl_add_u64 v[22:23], v[14:15], 0, s[0:1]
	s_waitcnt vmcnt(7)
	v_lshl_add_u64 v[30:31], v[22:23], 0, s[0:1]
	s_waitcnt vmcnt(5)
	v_lshl_add_u64 v[38:39], v[30:31], 0, s[0:1]
	s_waitcnt vmcnt(3)
	v_lshl_add_u64 v[46:47], v[38:39], 0, s[0:1]
	s_waitcnt vmcnt(1)
	v_lshl_add_u64 v[54:55], v[46:47], 0, s[0:1]
	s_waitcnt vmcnt(0)
	v_lshl_add_u64 v[62:63], v[54:55], 0, s[0:1]
	global_load_dwordx4 v[2:5], v[6:7], off nt
	global_load_dwordx4 v[10:13], v[6:7], off offset:128 nt
	s_nop 0
	global_load_dwordx4 v[6:9], v[14:15], off nt
	global_load_dwordx4 v[18:21], v[14:15], off offset:128 nt
	s_nop 0
	global_load_dwordx4 v[14:17], v[22:23], off nt
	global_load_dwordx4 v[26:29], v[22:23], off offset:128 nt
	s_nop 0
	global_load_dwordx4 v[22:25], v[30:31], off nt
	global_load_dwordx4 v[34:37], v[30:31], off offset:128 nt
	s_nop 0
	global_load_dwordx4 v[30:33], v[38:39], off nt
	global_load_dwordx4 v[42:45], v[38:39], off offset:128 nt
	s_nop 0
	global_load_dwordx4 v[38:41], v[46:47], off nt
	global_load_dwordx4 v[50:53], v[46:47], off offset:128 nt
	s_nop 0
	global_load_dwordx4 v[46:49], v[54:55], off nt
	global_load_dwordx4 v[58:61], v[54:55], off offset:128 nt
	s_nop 0
	global_load_dwordx4 v[54:57], v[62:63], off nt
	s_nop 0
	global_load_dwordx4 v[62:65], v[62:63], off offset:128 nt
	s_branch .LBB0_40

.LBB0_67:
	v_add_u32_e32 v66, s60, v1
	v_mad_i64_i32 v[66:67], s[0:1], v66, s54, 0
	v_lshl_add_u64 v[66:67], v[66:67], 2, s[52:53]
	s_ashr_i32 s63, s62, 31
	s_ashr_i32 s55, s54, 31
	v_lshl_add_u64 v[66:67], s[62:63], 2, v[66:67]
	v_lshl_add_u64 v[66:67], v[66:67], 0, v[216:217]
	s_lshl_b64 s[0:1], s[54:55], 5
	v_lshl_add_u64 v[70:71], v[66:67], 0, s[0:1]
	v_lshl_add_u64 v[74:75], v[70:71], 0, s[0:1]
	v_lshl_add_u64 v[78:79], v[74:75], 0, s[0:1]
	v_lshl_add_u64 v[82:83], v[78:79], 0, s[0:1]
	v_lshl_add_u64 v[86:87], v[82:83], 0, s[0:1]
	v_lshl_add_u64 v[90:91], v[86:87], 0, s[0:1]
	v_lshl_add_u64 v[98:99], v[90:91], 0, s[0:1]
	global_load_dwordx4 v[94:97], v[66:67], off nt
	s_nop 0
	global_load_dwordx4 v[66:69], v[66:67], off offset:128 nt
	s_nop 0
	global_load_dwordx4 v[102:105], v[70:71], off nt
	s_nop 0
	global_load_dwordx4 v[70:73], v[70:71], off offset:128 nt
	s_nop 0
	global_load_dwordx4 v[106:109], v[74:75], off nt
	s_nop 0
	global_load_dwordx4 v[74:77], v[74:75], off offset:128 nt
	s_nop 0
	global_load_dwordx4 v[110:113], v[78:79], off nt
	s_nop 0
	global_load_dwordx4 v[78:81], v[78:79], off offset:128 nt
	s_nop 0
	global_load_dwordx4 v[114:117], v[82:83], off nt
	s_nop 0
	global_load_dwordx4 v[82:85], v[82:83], off offset:128 nt
	s_nop 0
	global_load_dwordx4 v[118:121], v[86:87], off nt
	s_nop 0
	global_load_dwordx4 v[86:89], v[86:87], off offset:128 nt
	s_nop 0
	global_load_dwordx4 v[122:125], v[90:91], off nt
	s_nop 0
	global_load_dwordx4 v[90:93], v[90:91], off offset:128 nt
	s_nop 0
	global_load_dwordx4 v[126:129], v[98:99], off nt
	s_nop 0
	global_load_dwordx4 v[98:101], v[98:99], off offset:128 nt

.LBB0_161:
	v_add_u32_e32 v2, s96, v1
	v_mad_i64_i32 v[2:3], s[0:1], v2, s46, 0
	v_lshl_add_u64 v[2:3], v[2:3], 2, s[48:49]
	s_ashr_i32 s59, s58, 31
	s_ashr_i32 s47, s46, 31
	v_lshl_add_u64 v[2:3], s[58:59], 2, v[2:3]
	v_lshl_add_u64 v[6:7], v[2:3], 0, v[216:217]
	s_lshl_b64 s[0:1], s[46:47], 5
	v_lshl_add_u64 v[14:15], v[6:7], 0, s[0:1]
	v_lshl_add_u64 v[22:23], v[14:15], 0, s[0:1]
	v_lshl_add_u64 v[30:31], v[22:23], 0, s[0:1]
	v_lshl_add_u64 v[38:39], v[30:31], 0, s[0:1]
	v_lshl_add_u64 v[46:47], v[38:39], 0, s[0:1]
	v_lshl_add_u64 v[54:55], v[46:47], 0, s[0:1]
	v_lshl_add_u64 v[62:63], v[54:55], 0, s[0:1]
	global_load_dwordx4 v[2:5], v[6:7], off nt
	global_load_dwordx4 v[10:13], v[6:7], off offset:128 nt
	s_nop 0
	global_load_dwordx4 v[6:9], v[14:15], off nt
	global_load_dwordx4 v[18:21], v[14:15], off offset:128 nt
	s_nop 0
	global_load_dwordx4 v[14:17], v[22:23], off nt
	global_load_dwordx4 v[26:29], v[22:23], off offset:128 nt
	s_nop 0
	global_load_dwordx4 v[22:25], v[30:31], off nt
	global_load_dwordx4 v[34:37], v[30:31], off offset:128 nt
	s_nop 0
	global_load_dwordx4 v[30:33], v[38:39], off nt
	global_load_dwordx4 v[42:45], v[38:39], off offset:128 nt
	s_nop 0
	global_load_dwordx4 v[38:41], v[46:47], off nt
	global_load_dwordx4 v[50:53], v[46:47], off offset:128 nt
	s_nop 0
	global_load_dwordx4 v[46:49], v[54:55], off nt
	global_load_dwordx4 v[58:61], v[54:55], off offset:128 nt
	s_nop 0
	global_load_dwordx4 v[54:57], v[62:63], off nt
	s_nop 0
	global_load_dwordx4 v[62:65], v[62:63], off offset:128 nt

.LBB0_231:
	s_andn2_b64 vcc, exec, s[4:5]
	s_cbranch_vccnz .LBB0_228
	v_lshl_add_u64 v[2:3], s[6:7], 0, v[202:203]
	global_load_dwordx4 v[64:67], v[2:3], off nt
	global_load_dwordx4 v[58:61], v[2:3], off offset:1024 nt
	global_load_dwordx4 v[54:57], v[2:3], off offset:2048 nt
	global_load_dwordx4 v[50:53], v[2:3], off offset:3072 nt
	v_add_co_u32_e32 v4, vcc, s9, v2
	s_add_i32 s0, s34, 0x4000
	s_nop 0
	v_addc_co_u32_e32 v5, vcc, 0, v3, vcc
	global_load_dwordx4 v[46:49], v[4:5], off offset:-4096 nt
	s_waitcnt vmcnt(18)
	v_add_co_u32_e32 v6, vcc, s8, v2
	s_ashr_i32 s1, s0, 31
	s_nop 0
	v_addc_co_u32_e32 v7, vcc, 0, v3, vcc
	global_load_dwordx4 v[42:45], v[6:7], off offset:1024 nt
	global_load_dwordx4 v[38:41], v[6:7], off offset:2048 nt
	global_load_dwordx4 v[34:37], v[6:7], off offset:3072 nt
	global_load_dwordx4 v[30:33], v[4:5], off nt
	global_load_dwordx4 v[26:29], v[4:5], off offset:1024 nt
	global_load_dwordx4 v[22:25], v[4:5], off offset:2048 nt
	global_load_dwordx4 v[18:21], v[4:5], off offset:3072 nt
	v_add_co_u32_e32 v2, vcc, s13, v2
	s_lshl_b64 s[4:5], s[0:1], 12
	s_nop 0
	v_addc_co_u32_e32 v3, vcc, 0, v3, vcc
	global_load_dwordx4 v[14:17], v[2:3], off nt
	global_load_dwordx4 v[10:13], v[2:3], off offset:1024 nt
	global_load_dwordx4 v[6:9], v[2:3], off offset:2048 nt
	v_lshl_add_u64 v[2:3], s[6:7], 0, v[172:173]
	global_load_dwordx4 v[2:5], v[2:3], off nt
	v_cmp_lt_i32_e32 vcc, v122, v121
	s_lshl_b64 s[0:1], s[0:1], 13
	s_add_u32 s26, s10, s0
	s_addc_u32 s27, s11, s1
	v_readlane_b32 s0, v254, 54
	s_add_u32 s24, s0, s4
	v_readlane_b32 s0, v254, 56
	s_addc_u32 s25, s0, s5
	v_readlane_b32 s0, v254, 58
	v_readlane_b32 s1, v254, 59
	s_add_u32 s22, s0, s4
	s_addc_u32 s23, s1, s5
	s_waitcnt vmcnt(15)
	v_mov_b32_e32 v62, v65
	v_mov_b32_e32 v63, v66
	v_mov_b32_e32 v68, v64
	v_mov_b32_e32 v69, v67
	s_waitcnt vmcnt(14)
	v_mov_b32_e32 v70, v59
	v_mov_b32_e32 v71, v60
	v_mov_b32_e32 v72, v58
	v_mov_b32_e32 v73, v61
	v_pk_add_f32 v[62:63], v[62:63], v[68:69]
	v_pk_add_f32 v[68:69], v[70:71], v[72:73]
	v_add_f32_e32 v78, v62, v63
	v_pk_add_f32 v[62:63], v[68:69], v[68:69] op_sel:[0,1] op_sel_hi:[1,0]
	s_waitcnt vmcnt(13)
	v_add_f32_e32 v74, v54, v55
	v_add_f32_e32 v76, v56, v57
	s_waitcnt vmcnt(12)
	v_mov_b32_e32 v79, v50
	v_mov_b32_e32 v75, v52
	v_mov_b32_e32 v77, v53
	v_add_f32_e32 v78, 0, v78
	v_mov_b32_e32 v63, v51
	v_pk_add_f32 v[70:71], v[74:75], v[76:77]
	s_waitcnt vmcnt(11)
	v_mov_b32_e32 v72, v47
	v_mov_b32_e32 v73, v48
	v_mov_b32_e32 v74, v46
	v_mov_b32_e32 v75, v49
	v_pk_add_f32 v[62:63], v[78:79], v[62:63]
	v_pk_add_f32 v[68:69], v[72:73], v[74:75]
	v_pk_add_f32 v[62:63], v[62:63], v[70:71]
	v_pk_add_f32 v[68:69], v[68:69], v[68:69] op_sel:[0,1] op_sel_hi:[1,0]
	v_pk_add_f32 v[62:63], v[62:63], v[62:63] op_sel:[0,1] op_sel_hi:[1,0]
	s_waitcnt vmcnt(10)
	v_add_f32_e32 v76, v42, v43
	v_add_f32_e32 v80, v44, v45
	s_waitcnt vmcnt(9)
	v_mov_b32_e32 v77, v40
	v_mov_b32_e32 v81, v41
	v_mov_b32_e32 v69, v39
	v_mov_b32_e32 v63, v38
	s_waitcnt vmcnt(8)
	v_mov_b32_e32 v82, v35
	v_mov_b32_e32 v83, v36
	v_mov_b32_e32 v84, v34
	v_mov_b32_e32 v85, v37
	v_pk_add_f32 v[72:73], v[76:77], v[80:81]
	v_pk_add_f32 v[62:63], v[62:63], v[68:69]
	v_pk_add_f32 v[74:75], v[82:83], v[84:85]
	v_pk_add_f32 v[62:63], v[62:63], v[72:73]
	v_pk_add_f32 v[74:75], v[74:75], v[74:75] op_sel:[0,1] op_sel_hi:[1,0]
	v_pk_add_f32 v[62:63], v[62:63], v[62:63] op_sel:[0,1] op_sel_hi:[1,0]
	s_waitcnt vmcnt(7)
	v_add_f32_e32 v86, v30, v31
	v_add_f32_e32 v88, v32, v33
	s_waitcnt vmcnt(6)
	v_mov_b32_e32 v87, v28
	v_mov_b32_e32 v89, v29
	v_mov_b32_e32 v75, v27
	v_mov_b32_e32 v63, v26
	s_waitcnt vmcnt(5)
	v_mov_b32_e32 v90, v23
	v_mov_b32_e32 v91, v24
	v_mov_b32_e32 v92, v22
	v_mov_b32_e32 v93, v25
	v_pk_add_f32 v[76:77], v[86:87], v[88:89]
	v_pk_add_f32 v[62:63], v[62:63], v[74:75]
	v_pk_add_f32 v[80:81], v[90:91], v[92:93]
	v_pk_add_f32 v[62:63], v[62:63], v[76:77]
	v_pk_add_f32 v[80:81], v[80:81], v[80:81] op_sel:[0,1] op_sel_hi:[1,0]
	v_pk_add_f32 v[62:63], v[62:63], v[62:63] op_sel:[0,1] op_sel_hi:[1,0]
	s_waitcnt vmcnt(4)
	v_add_f32_e32 v94, v18, v19
	v_add_f32_e32 v96, v20, v21
	s_waitcnt vmcnt(3)
	v_mov_b32_e32 v95, v16
	v_mov_b32_e32 v97, v17
	v_mov_b32_e32 v81, v15
	v_mov_b32_e32 v63, v14
	v_pk_add_f32 v[62:63], v[62:63], v[80:81]
	v_pk_add_f32 v[68:69], v[94:95], v[96:97]
	s_waitcnt vmcnt(2)
	v_mov_b32_e32 v70, v10
	v_pk_add_f32 v[62:63], v[62:63], v[68:69]
	v_mov_b32_e32 v68, v11
	v_mov_b32_e32 v69, v12
	v_mov_b32_e32 v71, v13
	v_pk_add_f32 v[68:69], v[68:69], v[70:71]
	v_pk_add_f32 v[62:63], v[62:63], v[62:63] op_sel:[0,1] op_sel_hi:[1,0]
	v_pk_add_f32 v[68:69], v[68:69], v[68:69] op_sel:[0,1] op_sel_hi:[1,0]
	s_waitcnt vmcnt(1)
	v_add_f32_e32 v70, v6, v7
	v_add_f32_e32 v72, v8, v9
	s_waitcnt vmcnt(0)
	v_mov_b32_e32 v63, v2
	v_mov_b32_e32 v69, v3
	v_mov_b32_e32 v71, v4
	v_mov_b32_e32 v73, v5
	v_pk_add_f32 v[62:63], v[62:63], v[68:69]
	v_pk_add_f32 v[68:69], v[70:71], v[72:73]
	s_nop 0
	v_pk_add_f32 v[62:63], v[62:63], v[68:69]
	s_nop 0
	v_add_f32_e32 v62, v62, v63
	v_cndmask_b32_e32 v63, v232, v122, vcc
	v_lshlrev_b32_e32 v76, 2, v63
	ds_bpermute_b32 v63, v76, v62
	v_cmp_lt_i32_e32 vcc, v123, v121
	s_waitcnt lgkmcnt(0)
	v_add_f32_e32 v62, v62, v63
	v_cndmask_b32_e32 v63, v232, v123, vcc
	v_lshlrev_b32_e32 v78, 2, v63
	ds_bpermute_b32 v63, v78, v62
	v_cmp_lt_i32_e32 vcc, v124, v121
	s_waitcnt lgkmcnt(0)
	v_add_f32_e32 v62, v62, v63
	v_cndmask_b32_e32 v63, v232, v124, vcc
	v_lshlrev_b32_e32 v79, 2, v63
	ds_bpermute_b32 v63, v79, v62
	v_cmp_lt_i32_e32 vcc, v125, v121
	s_waitcnt lgkmcnt(0)
	v_add_f32_e32 v62, v62, v63
	v_cndmask_b32_e32 v63, v232, v125, vcc
	v_lshlrev_b32_e32 v80, 2, v63
	ds_bpermute_b32 v63, v80, v62
	v_cmp_lt_i32_e32 vcc, v126, v121
	s_waitcnt lgkmcnt(0)
	v_add_f32_e32 v62, v62, v63
	v_cndmask_b32_e32 v63, v232, v126, vcc
	v_lshlrev_b32_e32 v81, 2, v63
	ds_bpermute_b32 v63, v81, v62
	v_cmp_lt_i32_e32 vcc, v127, v121
	s_waitcnt lgkmcnt(0)
	v_add_f32_e32 v62, v62, v63
	v_cndmask_b32_e32 v63, v232, v127, vcc
	v_lshlrev_b32_e32 v82, 2, v63
	ds_bpermute_b32 v63, v82, v62
	s_waitcnt lgkmcnt(0)
	v_add_f32_e32 v77, v62, v63
	v_fmamk_f32 v73, v77, 0xb9800000, v65
	v_fmamk_f32 v72, v77, 0xb9800000, v64
	v_fmamk_f32 v67, v77, 0xb9800000, v67
	v_fmac_f32_e32 v66, 0xb9800000, v77
	v_pk_mul_f32 v[62:63], v[66:67], v[66:67]
	v_pk_mul_f32 v[64:65], v[72:73], v[72:73]
	v_fmamk_f32 v71, v77, 0xb9800000, v59
	v_pk_mov_b32 v[68:69], v[64:65], v[62:63] op_sel:[1,0]
	v_mov_b32_e32 v65, v63
	v_fmamk_f32 v70, v77, 0xb9800000, v58
	v_fmamk_f32 v61, v77, 0xb9800000, v61
	v_fmac_f32_e32 v60, 0xb9800000, v77
	v_pk_add_f32 v[62:63], v[68:69], v[64:65]
	v_pk_mul_f32 v[58:59], v[60:61], v[60:61]
	v_pk_mul_f32 v[64:65], v[70:71], v[70:71]
	v_fmac_f32_e32 v56, 0xb9800000, v77
	v_pk_mov_b32 v[68:69], v[64:65], v[58:59] op_sel:[1,0]
	v_mov_b32_e32 v65, v59
	v_pk_add_f32 v[58:59], v[68:69], v[64:65]
	v_fmamk_f32 v68, v77, 0xb9800000, v54
	v_fmamk_f32 v69, v77, 0xb9800000, v55
	v_mul_f32_e32 v54, v68, v68
	v_pk_fma_f32 v[54:55], v[68:69], v[68:69], v[54:55] op_sel_hi:[1,1,0]
	v_fmamk_f32 v57, v77, 0xb9800000, v57
	v_mul_f32_e32 v54, v56, v56
	v_pk_add_f32 v[62:63], v[62:63], v[62:63] op_sel_hi:[0,1]
	v_pk_add_f32 v[64:65], v[58:59], v[58:59] op_sel_hi:[0,1]
	v_pk_fma_f32 v[74:75], v[56:57], v[56:57], v[54:55] op_sel_hi:[1,1,0]
	v_fmamk_f32 v59, v77, 0xb9800000, v53
	v_fmamk_f32 v58, v77, 0xb9800000, v52
	v_fmamk_f32 v51, v77, 0xb9800000, v51
	v_fmac_f32_e32 v50, 0xb9800000, v77
	v_mul_f32_e32 v54, v50, v50
	v_mul_f32_e32 v74, v51, v51
	v_mul_f32_e32 v62, v58, v58
	v_mul_f32_e32 v64, v59, v59
	v_pk_add_f32 v[52:53], v[54:55], v[74:75]
	v_pk_add_f32 v[54:55], v[62:63], v[64:65]
	v_fmamk_f32 v119, v77, 0xb9800000, v47
	v_fmamk_f32 v118, v77, 0xb9800000, v46
	v_fmamk_f32 v49, v77, 0xb9800000, v49
	v_fmac_f32_e32 v48, 0xb9800000, v77
	v_fmamk_f32 v116, v77, 0xb9800000, v42
	v_pk_add_f32 v[52:53], v[52:53], v[54:55]
	v_pk_mul_f32 v[46:47], v[48:49], v[48:49]
	v_pk_mul_f32 v[54:55], v[118:119], v[118:119]
	v_fmamk_f32 v117, v77, 0xb9800000, v43
	v_mul_f32_e32 v42, v116, v116
	v_pk_mov_b32 v[62:63], v[54:55], v[46:47] op_sel:[1,0]
	v_mov_b32_e32 v55, v47
	v_fmac_f32_e32 v44, 0xb9800000, v77
	v_pk_fma_f32 v[42:43], v[116:117], v[116:117], v[42:43] op_sel_hi:[1,1,0]
	v_pk_add_f32 v[46:47], v[62:63], v[54:55]
	v_fmamk_f32 v45, v77, 0xb9800000, v45
	v_mul_f32_e32 v42, v44, v44
	v_pk_add_f32 v[52:53], v[52:53], v[52:53] op_sel_hi:[0,1]
	v_pk_add_f32 v[54:55], v[46:47], v[46:47] op_sel_hi:[0,1]
	v_pk_fma_f32 v[62:63], v[44:45], v[44:45], v[42:43] op_sel_hi:[1,1,0]
	v_fmamk_f32 v47, v77, 0xb9800000, v41
	v_fmamk_f32 v46, v77, 0xb9800000, v40
	v_fmamk_f32 v39, v77, 0xb9800000, v39
	v_fmac_f32_e32 v38, 0xb9800000, v77
	v_mul_f32_e32 v42, v38, v38
	v_mul_f32_e32 v62, v39, v39
	v_mul_f32_e32 v54, v46, v46
	v_mul_f32_e32 v52, v47, v47
	v_pk_add_f32 v[40:41], v[42:43], v[62:63]
	v_pk_add_f32 v[42:43], v[54:55], v[52:53]
	v_fmamk_f32 v35, v77, 0xb9800000, v35
	v_fmamk_f32 v34, v77, 0xb9800000, v34
	v_fmamk_f32 v37, v77, 0xb9800000, v37
	v_fmac_f32_e32 v36, 0xb9800000, v77
	v_fmamk_f32 v114, v77, 0xb9800000, v30
	v_pk_add_f32 v[40:41], v[40:41], v[42:43]
	v_pk_mul_f32 v[42:43], v[36:37], v[36:37]
	v_pk_mul_f32 v[52:53], v[34:35], v[34:35]
	v_fmamk_f32 v115, v77, 0xb9800000, v31
	v_mul_f32_e32 v30, v114, v114
	v_pk_mov_b32 v[54:55], v[52:53], v[42:43] op_sel:[1,0]
	v_mov_b32_e32 v53, v43
	v_fmac_f32_e32 v32, 0xb9800000, v77
	v_pk_fma_f32 v[30:31], v[114:115], v[114:115], v[30:31] op_sel_hi:[1,1,0]
	v_pk_add_f32 v[42:43], v[54:55], v[52:53]
	v_fmamk_f32 v33, v77, 0xb9800000, v33
	v_mul_f32_e32 v30, v32, v32
	v_pk_add_f32 v[40:41], v[40:41], v[40:41] op_sel_hi:[0,1]
	v_pk_add_f32 v[42:43], v[42:43], v[42:43] op_sel_hi:[0,1]
	v_pk_fma_f32 v[52:53], v[32:33], v[32:33], v[30:31] op_sel_hi:[1,1,0]
	v_fmamk_f32 v113, v77, 0xb9800000, v29
	v_fmamk_f32 v112, v77, 0xb9800000, v28
	v_fmamk_f32 v27, v77, 0xb9800000, v27
	v_fmac_f32_e32 v26, 0xb9800000, v77
	v_mul_f32_e32 v30, v26, v26
	v_mul_f32_e32 v52, v27, v27
	v_mul_f32_e32 v42, v112, v112
	v_mul_f32_e32 v40, v113, v113
	v_pk_add_f32 v[28:29], v[30:31], v[52:53]
	v_pk_add_f32 v[30:31], v[42:43], v[40:41]
	v_fmamk_f32 v111, v77, 0xb9800000, v23
	v_fmamk_f32 v110, v77, 0xb9800000, v22
	v_fmamk_f32 v25, v77, 0xb9800000, v25
	v_fmac_f32_e32 v24, 0xb9800000, v77
	v_fmamk_f32 v108, v77, 0xb9800000, v18
	v_pk_add_f32 v[28:29], v[28:29], v[30:31]
	v_pk_mul_f32 v[22:23], v[24:25], v[24:25]
	v_pk_mul_f32 v[30:31], v[110:111], v[110:111]
	v_fmamk_f32 v109, v77, 0xb9800000, v19
	v_mul_f32_e32 v18, v108, v108
	v_pk_mov_b32 v[40:41], v[30:31], v[22:23] op_sel:[1,0]
	v_mov_b32_e32 v31, v23
	v_fmac_f32_e32 v20, 0xb9800000, v77
	v_pk_fma_f32 v[18:19], v[108:109], v[108:109], v[18:19] op_sel_hi:[1,1,0]
	v_pk_add_f32 v[22:23], v[40:41], v[30:31]
	v_fmamk_f32 v21, v77, 0xb9800000, v21
	v_mul_f32_e32 v18, v20, v20
	v_pk_add_f32 v[28:29], v[28:29], v[28:29] op_sel_hi:[0,1]
	v_pk_add_f32 v[22:23], v[22:23], v[22:23] op_sel_hi:[0,1]
	v_pk_fma_f32 v[30:31], v[20:21], v[20:21], v[18:19] op_sel_hi:[1,1,0]
	v_fmamk_f32 v107, v77, 0xb9800000, v17
	v_fmamk_f32 v106, v77, 0xb9800000, v16
	v_fmamk_f32 v15, v77, 0xb9800000, v15
	v_fmac_f32_e32 v14, 0xb9800000, v77
	v_mul_f32_e32 v18, v14, v14
	v_mul_f32_e32 v30, v15, v15
	v_mul_f32_e32 v22, v106, v106
	v_mul_f32_e32 v28, v107, v107
	v_pk_add_f32 v[16:17], v[18:19], v[30:31]
	v_pk_add_f32 v[18:19], v[22:23], v[28:29]
	v_fmamk_f32 v105, v77, 0xb9800000, v11
	v_fmamk_f32 v104, v77, 0xb9800000, v10
	v_fmamk_f32 v13, v77, 0xb9800000, v13
	v_fmac_f32_e32 v12, 0xb9800000, v77
	v_fmamk_f32 v102, v77, 0xb9800000, v6
	v_pk_add_f32 v[16:17], v[16:17], v[18:19]
	v_pk_mul_f32 v[10:11], v[12:13], v[12:13]
	v_pk_mul_f32 v[18:19], v[104:105], v[104:105]
	v_fmamk_f32 v103, v77, 0xb9800000, v7
	v_mul_f32_e32 v6, v102, v102
	v_pk_mov_b32 v[22:23], v[18:19], v[10:11] op_sel:[1,0]
	v_mov_b32_e32 v19, v11
	v_fmac_f32_e32 v8, 0xb9800000, v77
	v_pk_fma_f32 v[6:7], v[102:103], v[102:103], v[6:7] op_sel_hi:[1,1,0]
	v_pk_add_f32 v[10:11], v[22:23], v[18:19]
	v_fmamk_f32 v9, v77, 0xb9800000, v9
	v_mul_f32_e32 v6, v8, v8
	v_pk_add_f32 v[16:17], v[16:17], v[16:17] op_sel_hi:[0,1]
	v_pk_add_f32 v[18:19], v[10:11], v[10:11] op_sel_hi:[0,1]
	v_pk_fma_f32 v[22:23], v[8:9], v[8:9], v[6:7] op_sel_hi:[1,1,0]
	v_fmamk_f32 v11, v77, 0xb9800000, v5
	v_fmamk_f32 v10, v77, 0xb9800000, v4
	v_fmamk_f32 v3, v77, 0xb9800000, v3
	v_fmac_f32_e32 v2, 0xb9800000, v77
	v_mul_f32_e32 v6, v2, v2
	v_mul_f32_e32 v22, v3, v3
	v_mul_f32_e32 v18, v10, v10
	v_mul_f32_e32 v16, v11, v11
	v_pk_add_f32 v[4:5], v[6:7], v[22:23]
	v_pk_add_f32 v[6:7], v[18:19], v[16:17]
	s_nop 0
	v_pk_add_f32 v[4:5], v[4:5], v[6:7]
	s_nop 0
	v_add_f32_e32 v4, v4, v5
	ds_bpermute_b32 v5, v76, v4
	global_load_dwordx4 v[74:77], v[174:175], off
	global_load_dwordx4 v[94:97], v[176:177], off
	global_load_dwordx4 v[98:101], v[174:175], off offset:1024
	global_load_dwordx4 v[206:209], v[176:177], off offset:1024
	global_load_dwordx4 v[210:213], v[174:175], off offset:2048
	global_load_dwordx4 v[28:31], v[174:175], off offset:3072
	global_load_dwordx4 v[214:217], v[176:177], off offset:2048
	global_load_dwordx4 v[40:43], v[176:177], off offset:3072
	s_waitcnt lgkmcnt(0)
	v_add_f32_e32 v4, v4, v5
	ds_bpermute_b32 v5, v78, v4
	s_waitcnt lgkmcnt(0)
	v_add_f32_e32 v4, v4, v5
	ds_bpermute_b32 v5, v79, v4
	s_waitcnt lgkmcnt(0)
	v_add_f32_e32 v4, v4, v5
	ds_bpermute_b32 v5, v80, v4
	s_waitcnt lgkmcnt(0)
	v_add_f32_e32 v4, v4, v5
	ds_bpermute_b32 v5, v81, v4
	s_waitcnt lgkmcnt(0)
	v_add_f32_e32 v4, v4, v5
	ds_bpermute_b32 v5, v82, v4
	s_waitcnt lgkmcnt(0)
	v_add_f32_e32 v4, v4, v5
	v_fmamk_f32 v4, v4, 0x39800000, v128
	v_mul_f32_e32 v5, 0x4f800000, v4
	v_cmp_gt_f32_e32 vcc, s28, v4
	s_nop 1
	v_cndmask_b32_e32 v4, v4, v5, vcc
	v_sqrt_f32_e32 v5, v4
	s_nop 0
	v_add_u32_e32 v6, -1, v5
	v_fma_f32 v7, -v6, v5, v4
	v_cmp_ge_f32_e64 s[4:5], 0, v7
	v_add_u32_e32 v7, 1, v5
	s_nop 0
	v_cndmask_b32_e64 v6, v5, v6, s[4:5]
	v_fma_f32 v5, -v7, v5, v4
	v_cmp_lt_f32_e64 s[4:5], 0, v5
	s_nop 1
	v_cndmask_b32_e64 v5, v6, v7, s[4:5]
	v_mul_f32_e32 v6, 0x37800000, v5
	v_cndmask_b32_e32 v5, v5, v6, vcc
	v_cmp_class_f32_e32 vcc, v4, v129
	s_nop 1
	v_cndmask_b32_e32 v4, v5, v4, vcc
	v_div_scale_f32 v5, s[0:1], v4, v4, 1.0
	v_rcp_f32_e32 v6, v5
	s_nop 0
	v_fma_f32 v7, -v5, v6, 1.0
	v_fmac_f32_e32 v6, v7, v6
	v_div_scale_f32 v7, vcc, 1.0, v4, 1.0
	v_mul_f32_e32 v16, v7, v6
	v_fma_f32 v17, -v5, v16, v7
	v_fmac_f32_e32 v16, v17, v6
	v_fma_f32 v5, -v5, v16, v7
	v_div_fmas_f32 v5, v5, v6, v16
	v_div_fixup_f32 v22, v5, v4, 1.0
	v_pk_mul_f32 v[72:73], v[72:73], v[22:23] op_sel_hi:[1,0]
	v_pk_mul_f32 v[66:67], v[66:67], v[22:23] op_sel_hi:[1,0]
	s_waitcnt vmcnt(6)
	v_pk_fma_f32 v[72:73], v[74:75], v[72:73], v[94:95]
	v_pk_fma_f32 v[66:67], v[76:77], v[66:67], v[96:97]
	v_mul_f32_e32 v76, 0x41fe0000, v73
	v_mul_f32_e32 v23, 0x41fe0000, v72
	v_mul_f32_e32 v77, 0x41fe0000, v66
	v_mul_f32_e32 v94, 0x41fe0000, v67
	v_med3_f32 v76, v76, s29, v204
	v_med3_f32 v23, v23, s29, v204
	v_rndne_f32_e32 v76, v76
	v_med3_f32 v77, v77, s29, v204
	v_med3_f32 v94, v94, s29, v204
	v_rndne_f32_e32 v23, v23
	v_cvt_i32_f32_e32 v76, v76
	v_rndne_f32_e32 v77, v77
	v_rndne_f32_e32 v94, v94
	v_cvt_i32_f32_e32 v23, v23
	v_cvt_i32_f32_sdwa v77, v77 dst_sel:WORD_1 dst_unused:UNUSED_PAD src0_sel:DWORD
	v_cvt_i32_f32_e32 v94, v94
	v_lshlrev_b32_e32 v76, 8, v76
	v_and_b32_e32 v76, 0xff00, v76
	v_and_b32_e32 v77, 0xff0000, v77
	v_perm_b32 v23, v94, v23, s30
	global_load_dwordx4 v[86:89], v[130:131], off
	global_load_dwordx4 v[90:93], v[132:133], off
	global_load_dwordx4 v[78:81], v[134:135], off
	global_load_dwordx4 v[82:85], v[136:137], off
	global_load_dwordx4 v[52:55], v[138:139], off
	global_load_dwordx4 v[62:65], v[140:141], off
	global_load_dwordx4 v[4:7], v[142:143], off
	global_load_dwordx4 v[16:19], v[144:145], off
	s_nop 0
	v_cvt_pk_bf16_f32 v74, v72, v73
	v_or3_b32 v23, v23, v76, v77
	v_bfe_u32 v76, v74, 7, 8
	s_nop 0
	v_cvt_pk_bf16_f32 v75, v66, v67
	global_store_dwordx2 v155, v[74:75], s[26:27]
	global_store_dword v191, v23, s[24:25]
	v_lshlrev_b32_e32 v23, 16, v74
	v_lshlrev_b32_e32 v77, 23, v76
	v_sub_u32_e32 v77, 0x82800000, v77
	v_add_u32_e32 v76, -16, v76
	v_sub_f32_e32 v23, v72, v23
	v_and_b32_e32 v72, 0xffff0000, v74
	v_bfe_u32 v74, v74, 23, 8
	v_mul_f32_e32 v23, v23, v77
	v_cmp_gt_u32_e32 vcc, s31, v76
	v_lshlrev_b32_e32 v76, 23, v74
	v_mul_f32_e32 v23, 0x437e0000, v23
	v_sub_u32_e32 v76, 0x82800000, v76
	v_add_u32_e32 v74, -16, v74
	v_sub_f32_e32 v72, v73, v72
	v_cndmask_b32_e32 v23, 0, v23, vcc
	v_mul_f32_e32 v72, v72, v76
	v_cmp_gt_u32_e32 vcc, s31, v74
	v_bfe_u32 v74, v75, 7, 8
	v_mul_f32_e32 v72, 0x437e0000, v72
	v_lshlrev_b32_e32 v76, 23, v74
	v_add_u32_e32 v74, -16, v74
	v_cndmask_b32_e32 v72, 0, v72, vcc
	v_lshlrev_b32_e32 v73, 16, v75
	v_cmp_gt_u32_e32 vcc, s31, v74
	v_bfe_u32 v74, v75, 23, 8
	v_sub_u32_e32 v76, 0x82800000, v76
	v_sub_f32_e32 v66, v66, v73
	v_and_b32_e32 v73, 0xffff0000, v75
	v_lshlrev_b32_e32 v75, 23, v74
	v_mul_f32_e32 v66, v66, v76
	v_sub_u32_e32 v75, 0x82800000, v75
	v_sub_f32_e32 v67, v67, v73
	v_mul_f32_e32 v66, 0x437e0000, v66
	v_add_u32_e32 v74, -16, v74
	v_mul_f32_e32 v67, v67, v75
	v_cndmask_b32_e32 v66, 0, v66, vcc
	v_mul_f32_e32 v67, 0x437e0000, v67
	v_cmp_gt_u32_e32 vcc, s31, v74
	v_med3_f32 v72, v72, s29, v204
	v_med3_f32 v23, v23, s29, v204
	v_cndmask_b32_e32 v67, 0, v67, vcc
	v_rndne_f32_e32 v72, v72
	v_med3_f32 v66, v66, s29, v204
	v_rndne_f32_e32 v23, v23
	v_cvt_i32_f32_e32 v72, v72
	v_rndne_f32_e32 v66, v66
	v_med3_f32 v67, v67, s29, v204
	v_cvt_i32_f32_e32 v23, v23
	v_cvt_i32_f32_sdwa v66, v66 dst_sel:WORD_1 dst_unused:UNUSED_PAD src0_sel:DWORD
	v_rndne_f32_e32 v67, v67
	v_cvt_i32_f32_sdwa v67, v67 dst_sel:BYTE_3 dst_unused:UNUSED_PAD src0_sel:DWORD
	v_lshlrev_b32_e32 v72, 8, v72
	v_perm_b32 v23, v72, v23, s33
	v_and_b32_e32 v66, 0xff0000, v66
	v_or3_b32 v23, v23, v67, v66
	v_pk_mul_f32 v[66:67], v[70:71], v[22:23] op_sel_hi:[1,0]
	v_pk_mul_f32 v[60:61], v[60:61], v[22:23] op_sel_hi:[1,0]
	s_waitcnt vmcnt(14)
	v_pk_fma_f32 v[66:67], v[98:99], v[66:67], v[206:207]
	v_pk_fma_f32 v[60:61], v[100:101], v[60:61], v[208:209]
	v_mul_f32_e32 v72, 0x41fe0000, v67
	global_store_dword v191, v23, s[22:23]
	v_mul_f32_e32 v23, 0x41fe0000, v66
	v_mul_f32_e32 v73, 0x41fe0000, v60
	v_mul_f32_e32 v74, 0x41fe0000, v61
	v_med3_f32 v72, v72, s29, v204
	v_med3_f32 v23, v23, s29, v204
	v_rndne_f32_e32 v72, v72
	v_med3_f32 v73, v73, s29, v204
	v_med3_f32 v74, v74, s29, v204
	v_rndne_f32_e32 v23, v23
	v_cvt_i32_f32_e32 v72, v72
	v_rndne_f32_e32 v73, v73
	v_rndne_f32_e32 v74, v74
	v_cvt_i32_f32_e32 v23, v23
	v_cvt_i32_f32_sdwa v73, v73 dst_sel:WORD_1 dst_unused:UNUSED_PAD src0_sel:DWORD
	v_cvt_i32_f32_e32 v74, v74
	v_lshlrev_b32_e32 v72, 8, v72
	v_and_b32_e32 v72, 0xff00, v72
	v_and_b32_e32 v73, 0xff0000, v73
	v_perm_b32 v23, v74, v23, s30
	s_nop 0
	v_cvt_pk_bf16_f32 v70, v66, v67
	v_or3_b32 v23, v23, v72, v73
	v_bfe_u32 v72, v70, 7, 8
	s_nop 0
	v_cvt_pk_bf16_f32 v71, v60, v61
	global_store_dwordx2 v155, v[70:71], s[26:27] offset:512
	global_store_dword v191, v23, s[24:25] offset:256
	v_lshlrev_b32_e32 v23, 16, v70
	v_lshlrev_b32_e32 v73, 23, v72
	v_sub_u32_e32 v73, 0x82800000, v73
	v_add_u32_e32 v72, -16, v72
	v_sub_f32_e32 v23, v66, v23
	v_and_b32_e32 v66, 0xffff0000, v70
	v_bfe_u32 v70, v70, 23, 8
	v_mul_f32_e32 v23, v23, v73
	v_cmp_gt_u32_e32 vcc, s31, v72
	v_lshlrev_b32_e32 v72, 23, v70
	v_mul_f32_e32 v23, 0x437e0000, v23
	v_sub_u32_e32 v72, 0x82800000, v72
	v_add_u32_e32 v70, -16, v70
	v_sub_f32_e32 v66, v67, v66
	v_cndmask_b32_e32 v23, 0, v23, vcc
	v_mul_f32_e32 v66, v66, v72
	v_cmp_gt_u32_e32 vcc, s31, v70
	v_bfe_u32 v70, v71, 7, 8
	v_mul_f32_e32 v66, 0x437e0000, v66
	v_lshlrev_b32_e32 v72, 23, v70
	v_add_u32_e32 v70, -16, v70
	v_cndmask_b32_e32 v66, 0, v66, vcc
	v_lshlrev_b32_e32 v67, 16, v71
	v_cmp_gt_u32_e32 vcc, s31, v70
	v_bfe_u32 v70, v71, 23, 8
	v_sub_u32_e32 v72, 0x82800000, v72
	v_sub_f32_e32 v60, v60, v67
	v_and_b32_e32 v67, 0xffff0000, v71
	v_lshlrev_b32_e32 v71, 23, v70
	v_mul_f32_e32 v60, v60, v72
	v_sub_u32_e32 v71, 0x82800000, v71
	v_sub_f32_e32 v61, v61, v67
	v_mul_f32_e32 v60, 0x437e0000, v60
	v_add_u32_e32 v70, -16, v70
	v_mul_f32_e32 v61, v61, v71
	v_cndmask_b32_e32 v60, 0, v60, vcc
	v_mul_f32_e32 v61, 0x437e0000, v61
	v_cmp_gt_u32_e32 vcc, s31, v70
	v_med3_f32 v66, v66, s29, v204
	v_med3_f32 v23, v23, s29, v204
	v_cndmask_b32_e32 v61, 0, v61, vcc
	v_rndne_f32_e32 v66, v66
	v_med3_f32 v60, v60, s29, v204
	v_rndne_f32_e32 v23, v23
	v_cvt_i32_f32_e32 v66, v66
	v_rndne_f32_e32 v60, v60
	v_med3_f32 v61, v61, s29, v204
	v_cvt_i32_f32_e32 v23, v23
	v_cvt_i32_f32_sdwa v60, v60 dst_sel:WORD_1 dst_unused:UNUSED_PAD src0_sel:DWORD
	v_rndne_f32_e32 v61, v61
	v_cvt_i32_f32_sdwa v61, v61 dst_sel:BYTE_3 dst_unused:UNUSED_PAD src0_sel:DWORD
	v_lshlrev_b32_e32 v66, 8, v66
	v_perm_b32 v23, v66, v23, s33
	v_and_b32_e32 v60, 0xff0000, v60
	v_or3_b32 v23, v23, v61, v60
	v_pk_mul_f32 v[60:61], v[68:69], v[22:23] op_sel_hi:[1,0]
	v_pk_mul_f32 v[56:57], v[56:57], v[22:23] op_sel_hi:[1,0]
	s_waitcnt vmcnt(14)
	v_pk_fma_f32 v[60:61], v[210:211], v[60:61], v[214:215]
	v_pk_fma_f32 v[56:57], v[212:213], v[56:57], v[216:217]
	v_mul_f32_e32 v68, 0x41fe0000, v61
	global_store_dword v191, v23, s[22:23] offset:256
	v_mul_f32_e32 v23, 0x41fe0000, v60
	v_mul_f32_e32 v69, 0x41fe0000, v56
	v_mul_f32_e32 v70, 0x41fe0000, v57
	v_med3_f32 v68, v68, s29, v204
	v_med3_f32 v23, v23, s29, v204
	v_rndne_f32_e32 v68, v68
	v_med3_f32 v69, v69, s29, v204
	v_med3_f32 v70, v70, s29, v204
	v_rndne_f32_e32 v23, v23
	v_cvt_i32_f32_e32 v68, v68
	v_rndne_f32_e32 v69, v69
	v_rndne_f32_e32 v70, v70
	v_cvt_i32_f32_e32 v23, v23
	v_cvt_i32_f32_sdwa v69, v69 dst_sel:WORD_1 dst_unused:UNUSED_PAD src0_sel:DWORD
	v_cvt_i32_f32_e32 v70, v70
	v_lshlrev_b32_e32 v68, 8, v68
	v_and_b32_e32 v68, 0xff00, v68
	v_and_b32_e32 v69, 0xff0000, v69
	v_perm_b32 v23, v70, v23, s30
	s_nop 0
	v_cvt_pk_bf16_f32 v66, v60, v61
	v_or3_b32 v23, v23, v68, v69
	v_bfe_u32 v68, v66, 7, 8
	s_nop 0
	v_cvt_pk_bf16_f32 v67, v56, v57
	global_store_dwordx2 v155, v[66:67], s[26:27] offset:1024
	global_store_dword v191, v23, s[24:25] offset:512
	v_lshlrev_b32_e32 v23, 16, v66
	v_lshlrev_b32_e32 v69, 23, v68
	v_sub_u32_e32 v69, 0x82800000, v69
	v_add_u32_e32 v68, -16, v68
	v_sub_f32_e32 v23, v60, v23
	v_and_b32_e32 v60, 0xffff0000, v66
	v_bfe_u32 v66, v66, 23, 8
	v_mul_f32_e32 v23, v23, v69
	v_cmp_gt_u32_e32 vcc, s31, v68
	v_lshlrev_b32_e32 v68, 23, v66
	v_mul_f32_e32 v23, 0x437e0000, v23
	v_sub_u32_e32 v68, 0x82800000, v68
	v_add_u32_e32 v66, -16, v66
	v_sub_f32_e32 v60, v61, v60
	v_cndmask_b32_e32 v23, 0, v23, vcc
	v_mul_f32_e32 v60, v60, v68
	v_cmp_gt_u32_e32 vcc, s31, v66
	v_bfe_u32 v66, v67, 7, 8
	v_mul_f32_e32 v60, 0x437e0000, v60
	v_lshlrev_b32_e32 v68, 23, v66
	v_add_u32_e32 v66, -16, v66
	v_cndmask_b32_e32 v60, 0, v60, vcc
	v_lshlrev_b32_e32 v61, 16, v67
	v_cmp_gt_u32_e32 vcc, s31, v66
	v_bfe_u32 v66, v67, 23, 8
	v_sub_u32_e32 v68, 0x82800000, v68
	v_sub_f32_e32 v56, v56, v61
	v_and_b32_e32 v61, 0xffff0000, v67
	v_lshlrev_b32_e32 v67, 23, v66
	v_mul_f32_e32 v56, v56, v68
	v_sub_u32_e32 v67, 0x82800000, v67
	v_sub_f32_e32 v57, v57, v61
	v_mul_f32_e32 v56, 0x437e0000, v56
	v_add_u32_e32 v66, -16, v66
	v_mul_f32_e32 v57, v57, v67
	v_cndmask_b32_e32 v56, 0, v56, vcc
	v_mul_f32_e32 v57, 0x437e0000, v57
	v_cmp_gt_u32_e32 vcc, s31, v66
	v_med3_f32 v60, v60, s29, v204
	v_med3_f32 v23, v23, s29, v204
	v_cndmask_b32_e32 v57, 0, v57, vcc
	v_rndne_f32_e32 v60, v60
	v_med3_f32 v56, v56, s29, v204
	v_rndne_f32_e32 v23, v23
	v_cvt_i32_f32_e32 v60, v60
	v_rndne_f32_e32 v56, v56
	v_med3_f32 v57, v57, s29, v204
	v_cvt_i32_f32_e32 v23, v23
	v_cvt_i32_f32_sdwa v56, v56 dst_sel:WORD_1 dst_unused:UNUSED_PAD src0_sel:DWORD
	v_rndne_f32_e32 v57, v57
	v_cvt_i32_f32_sdwa v57, v57 dst_sel:BYTE_3 dst_unused:UNUSED_PAD src0_sel:DWORD
	v_lshlrev_b32_e32 v60, 8, v60
	v_perm_b32 v23, v60, v23, s33
	v_and_b32_e32 v56, 0xff0000, v56
	v_or3_b32 v23, v23, v57, v56
	v_pk_mul_f32 v[50:51], v[50:51], v[22:23] op_sel_hi:[1,0]
	v_pk_mul_f32 v[56:57], v[58:59], v[22:23] op_sel_hi:[1,0]
	s_waitcnt vmcnt(16)
	v_pk_fma_f32 v[28:29], v[28:29], v[50:51], v[40:41]
	v_pk_fma_f32 v[30:31], v[30:31], v[56:57], v[42:43]
	v_mul_f32_e32 v42, 0x41fe0000, v29
	global_store_dword v191, v23, s[22:23] offset:512
	v_mul_f32_e32 v23, 0x41fe0000, v28
	v_mul_f32_e32 v43, 0x41fe0000, v30
	v_mul_f32_e32 v50, 0x41fe0000, v31
	v_med3_f32 v42, v42, s29, v204
	v_med3_f32 v23, v23, s29, v204
	v_rndne_f32_e32 v42, v42
	v_med3_f32 v43, v43, s29, v204
	v_med3_f32 v50, v50, s29, v204
	v_rndne_f32_e32 v23, v23
	v_cvt_i32_f32_e32 v42, v42
	v_rndne_f32_e32 v43, v43
	v_rndne_f32_e32 v50, v50
	v_cvt_i32_f32_e32 v23, v23
	v_cvt_i32_f32_sdwa v43, v43 dst_sel:WORD_1 dst_unused:UNUSED_PAD src0_sel:DWORD
	v_cvt_i32_f32_e32 v50, v50
	v_lshlrev_b32_e32 v42, 8, v42
	v_and_b32_e32 v42, 0xff00, v42
	v_and_b32_e32 v43, 0xff0000, v43
	v_perm_b32 v23, v50, v23, s30
	s_nop 0
	v_cvt_pk_bf16_f32 v40, v28, v29
	v_or3_b32 v23, v23, v42, v43
	v_bfe_u32 v42, v40, 7, 8
	s_nop 0
	v_cvt_pk_bf16_f32 v41, v30, v31
	global_store_dwordx2 v155, v[40:41], s[26:27] offset:1536
	global_store_dword v191, v23, s[24:25] offset:768
	v_lshlrev_b32_e32 v23, 16, v40
	v_lshlrev_b32_e32 v43, 23, v42
	v_sub_u32_e32 v43, 0x82800000, v43
	v_add_u32_e32 v42, -16, v42
	v_sub_f32_e32 v23, v28, v23
	v_and_b32_e32 v28, 0xffff0000, v40
	v_bfe_u32 v40, v40, 23, 8
	v_mul_f32_e32 v23, v23, v43
	v_cmp_gt_u32_e32 vcc, s31, v42
	v_lshlrev_b32_e32 v42, 23, v40
	v_mul_f32_e32 v23, 0x437e0000, v23
	v_sub_u32_e32 v42, 0x82800000, v42
	v_add_u32_e32 v40, -16, v40
	v_sub_f32_e32 v28, v29, v28
	v_cndmask_b32_e32 v23, 0, v23, vcc
	v_mul_f32_e32 v28, v28, v42
	v_cmp_gt_u32_e32 vcc, s31, v40
	v_bfe_u32 v40, v41, 7, 8
	v_mul_f32_e32 v28, 0x437e0000, v28
	v_lshlrev_b32_e32 v42, 23, v40
	v_add_u32_e32 v40, -16, v40
	v_cndmask_b32_e32 v28, 0, v28, vcc
	v_lshlrev_b32_e32 v29, 16, v41
	v_cmp_gt_u32_e32 vcc, s31, v40
	v_bfe_u32 v40, v41, 23, 8
	v_sub_u32_e32 v42, 0x82800000, v42
	v_sub_f32_e32 v29, v30, v29
	v_and_b32_e32 v30, 0xffff0000, v41
	v_lshlrev_b32_e32 v41, 23, v40
	v_mul_f32_e32 v29, v29, v42
	v_sub_u32_e32 v41, 0x82800000, v41
	v_sub_f32_e32 v30, v31, v30
	v_mul_f32_e32 v29, 0x437e0000, v29
	v_add_u32_e32 v40, -16, v40
	v_mul_f32_e32 v30, v30, v41
	v_cndmask_b32_e32 v29, 0, v29, vcc
	v_mul_f32_e32 v30, 0x437e0000, v30
	v_cmp_gt_u32_e32 vcc, s31, v40
	v_med3_f32 v28, v28, s29, v204
	v_med3_f32 v23, v23, s29, v204
	v_cndmask_b32_e32 v30, 0, v30, vcc
	v_rndne_f32_e32 v28, v28
	v_med3_f32 v29, v29, s29, v204
	v_rndne_f32_e32 v23, v23
	v_cvt_i32_f32_e32 v28, v28
	v_rndne_f32_e32 v29, v29
	v_med3_f32 v30, v30, s29, v204
	v_cvt_i32_f32_e32 v23, v23
	v_cvt_i32_f32_sdwa v29, v29 dst_sel:WORD_1 dst_unused:UNUSED_PAD src0_sel:DWORD
	v_rndne_f32_e32 v30, v30
	v_cvt_i32_f32_sdwa v30, v30 dst_sel:BYTE_3 dst_unused:UNUSED_PAD src0_sel:DWORD
	v_lshlrev_b32_e32 v28, 8, v28
	v_perm_b32 v23, v28, v23, s33
	v_and_b32_e32 v28, 0xff0000, v29
	v_or3_b32 v23, v23, v30, v28
	v_pk_mul_f32 v[50:51], v[118:119], v[22:23] op_sel_hi:[1,0]
	v_pk_mul_f32 v[48:49], v[48:49], v[22:23] op_sel_hi:[1,0]
	s_waitcnt vmcnt(17)
	v_pk_fma_f32 v[50:51], v[86:87], v[50:51], v[90:91]
	v_pk_fma_f32 v[48:49], v[88:89], v[48:49], v[92:93]
	v_mul_f32_e32 v86, 0x41fe0000, v51
	global_store_dword v191, v23, s[22:23] offset:768
	v_mul_f32_e32 v23, 0x41fe0000, v50
	v_mul_f32_e32 v87, 0x41fe0000, v48
	v_mul_f32_e32 v88, 0x41fe0000, v49
	v_med3_f32 v86, v86, s29, v204
	v_med3_f32 v23, v23, s29, v204
	v_rndne_f32_e32 v86, v86
	v_med3_f32 v87, v87, s29, v204
	v_med3_f32 v88, v88, s29, v204
	v_rndne_f32_e32 v23, v23
	v_cvt_i32_f32_e32 v86, v86
	v_rndne_f32_e32 v87, v87
	v_rndne_f32_e32 v88, v88
	v_cvt_i32_f32_e32 v23, v23
	v_cvt_i32_f32_sdwa v87, v87 dst_sel:WORD_1 dst_unused:UNUSED_PAD src0_sel:DWORD
	v_cvt_i32_f32_e32 v88, v88
	v_lshlrev_b32_e32 v86, 8, v86
	v_and_b32_e32 v86, 0xff00, v86
	v_and_b32_e32 v87, 0xff0000, v87
	v_perm_b32 v23, v88, v23, s30
	global_load_dwordx4 v[94:97], v[146:147], off
	global_load_dwordx4 v[98:101], v[148:149], off
	global_load_dwordx4 v[70:73], v[150:151], off
	global_load_dwordx4 v[74:77], v[152:153], off
	global_load_dwordx4 v[56:59], v[156:157], off
	global_load_dwordx4 v[66:69], v[158:159], off
	global_load_dwordx4 v[28:31], v[160:161], off
	global_load_dwordx4 v[40:43], v[162:163], off
	s_nop 0
	v_cvt_pk_bf16_f32 v60, v50, v51
	v_or3_b32 v23, v23, v86, v87
	v_bfe_u32 v86, v60, 7, 8
	s_nop 0
	v_cvt_pk_bf16_f32 v61, v48, v49
	global_store_dwordx2 v155, v[60:61], s[26:27] offset:2048
	global_store_dword v191, v23, s[24:25] offset:1024
	v_lshlrev_b32_e32 v23, 16, v60
	v_lshlrev_b32_e32 v87, 23, v86
	v_sub_u32_e32 v87, 0x82800000, v87
	v_add_u32_e32 v86, -16, v86
	v_sub_f32_e32 v23, v50, v23
	v_and_b32_e32 v50, 0xffff0000, v60
	v_bfe_u32 v60, v60, 23, 8
	v_mul_f32_e32 v23, v23, v87
	v_cmp_gt_u32_e32 vcc, s31, v86
	v_lshlrev_b32_e32 v86, 23, v60
	v_mul_f32_e32 v23, 0x437e0000, v23
	v_sub_u32_e32 v86, 0x82800000, v86
	v_add_u32_e32 v60, -16, v60
	v_sub_f32_e32 v50, v51, v50
	v_cndmask_b32_e32 v23, 0, v23, vcc
	v_mul_f32_e32 v50, v50, v86
	v_cmp_gt_u32_e32 vcc, s31, v60
	v_bfe_u32 v60, v61, 7, 8
	v_mul_f32_e32 v50, 0x437e0000, v50
	v_lshlrev_b32_e32 v86, 23, v60
	v_add_u32_e32 v60, -16, v60
	v_cndmask_b32_e32 v50, 0, v50, vcc
	v_lshlrev_b32_e32 v51, 16, v61
	v_cmp_gt_u32_e32 vcc, s31, v60
	v_bfe_u32 v60, v61, 23, 8
	v_sub_u32_e32 v86, 0x82800000, v86
	v_sub_f32_e32 v48, v48, v51
	v_and_b32_e32 v51, 0xffff0000, v61
	v_lshlrev_b32_e32 v61, 23, v60
	v_mul_f32_e32 v48, v48, v86
	v_sub_u32_e32 v61, 0x82800000, v61
	v_sub_f32_e32 v49, v49, v51
	v_mul_f32_e32 v48, 0x437e0000, v48
	v_add_u32_e32 v60, -16, v60
	v_mul_f32_e32 v49, v49, v61
	v_cndmask_b32_e32 v48, 0, v48, vcc
	v_mul_f32_e32 v49, 0x437e0000, v49
	v_cmp_gt_u32_e32 vcc, s31, v60
	v_med3_f32 v50, v50, s29, v204
	v_med3_f32 v23, v23, s29, v204
	v_cndmask_b32_e32 v49, 0, v49, vcc
	v_rndne_f32_e32 v50, v50
	v_med3_f32 v48, v48, s29, v204
	v_rndne_f32_e32 v23, v23
	v_cvt_i32_f32_e32 v50, v50
	v_rndne_f32_e32 v48, v48
	v_med3_f32 v49, v49, s29, v204
	v_cvt_i32_f32_e32 v23, v23
	v_cvt_i32_f32_sdwa v48, v48 dst_sel:WORD_1 dst_unused:UNUSED_PAD src0_sel:DWORD
	v_rndne_f32_e32 v49, v49
	v_cvt_i32_f32_sdwa v49, v49 dst_sel:BYTE_3 dst_unused:UNUSED_PAD src0_sel:DWORD
	v_lshlrev_b32_e32 v50, 8, v50
	v_perm_b32 v23, v50, v23, s33
	v_and_b32_e32 v48, 0xff0000, v48
	v_or3_b32 v23, v23, v49, v48
	v_pk_mul_f32 v[48:49], v[116:117], v[22:23] op_sel_hi:[1,0]
	v_pk_mul_f32 v[44:45], v[44:45], v[22:23] op_sel_hi:[1,0]
	s_waitcnt vmcnt(26)
	v_pk_fma_f32 v[48:49], v[78:79], v[48:49], v[82:83]
	v_pk_fma_f32 v[44:45], v[80:81], v[44:45], v[84:85]
	v_mul_f32_e32 v60, 0x41fe0000, v49
	global_store_dword v191, v23, s[22:23] offset:1024
	v_mul_f32_e32 v23, 0x41fe0000, v48
	v_mul_f32_e32 v61, 0x41fe0000, v44
	v_mul_f32_e32 v78, 0x41fe0000, v45
	v_med3_f32 v60, v60, s29, v204
	v_med3_f32 v23, v23, s29, v204
	v_rndne_f32_e32 v60, v60
	v_med3_f32 v61, v61, s29, v204
	v_med3_f32 v78, v78, s29, v204
	v_rndne_f32_e32 v23, v23
	v_cvt_i32_f32_e32 v60, v60
	v_rndne_f32_e32 v61, v61
	v_rndne_f32_e32 v78, v78
	v_cvt_i32_f32_e32 v23, v23
	v_cvt_i32_f32_sdwa v61, v61 dst_sel:WORD_1 dst_unused:UNUSED_PAD src0_sel:DWORD
	v_cvt_i32_f32_e32 v78, v78
	v_lshlrev_b32_e32 v60, 8, v60
	v_and_b32_e32 v60, 0xff00, v60
	v_and_b32_e32 v61, 0xff0000, v61
	v_perm_b32 v23, v78, v23, s30
	s_nop 0
	v_cvt_pk_bf16_f32 v50, v48, v49
	v_or3_b32 v23, v23, v60, v61
	v_bfe_u32 v60, v50, 7, 8
	s_nop 0
	v_cvt_pk_bf16_f32 v51, v44, v45
	global_store_dwordx2 v155, v[50:51], s[26:27] offset:2560
	global_store_dword v191, v23, s[24:25] offset:1280
	v_lshlrev_b32_e32 v23, 16, v50
	v_lshlrev_b32_e32 v61, 23, v60
	v_sub_u32_e32 v61, 0x82800000, v61
	v_add_u32_e32 v60, -16, v60
	v_sub_f32_e32 v23, v48, v23
	v_and_b32_e32 v48, 0xffff0000, v50
	v_bfe_u32 v50, v50, 23, 8
	v_mul_f32_e32 v23, v23, v61
	v_cmp_gt_u32_e32 vcc, s31, v60
	v_lshlrev_b32_e32 v60, 23, v50
	v_mul_f32_e32 v23, 0x437e0000, v23
	v_sub_u32_e32 v60, 0x82800000, v60
	v_add_u32_e32 v50, -16, v50
	v_sub_f32_e32 v48, v49, v48
	v_cndmask_b32_e32 v23, 0, v23, vcc
	v_mul_f32_e32 v48, v48, v60
	v_cmp_gt_u32_e32 vcc, s31, v50
	v_bfe_u32 v50, v51, 7, 8
	v_mul_f32_e32 v48, 0x437e0000, v48
	v_lshlrev_b32_e32 v60, 23, v50
	v_add_u32_e32 v50, -16, v50
	v_cndmask_b32_e32 v48, 0, v48, vcc
	v_lshlrev_b32_e32 v49, 16, v51
	v_cmp_gt_u32_e32 vcc, s31, v50
	v_bfe_u32 v50, v51, 23, 8
	v_sub_u32_e32 v60, 0x82800000, v60
	v_sub_f32_e32 v44, v44, v49
	v_and_b32_e32 v49, 0xffff0000, v51
	v_lshlrev_b32_e32 v51, 23, v50
	v_mul_f32_e32 v44, v44, v60
	v_sub_u32_e32 v51, 0x82800000, v51
	v_sub_f32_e32 v45, v45, v49
	v_mul_f32_e32 v44, 0x437e0000, v44
	v_add_u32_e32 v50, -16, v50
	v_mul_f32_e32 v45, v45, v51
	v_cndmask_b32_e32 v44, 0, v44, vcc
	v_mul_f32_e32 v45, 0x437e0000, v45
	v_cmp_gt_u32_e32 vcc, s31, v50
	v_med3_f32 v48, v48, s29, v204
	v_med3_f32 v23, v23, s29, v204
	v_cndmask_b32_e32 v45, 0, v45, vcc
	v_rndne_f32_e32 v48, v48
	v_med3_f32 v44, v44, s29, v204
	v_rndne_f32_e32 v23, v23
	v_cvt_i32_f32_e32 v48, v48
	v_rndne_f32_e32 v44, v44
	v_med3_f32 v45, v45, s29, v204
	v_cvt_i32_f32_e32 v23, v23
	v_cvt_i32_f32_sdwa v44, v44 dst_sel:WORD_1 dst_unused:UNUSED_PAD src0_sel:DWORD
	v_rndne_f32_e32 v45, v45
	v_cvt_i32_f32_sdwa v45, v45 dst_sel:BYTE_3 dst_unused:UNUSED_PAD src0_sel:DWORD
	v_lshlrev_b32_e32 v48, 8, v48
	v_perm_b32 v23, v48, v23, s33
	v_and_b32_e32 v44, 0xff0000, v44
	v_or3_b32 v23, v23, v45, v44
	v_pk_mul_f32 v[38:39], v[38:39], v[22:23] op_sel_hi:[1,0]
	v_pk_mul_f32 v[44:45], v[46:47], v[22:23] op_sel_hi:[1,0]
	s_waitcnt vmcnt(27)
	v_pk_fma_f32 v[38:39], v[52:53], v[38:39], v[62:63]
	v_pk_fma_f32 v[44:45], v[54:55], v[44:45], v[64:65]
	v_mul_f32_e32 v48, 0x41fe0000, v39
	global_store_dword v191, v23, s[22:23] offset:1280
	v_mul_f32_e32 v23, 0x41fe0000, v38
	v_mul_f32_e32 v49, 0x41fe0000, v44
	v_mul_f32_e32 v50, 0x41fe0000, v45
	v_med3_f32 v48, v48, s29, v204
	v_med3_f32 v23, v23, s29, v204
	v_rndne_f32_e32 v48, v48
	v_med3_f32 v49, v49, s29, v204
	v_med3_f32 v50, v50, s29, v204
	v_rndne_f32_e32 v23, v23
	v_cvt_i32_f32_e32 v48, v48
	v_rndne_f32_e32 v49, v49
	v_rndne_f32_e32 v50, v50
	v_cvt_i32_f32_e32 v23, v23
	v_cvt_i32_f32_sdwa v49, v49 dst_sel:WORD_1 dst_unused:UNUSED_PAD src0_sel:DWORD
	v_cvt_i32_f32_e32 v50, v50
	v_lshlrev_b32_e32 v48, 8, v48
	v_and_b32_e32 v48, 0xff00, v48
	v_and_b32_e32 v49, 0xff0000, v49
	v_perm_b32 v23, v50, v23, s30
	s_nop 0
	v_cvt_pk_bf16_f32 v46, v38, v39
	v_or3_b32 v23, v23, v48, v49
	v_bfe_u32 v48, v46, 7, 8
	s_nop 0
	v_cvt_pk_bf16_f32 v47, v44, v45
	global_store_dwordx2 v155, v[46:47], s[26:27] offset:3072
	global_store_dword v191, v23, s[24:25] offset:1536
	v_lshlrev_b32_e32 v23, 16, v46
	v_lshlrev_b32_e32 v49, 23, v48
	v_sub_u32_e32 v49, 0x82800000, v49
	v_add_u32_e32 v48, -16, v48
	v_sub_f32_e32 v23, v38, v23
	v_and_b32_e32 v38, 0xffff0000, v46
	v_bfe_u32 v46, v46, 23, 8
	v_mul_f32_e32 v23, v23, v49
	v_cmp_gt_u32_e32 vcc, s31, v48
	v_lshlrev_b32_e32 v48, 23, v46
	v_mul_f32_e32 v23, 0x437e0000, v23
	v_sub_u32_e32 v48, 0x82800000, v48
	v_add_u32_e32 v46, -16, v46
	v_sub_f32_e32 v38, v39, v38
	v_cndmask_b32_e32 v23, 0, v23, vcc
	v_mul_f32_e32 v38, v38, v48
	v_cmp_gt_u32_e32 vcc, s31, v46
	v_bfe_u32 v46, v47, 7, 8
	v_mul_f32_e32 v38, 0x437e0000, v38
	v_lshlrev_b32_e32 v48, 23, v46
	v_add_u32_e32 v46, -16, v46
	v_cndmask_b32_e32 v38, 0, v38, vcc
	v_lshlrev_b32_e32 v39, 16, v47
	v_cmp_gt_u32_e32 vcc, s31, v46
	v_bfe_u32 v46, v47, 23, 8
	v_sub_u32_e32 v48, 0x82800000, v48
	v_sub_f32_e32 v39, v44, v39
	v_and_b32_e32 v44, 0xffff0000, v47
	v_lshlrev_b32_e32 v47, 23, v46
	v_mul_f32_e32 v39, v39, v48
	v_sub_u32_e32 v47, 0x82800000, v47
	v_sub_f32_e32 v44, v45, v44
	v_mul_f32_e32 v39, 0x437e0000, v39
	v_add_u32_e32 v46, -16, v46
	v_mul_f32_e32 v44, v44, v47
	v_cndmask_b32_e32 v39, 0, v39, vcc
	v_mul_f32_e32 v44, 0x437e0000, v44
	v_cmp_gt_u32_e32 vcc, s31, v46
	v_med3_f32 v38, v38, s29, v204
	v_med3_f32 v23, v23, s29, v204
	v_cndmask_b32_e32 v44, 0, v44, vcc
	v_rndne_f32_e32 v38, v38
	v_med3_f32 v39, v39, s29, v204
	v_rndne_f32_e32 v23, v23
	v_cvt_i32_f32_e32 v38, v38
	v_rndne_f32_e32 v39, v39
	v_med3_f32 v44, v44, s29, v204
	v_cvt_i32_f32_e32 v23, v23
	v_cvt_i32_f32_sdwa v39, v39 dst_sel:WORD_1 dst_unused:UNUSED_PAD src0_sel:DWORD
	v_rndne_f32_e32 v44, v44
	v_cvt_i32_f32_sdwa v44, v44 dst_sel:BYTE_3 dst_unused:UNUSED_PAD src0_sel:DWORD
	v_lshlrev_b32_e32 v38, 8, v38
	v_perm_b32 v23, v38, v23, s33
	v_and_b32_e32 v38, 0xff0000, v39
	v_or3_b32 v23, v23, v44, v38
	v_pk_mul_f32 v[34:35], v[34:35], v[22:23] op_sel_hi:[1,0]
	v_pk_mul_f32 v[36:37], v[36:37], v[22:23] op_sel_hi:[1,0]
	s_waitcnt vmcnt(28)
	v_pk_fma_f32 v[4:5], v[4:5], v[34:35], v[16:17]
	v_pk_fma_f32 v[6:7], v[6:7], v[36:37], v[18:19]
	v_mul_f32_e32 v19, 0x41fe0000, v5
	global_store_dword v191, v23, s[22:23] offset:1536
	v_mul_f32_e32 v18, 0x41fe0000, v4
	v_mul_f32_e32 v23, 0x41fe0000, v6
	v_mul_f32_e32 v34, 0x41fe0000, v7
	v_med3_f32 v19, v19, s29, v204
	v_med3_f32 v18, v18, s29, v204
	v_rndne_f32_e32 v19, v19
	v_med3_f32 v23, v23, s29, v204
	v_med3_f32 v34, v34, s29, v204
	v_rndne_f32_e32 v18, v18
	v_cvt_i32_f32_e32 v19, v19
	v_rndne_f32_e32 v23, v23
	v_rndne_f32_e32 v34, v34
	v_cvt_i32_f32_e32 v18, v18
	v_cvt_i32_f32_sdwa v23, v23 dst_sel:WORD_1 dst_unused:UNUSED_PAD src0_sel:DWORD
	v_cvt_i32_f32_e32 v34, v34
	v_lshlrev_b32_e32 v19, 8, v19
	v_and_b32_e32 v19, 0xff00, v19
	v_and_b32_e32 v23, 0xff0000, v23
	v_perm_b32 v18, v34, v18, s30
	s_nop 0
	v_cvt_pk_bf16_f32 v16, v4, v5
	v_or3_b32 v18, v18, v19, v23
	v_bfe_u32 v19, v16, 7, 8
	s_nop 0
	v_cvt_pk_bf16_f32 v17, v6, v7
	global_store_dwordx2 v155, v[16:17], s[26:27] offset:3584
	global_store_dword v191, v18, s[24:25] offset:1792
	v_lshlrev_b32_e32 v18, 16, v16
	v_lshlrev_b32_e32 v23, 23, v19
	v_sub_u32_e32 v23, 0x82800000, v23
	v_add_u32_e32 v19, -16, v19
	v_sub_f32_e32 v4, v4, v18
	v_and_b32_e32 v18, 0xffff0000, v16
	v_bfe_u32 v16, v16, 23, 8
	v_mul_f32_e32 v4, v4, v23
	v_cmp_gt_u32_e32 vcc, s31, v19
	v_lshlrev_b32_e32 v19, 23, v16
	v_mul_f32_e32 v4, 0x437e0000, v4
	v_sub_u32_e32 v19, 0x82800000, v19
	v_add_u32_e32 v16, -16, v16
	v_sub_f32_e32 v5, v5, v18
	v_cndmask_b32_e32 v4, 0, v4, vcc
	v_mul_f32_e32 v5, v5, v19
	v_cmp_gt_u32_e32 vcc, s31, v16
	v_lshlrev_b32_e32 v16, 16, v17
	v_bfe_u32 v18, v17, 7, 8
	v_mul_f32_e32 v5, 0x437e0000, v5
	v_lshlrev_b32_e32 v19, 23, v18
	v_add_u32_e32 v18, -16, v18
	v_sub_f32_e32 v6, v6, v16
	v_and_b32_e32 v16, 0xffff0000, v17
	v_bfe_u32 v17, v17, 23, 8
	v_cndmask_b32_e32 v5, 0, v5, vcc
	v_sub_u32_e32 v19, 0x82800000, v19
	v_cmp_gt_u32_e32 vcc, s31, v18
	v_lshlrev_b32_e32 v18, 23, v17
	v_mul_f32_e32 v6, v6, v19
	v_sub_u32_e32 v18, 0x82800000, v18
	v_sub_f32_e32 v7, v7, v16
	v_mul_f32_e32 v6, 0x437e0000, v6
	v_add_u32_e32 v17, -16, v17
	v_mul_f32_e32 v7, v7, v18
	v_pk_mul_f32 v[38:39], v[114:115], v[22:23] op_sel_hi:[1,0]
	v_cndmask_b32_e32 v6, 0, v6, vcc
	v_mul_f32_e32 v7, 0x437e0000, v7
	v_cmp_gt_u32_e32 vcc, s31, v17
	v_med3_f32 v5, v5, s29, v204
	v_pk_mul_f32 v[32:33], v[32:33], v[22:23] op_sel_hi:[1,0]
	s_waitcnt vmcnt(17)
	v_pk_fma_f32 v[38:39], v[94:95], v[38:39], v[98:99]
	v_cndmask_b32_e32 v7, 0, v7, vcc
	v_med3_f32 v4, v4, s29, v204
	v_rndne_f32_e32 v5, v5
	v_med3_f32 v6, v6, s29, v204
	v_pk_fma_f32 v[32:33], v[96:97], v[32:33], v[100:101]
	v_mul_f32_e32 v82, 0x41fe0000, v39
	v_rndne_f32_e32 v4, v4
	v_cvt_i32_f32_e32 v5, v5
	v_rndne_f32_e32 v6, v6
	v_med3_f32 v7, v7, s29, v204
	v_mul_f32_e32 v23, 0x41fe0000, v38
	v_mul_f32_e32 v83, 0x41fe0000, v32
	v_mul_f32_e32 v84, 0x41fe0000, v33
	v_med3_f32 v82, v82, s29, v204
	v_cvt_i32_f32_e32 v4, v4
	v_cvt_i32_f32_sdwa v6, v6 dst_sel:WORD_1 dst_unused:UNUSED_PAD src0_sel:DWORD
	v_rndne_f32_e32 v7, v7
	v_med3_f32 v23, v23, s29, v204
	v_rndne_f32_e32 v82, v82
	v_med3_f32 v83, v83, s29, v204
	v_med3_f32 v84, v84, s29, v204
	v_cvt_i32_f32_sdwa v7, v7 dst_sel:BYTE_3 dst_unused:UNUSED_PAD src0_sel:DWORD
	v_rndne_f32_e32 v23, v23
	v_cvt_i32_f32_e32 v82, v82
	v_rndne_f32_e32 v83, v83
	v_rndne_f32_e32 v84, v84
	v_cvt_i32_f32_e32 v23, v23
	v_cvt_i32_f32_sdwa v83, v83 dst_sel:WORD_1 dst_unused:UNUSED_PAD src0_sel:DWORD
	v_cvt_i32_f32_e32 v84, v84
	v_lshlrev_b32_e32 v5, 8, v5
	v_perm_b32 v4, v5, v4, s33
	v_and_b32_e32 v5, 0xff0000, v6
	v_or3_b32 v4, v4, v7, v5
	v_lshlrev_b32_e32 v82, 8, v82
	global_store_dword v191, v4, s[22:23] offset:1792
	v_and_b32_e32 v82, 0xff00, v82
	v_and_b32_e32 v83, 0xff0000, v83
	v_perm_b32 v23, v84, v23, s30
	global_load_dwordx4 v[60:63], v[164:165], off
	global_load_dwordx4 v[78:81], v[166:167], off
	global_load_dwordx4 v[48:51], v[168:169], off
	global_load_dwordx4 v[52:55], v[170:171], off
	global_load_dwordx4 v[34:37], v[178:179], off
	global_load_dwordx4 v[44:47], v[180:181], off
	global_load_dwordx4 v[4:7], v[182:183], off
	global_load_dwordx4 v[16:19], v[184:185], off
	s_nop 0
	v_cvt_pk_bf16_f32 v64, v38, v39
	v_or3_b32 v23, v23, v82, v83
	v_bfe_u32 v82, v64, 7, 8
	s_nop 0
	v_cvt_pk_bf16_f32 v65, v32, v33
	global_store_dwordx2 v193, v[64:65], s[26:27]
	global_store_dword v191, v23, s[24:25] offset:2048
	v_lshlrev_b32_e32 v23, 16, v64
	v_lshlrev_b32_e32 v83, 23, v82
	v_sub_u32_e32 v83, 0x82800000, v83
	v_add_u32_e32 v82, -16, v82
	v_sub_f32_e32 v23, v38, v23
	v_and_b32_e32 v38, 0xffff0000, v64
	v_bfe_u32 v64, v64, 23, 8
	v_mul_f32_e32 v23, v23, v83
	v_cmp_gt_u32_e32 vcc, s31, v82
	v_lshlrev_b32_e32 v82, 23, v64
	v_mul_f32_e32 v23, 0x437e0000, v23
	v_sub_u32_e32 v82, 0x82800000, v82
	v_add_u32_e32 v64, -16, v64
	v_sub_f32_e32 v38, v39, v38
	v_cndmask_b32_e32 v23, 0, v23, vcc
	v_mul_f32_e32 v38, v38, v82
	v_cmp_gt_u32_e32 vcc, s31, v64
	v_bfe_u32 v64, v65, 7, 8
	v_mul_f32_e32 v38, 0x437e0000, v38
	v_lshlrev_b32_e32 v82, 23, v64
	v_add_u32_e32 v64, -16, v64
	v_cndmask_b32_e32 v38, 0, v38, vcc
	v_lshlrev_b32_e32 v39, 16, v65
	v_cmp_gt_u32_e32 vcc, s31, v64
	v_bfe_u32 v64, v65, 23, 8
	v_sub_u32_e32 v82, 0x82800000, v82
	v_sub_f32_e32 v32, v32, v39
	v_and_b32_e32 v39, 0xffff0000, v65
	v_lshlrev_b32_e32 v65, 23, v64
	v_mul_f32_e32 v32, v32, v82
	v_sub_u32_e32 v65, 0x82800000, v65
	v_sub_f32_e32 v33, v33, v39
	v_mul_f32_e32 v32, 0x437e0000, v32
	v_add_u32_e32 v64, -16, v64
	v_mul_f32_e32 v33, v33, v65
	v_cndmask_b32_e32 v32, 0, v32, vcc
	v_mul_f32_e32 v33, 0x437e0000, v33
	v_cmp_gt_u32_e32 vcc, s31, v64
	v_med3_f32 v38, v38, s29, v204
	v_med3_f32 v23, v23, s29, v204
	v_cndmask_b32_e32 v33, 0, v33, vcc
	v_rndne_f32_e32 v38, v38
	v_med3_f32 v32, v32, s29, v204
	v_rndne_f32_e32 v23, v23
	v_cvt_i32_f32_e32 v38, v38
	v_rndne_f32_e32 v32, v32
	v_med3_f32 v33, v33, s29, v204
	v_cvt_i32_f32_e32 v23, v23
	v_cvt_i32_f32_sdwa v32, v32 dst_sel:WORD_1 dst_unused:UNUSED_PAD src0_sel:DWORD
	v_rndne_f32_e32 v33, v33
	v_cvt_i32_f32_sdwa v33, v33 dst_sel:BYTE_3 dst_unused:UNUSED_PAD src0_sel:DWORD
	v_lshlrev_b32_e32 v38, 8, v38
	v_perm_b32 v23, v38, v23, s33
	v_and_b32_e32 v32, 0xff0000, v32
	v_or3_b32 v23, v23, v33, v32
	v_pk_mul_f32 v[26:27], v[26:27], v[22:23] op_sel_hi:[1,0]
	v_pk_mul_f32 v[32:33], v[112:113], v[22:23] op_sel_hi:[1,0]
	s_waitcnt vmcnt(26)
	v_pk_fma_f32 v[26:27], v[70:71], v[26:27], v[74:75]
	v_pk_fma_f32 v[32:33], v[72:73], v[32:33], v[76:77]
	v_mul_f32_e32 v64, 0x41fe0000, v27
	global_store_dword v191, v23, s[22:23] offset:2048
	v_mul_f32_e32 v23, 0x41fe0000, v26
	v_mul_f32_e32 v65, 0x41fe0000, v32
	v_mul_f32_e32 v70, 0x41fe0000, v33
	v_med3_f32 v64, v64, s29, v204
	v_med3_f32 v23, v23, s29, v204
	v_rndne_f32_e32 v64, v64
	v_med3_f32 v65, v65, s29, v204
	v_med3_f32 v70, v70, s29, v204
	v_rndne_f32_e32 v23, v23
	v_cvt_i32_f32_e32 v64, v64
	v_rndne_f32_e32 v65, v65
	v_rndne_f32_e32 v70, v70
	v_cvt_i32_f32_e32 v23, v23
	v_cvt_i32_f32_sdwa v65, v65 dst_sel:WORD_1 dst_unused:UNUSED_PAD src0_sel:DWORD
	v_cvt_i32_f32_e32 v70, v70
	v_lshlrev_b32_e32 v64, 8, v64
	v_and_b32_e32 v64, 0xff00, v64
	v_and_b32_e32 v65, 0xff0000, v65
	v_perm_b32 v23, v70, v23, s30
	s_nop 0
	v_cvt_pk_bf16_f32 v38, v26, v27
	v_or3_b32 v23, v23, v64, v65
	v_bfe_u32 v64, v38, 7, 8
	s_nop 0
	v_cvt_pk_bf16_f32 v39, v32, v33
	global_store_dwordx2 v195, v[38:39], s[26:27]
	global_store_dword v191, v23, s[24:25] offset:2304
	v_lshlrev_b32_e32 v23, 16, v38
	v_lshlrev_b32_e32 v65, 23, v64
	v_sub_u32_e32 v65, 0x82800000, v65
	v_add_u32_e32 v64, -16, v64
	v_sub_f32_e32 v23, v26, v23
	v_and_b32_e32 v26, 0xffff0000, v38
	v_bfe_u32 v38, v38, 23, 8
	v_mul_f32_e32 v23, v23, v65
	v_cmp_gt_u32_e32 vcc, s31, v64
	v_lshlrev_b32_e32 v64, 23, v38
	v_mul_f32_e32 v23, 0x437e0000, v23
	v_sub_u32_e32 v64, 0x82800000, v64
	v_add_u32_e32 v38, -16, v38
	v_sub_f32_e32 v26, v27, v26
	v_cndmask_b32_e32 v23, 0, v23, vcc
	v_mul_f32_e32 v26, v26, v64
	v_cmp_gt_u32_e32 vcc, s31, v38
	v_bfe_u32 v38, v39, 7, 8
	v_mul_f32_e32 v26, 0x437e0000, v26
	v_lshlrev_b32_e32 v64, 23, v38
	v_add_u32_e32 v38, -16, v38
	v_cndmask_b32_e32 v26, 0, v26, vcc
	v_lshlrev_b32_e32 v27, 16, v39
	v_cmp_gt_u32_e32 vcc, s31, v38
	v_bfe_u32 v38, v39, 23, 8
	v_sub_u32_e32 v64, 0x82800000, v64
	v_sub_f32_e32 v27, v32, v27
	v_and_b32_e32 v32, 0xffff0000, v39
	v_lshlrev_b32_e32 v39, 23, v38
	v_mul_f32_e32 v27, v27, v64
	v_sub_u32_e32 v39, 0x82800000, v39
	v_sub_f32_e32 v32, v33, v32
	v_mul_f32_e32 v27, 0x437e0000, v27
	v_add_u32_e32 v38, -16, v38
	v_mul_f32_e32 v32, v32, v39
	v_cndmask_b32_e32 v27, 0, v27, vcc
	v_mul_f32_e32 v32, 0x437e0000, v32
	v_cmp_gt_u32_e32 vcc, s31, v38
	v_med3_f32 v26, v26, s29, v204
	v_med3_f32 v23, v23, s29, v204
	v_cndmask_b32_e32 v32, 0, v32, vcc
	v_rndne_f32_e32 v26, v26
	v_med3_f32 v27, v27, s29, v204
	v_rndne_f32_e32 v23, v23
	v_cvt_i32_f32_e32 v26, v26
	v_rndne_f32_e32 v27, v27
	v_med3_f32 v32, v32, s29, v204
	v_cvt_i32_f32_e32 v23, v23
	v_cvt_i32_f32_sdwa v27, v27 dst_sel:WORD_1 dst_unused:UNUSED_PAD src0_sel:DWORD
	v_rndne_f32_e32 v32, v32
	v_cvt_i32_f32_sdwa v32, v32 dst_sel:BYTE_3 dst_unused:UNUSED_PAD src0_sel:DWORD
	v_lshlrev_b32_e32 v26, 8, v26
	v_perm_b32 v23, v26, v23, s33
	v_and_b32_e32 v26, 0xff0000, v27
	v_or3_b32 v23, v23, v32, v26
	v_pk_mul_f32 v[26:27], v[110:111], v[22:23] op_sel_hi:[1,0]
	v_pk_mul_f32 v[24:25], v[24:25], v[22:23] op_sel_hi:[1,0]
	s_waitcnt vmcnt(27)
	v_pk_fma_f32 v[26:27], v[26:27], v[56:57], v[66:67]
	v_pk_fma_f32 v[24:25], v[24:25], v[58:59], v[68:69]
	v_mul_f32_e32 v38, 0x41fe0000, v27
	global_store_dword v191, v23, s[22:23] offset:2304
	v_mul_f32_e32 v23, 0x41fe0000, v26
	v_mul_f32_e32 v39, 0x41fe0000, v24
	v_mul_f32_e32 v56, 0x41fe0000, v25
	v_med3_f32 v38, v38, s29, v204
	v_med3_f32 v23, v23, s29, v204
	v_rndne_f32_e32 v38, v38
	v_med3_f32 v39, v39, s29, v204
	v_med3_f32 v56, v56, s29, v204
	v_rndne_f32_e32 v23, v23
	v_cvt_i32_f32_e32 v38, v38
	v_rndne_f32_e32 v39, v39
	v_rndne_f32_e32 v56, v56
	v_cvt_i32_f32_e32 v23, v23
	v_cvt_i32_f32_sdwa v39, v39 dst_sel:WORD_1 dst_unused:UNUSED_PAD src0_sel:DWORD
	v_cvt_i32_f32_e32 v56, v56
	v_lshlrev_b32_e32 v38, 8, v38
	v_and_b32_e32 v38, 0xff00, v38
	v_and_b32_e32 v39, 0xff0000, v39
	v_perm_b32 v23, v56, v23, s30
	s_nop 0
	v_cvt_pk_bf16_f32 v32, v26, v27
	v_or3_b32 v23, v23, v38, v39
	v_bfe_u32 v38, v32, 7, 8
	s_nop 0
	v_cvt_pk_bf16_f32 v33, v24, v25
	global_store_dwordx2 v200, v[32:33], s[26:27]
	global_store_dword v191, v23, s[24:25] offset:2560
	v_lshlrev_b32_e32 v23, 16, v32
	v_lshlrev_b32_e32 v39, 23, v38
	v_sub_u32_e32 v39, 0x82800000, v39
	v_add_u32_e32 v38, -16, v38
	v_sub_f32_e32 v23, v26, v23
	v_and_b32_e32 v26, 0xffff0000, v32
	v_bfe_u32 v32, v32, 23, 8
	v_mul_f32_e32 v23, v23, v39
	v_cmp_gt_u32_e32 vcc, s31, v38
	v_lshlrev_b32_e32 v38, 23, v32
	v_mul_f32_e32 v23, 0x437e0000, v23
	v_sub_u32_e32 v38, 0x82800000, v38
	v_add_u32_e32 v32, -16, v32
	v_sub_f32_e32 v26, v27, v26
	v_cndmask_b32_e32 v23, 0, v23, vcc
	v_mul_f32_e32 v26, v26, v38
	v_cmp_gt_u32_e32 vcc, s31, v32
	v_bfe_u32 v32, v33, 7, 8
	v_mul_f32_e32 v26, 0x437e0000, v26
	v_lshlrev_b32_e32 v38, 23, v32
	v_add_u32_e32 v32, -16, v32
	v_cndmask_b32_e32 v26, 0, v26, vcc
	v_lshlrev_b32_e32 v27, 16, v33
	v_cmp_gt_u32_e32 vcc, s31, v32
	v_bfe_u32 v32, v33, 23, 8
	v_sub_u32_e32 v38, 0x82800000, v38
	v_sub_f32_e32 v24, v24, v27
	v_and_b32_e32 v27, 0xffff0000, v33
	v_lshlrev_b32_e32 v33, 23, v32
	v_mul_f32_e32 v24, v24, v38
	v_sub_u32_e32 v33, 0x82800000, v33
	v_sub_f32_e32 v25, v25, v27
	v_mul_f32_e32 v24, 0x437e0000, v24
	v_add_u32_e32 v32, -16, v32
	v_mul_f32_e32 v25, v25, v33
	v_cndmask_b32_e32 v24, 0, v24, vcc
	v_mul_f32_e32 v25, 0x437e0000, v25
	v_cmp_gt_u32_e32 vcc, s31, v32
	v_med3_f32 v26, v26, s29, v204
	v_med3_f32 v23, v23, s29, v204
	v_cndmask_b32_e32 v25, 0, v25, vcc
	v_rndne_f32_e32 v26, v26
	v_med3_f32 v24, v24, s29, v204
	v_rndne_f32_e32 v23, v23
	v_cvt_i32_f32_e32 v26, v26
	v_rndne_f32_e32 v24, v24
	v_med3_f32 v25, v25, s29, v204
	v_cvt_i32_f32_e32 v23, v23
	v_cvt_i32_f32_sdwa v24, v24 dst_sel:WORD_1 dst_unused:UNUSED_PAD src0_sel:DWORD
	v_rndne_f32_e32 v25, v25
	v_cvt_i32_f32_sdwa v25, v25 dst_sel:BYTE_3 dst_unused:UNUSED_PAD src0_sel:DWORD
	v_lshlrev_b32_e32 v26, 8, v26
	v_perm_b32 v23, v26, v23, s33
	v_and_b32_e32 v24, 0xff0000, v24
	v_or3_b32 v23, v23, v25, v24
	v_pk_mul_f32 v[24:25], v[108:109], v[22:23] op_sel_hi:[1,0]
	v_pk_mul_f32 v[20:21], v[20:21], v[22:23] op_sel_hi:[1,0]
	s_waitcnt vmcnt(28)
	v_pk_fma_f32 v[24:25], v[24:25], v[28:29], v[40:41]
	v_pk_fma_f32 v[20:21], v[20:21], v[30:31], v[42:43]
	v_mul_f32_e32 v28, 0x41fe0000, v25
	global_store_dword v191, v23, s[22:23] offset:2560
	v_mul_f32_e32 v23, 0x41fe0000, v24
	v_mul_f32_e32 v29, 0x41fe0000, v20
	v_mul_f32_e32 v30, 0x41fe0000, v21
	v_med3_f32 v28, v28, s29, v204
	v_med3_f32 v23, v23, s29, v204
	v_rndne_f32_e32 v28, v28
	v_med3_f32 v29, v29, s29, v204
	v_med3_f32 v30, v30, s29, v204
	v_rndne_f32_e32 v23, v23
	v_cvt_i32_f32_e32 v28, v28
	v_rndne_f32_e32 v29, v29
	v_rndne_f32_e32 v30, v30
	v_cvt_i32_f32_e32 v23, v23
	v_cvt_i32_f32_sdwa v29, v29 dst_sel:WORD_1 dst_unused:UNUSED_PAD src0_sel:DWORD
	v_cvt_i32_f32_e32 v30, v30
	v_lshlrev_b32_e32 v28, 8, v28
	v_and_b32_e32 v28, 0xff00, v28
	v_and_b32_e32 v29, 0xff0000, v29
	v_perm_b32 v23, v30, v23, s30
	s_nop 0
	v_cvt_pk_bf16_f32 v26, v24, v25
	v_or3_b32 v23, v23, v28, v29
	v_bfe_u32 v28, v26, 7, 8
	s_nop 0
	v_cvt_pk_bf16_f32 v27, v20, v21
	global_store_dwordx2 v194, v[26:27], s[26:27]
	global_store_dword v191, v23, s[24:25] offset:2816
	v_lshlrev_b32_e32 v23, 16, v26
	v_lshlrev_b32_e32 v29, 23, v28
	v_sub_u32_e32 v29, 0x82800000, v29
	v_add_u32_e32 v28, -16, v28
	v_sub_f32_e32 v23, v24, v23
	v_and_b32_e32 v24, 0xffff0000, v26
	v_bfe_u32 v26, v26, 23, 8
	v_mul_f32_e32 v23, v23, v29
	v_cmp_gt_u32_e32 vcc, s31, v28
	v_lshlrev_b32_e32 v28, 23, v26
	v_mul_f32_e32 v23, 0x437e0000, v23
	v_sub_u32_e32 v28, 0x82800000, v28
	v_add_u32_e32 v26, -16, v26
	v_sub_f32_e32 v24, v25, v24
	v_cndmask_b32_e32 v23, 0, v23, vcc
	v_mul_f32_e32 v24, v24, v28
	v_cmp_gt_u32_e32 vcc, s31, v26
	v_bfe_u32 v26, v27, 7, 8
	v_mul_f32_e32 v24, 0x437e0000, v24
	v_lshlrev_b32_e32 v28, 23, v26
	v_add_u32_e32 v26, -16, v26
	v_cndmask_b32_e32 v24, 0, v24, vcc
	v_lshlrev_b32_e32 v25, 16, v27
	v_cmp_gt_u32_e32 vcc, s31, v26
	v_bfe_u32 v26, v27, 23, 8
	v_sub_u32_e32 v28, 0x82800000, v28
	v_sub_f32_e32 v20, v20, v25
	v_and_b32_e32 v25, 0xffff0000, v27
	v_lshlrev_b32_e32 v27, 23, v26
	v_mul_f32_e32 v20, v20, v28
	v_sub_u32_e32 v27, 0x82800000, v27
	v_sub_f32_e32 v21, v21, v25
	v_mul_f32_e32 v20, 0x437e0000, v20
	v_add_u32_e32 v26, -16, v26
	v_mul_f32_e32 v21, v21, v27
	v_cndmask_b32_e32 v20, 0, v20, vcc
	v_mul_f32_e32 v21, 0x437e0000, v21
	v_cmp_gt_u32_e32 vcc, s31, v26
	v_med3_f32 v24, v24, s29, v204
	v_med3_f32 v23, v23, s29, v204
	v_cndmask_b32_e32 v21, 0, v21, vcc
	v_rndne_f32_e32 v24, v24
	v_med3_f32 v20, v20, s29, v204
	v_rndne_f32_e32 v23, v23
	v_cvt_i32_f32_e32 v24, v24
	v_rndne_f32_e32 v20, v20
	v_med3_f32 v21, v21, s29, v204
	v_cvt_i32_f32_e32 v23, v23
	v_cvt_i32_f32_sdwa v20, v20 dst_sel:WORD_1 dst_unused:UNUSED_PAD src0_sel:DWORD
	v_rndne_f32_e32 v21, v21
	v_cvt_i32_f32_sdwa v21, v21 dst_sel:BYTE_3 dst_unused:UNUSED_PAD src0_sel:DWORD
	v_lshlrev_b32_e32 v24, 8, v24
	v_perm_b32 v23, v24, v23, s33
	v_and_b32_e32 v20, 0xff0000, v20
	v_or3_b32 v20, v23, v21, v20
	v_pk_mul_f32 v[14:15], v[14:15], v[22:23] op_sel_hi:[1,0]
	global_store_dword v191, v20, s[22:23] offset:2816
	v_pk_mul_f32 v[20:21], v[106:107], v[22:23] op_sel_hi:[1,0]
	s_waitcnt vmcnt(18)
	v_pk_fma_f32 v[14:15], v[14:15], v[60:61], v[78:79]
	v_pk_fma_f32 v[20:21], v[20:21], v[62:63], v[80:81]
	v_mul_f32_e32 v26, 0x41fe0000, v15
	v_mul_f32_e32 v23, 0x41fe0000, v14
	v_mul_f32_e32 v27, 0x41fe0000, v20
	v_mul_f32_e32 v28, 0x41fe0000, v21
	v_med3_f32 v26, v26, s29, v204
	v_med3_f32 v23, v23, s29, v204
	v_rndne_f32_e32 v26, v26
	v_med3_f32 v27, v27, s29, v204
	v_med3_f32 v28, v28, s29, v204
	v_rndne_f32_e32 v23, v23
	v_cvt_i32_f32_e32 v26, v26
	v_rndne_f32_e32 v27, v27
	v_rndne_f32_e32 v28, v28
	v_cvt_i32_f32_e32 v23, v23
	v_cvt_i32_f32_sdwa v27, v27 dst_sel:WORD_1 dst_unused:UNUSED_PAD src0_sel:DWORD
	v_cvt_i32_f32_e32 v28, v28
	v_lshlrev_b32_e32 v26, 8, v26
	v_and_b32_e32 v26, 0xff00, v26
	v_and_b32_e32 v27, 0xff0000, v27
	v_perm_b32 v23, v28, v23, s30
	s_nop 0
	v_cvt_pk_bf16_f32 v24, v14, v15
	v_or3_b32 v23, v23, v26, v27
	v_bfe_u32 v26, v24, 7, 8
	s_nop 0
	v_cvt_pk_bf16_f32 v25, v20, v21
	global_store_dwordx2 v192, v[24:25], s[26:27]
	global_store_dword v191, v23, s[24:25] offset:3072
	v_lshlrev_b32_e32 v23, 16, v24
	v_lshlrev_b32_e32 v27, 23, v26
	v_sub_u32_e32 v27, 0x82800000, v27
	v_add_u32_e32 v26, -16, v26
	v_sub_f32_e32 v14, v14, v23
	v_and_b32_e32 v23, 0xffff0000, v24
	v_bfe_u32 v24, v24, 23, 8
	v_mul_f32_e32 v14, v14, v27
	v_cmp_gt_u32_e32 vcc, s31, v26
	v_lshlrev_b32_e32 v26, 23, v24
	v_mul_f32_e32 v14, 0x437e0000, v14
	v_sub_u32_e32 v26, 0x82800000, v26
	v_add_u32_e32 v24, -16, v24
	v_sub_f32_e32 v15, v15, v23
	v_cndmask_b32_e32 v14, 0, v14, vcc
	v_mul_f32_e32 v15, v15, v26
	v_cmp_gt_u32_e32 vcc, s31, v24
	v_bfe_u32 v24, v25, 7, 8
	v_mul_f32_e32 v15, 0x437e0000, v15
	v_lshlrev_b32_e32 v26, 23, v24
	v_add_u32_e32 v24, -16, v24
	v_cndmask_b32_e32 v15, 0, v15, vcc
	v_lshlrev_b32_e32 v23, 16, v25
	v_cmp_gt_u32_e32 vcc, s31, v24
	v_bfe_u32 v24, v25, 23, 8
	v_sub_u32_e32 v26, 0x82800000, v26
	v_sub_f32_e32 v20, v20, v23
	v_and_b32_e32 v23, 0xffff0000, v25
	v_lshlrev_b32_e32 v25, 23, v24
	v_mul_f32_e32 v20, v20, v26
	v_sub_u32_e32 v25, 0x82800000, v25
	v_sub_f32_e32 v21, v21, v23
	v_mul_f32_e32 v20, 0x437e0000, v20
	v_add_u32_e32 v24, -16, v24
	v_mul_f32_e32 v21, v21, v25
	v_cndmask_b32_e32 v20, 0, v20, vcc
	v_mul_f32_e32 v21, 0x437e0000, v21
	v_cmp_gt_u32_e32 vcc, s31, v24
	v_med3_f32 v15, v15, s29, v204
	v_med3_f32 v14, v14, s29, v204
	v_cndmask_b32_e32 v21, 0, v21, vcc
	v_rndne_f32_e32 v15, v15
	v_med3_f32 v20, v20, s29, v204
	v_rndne_f32_e32 v14, v14
	v_cvt_i32_f32_e32 v15, v15
	v_rndne_f32_e32 v20, v20
	v_med3_f32 v21, v21, s29, v204
	v_cvt_i32_f32_e32 v14, v14
	v_cvt_i32_f32_sdwa v20, v20 dst_sel:WORD_1 dst_unused:UNUSED_PAD src0_sel:DWORD
	v_rndne_f32_e32 v21, v21
	v_cvt_i32_f32_sdwa v21, v21 dst_sel:BYTE_3 dst_unused:UNUSED_PAD src0_sel:DWORD
	v_lshlrev_b32_e32 v15, 8, v15
	v_perm_b32 v14, v15, v14, s33
	v_and_b32_e32 v15, 0xff0000, v20
	v_or3_b32 v14, v14, v21, v15
	global_store_dword v191, v14, s[22:23] offset:3072
	v_pk_mul_f32 v[14:15], v[104:105], v[22:23] op_sel_hi:[1,0]
	v_pk_mul_f32 v[12:13], v[12:13], v[22:23] op_sel_hi:[1,0]
	s_waitcnt vmcnt(19)
	v_pk_fma_f32 v[14:15], v[14:15], v[48:49], v[52:53]
	v_pk_fma_f32 v[12:13], v[12:13], v[50:51], v[54:55]
	v_mul_f32_e32 v24, 0x41fe0000, v15
	v_mul_f32_e32 v23, 0x41fe0000, v14
	v_mul_f32_e32 v25, 0x41fe0000, v12
	v_mul_f32_e32 v26, 0x41fe0000, v13
	v_med3_f32 v24, v24, s29, v204
	v_med3_f32 v23, v23, s29, v204
	v_rndne_f32_e32 v24, v24
	v_med3_f32 v25, v25, s29, v204
	v_med3_f32 v26, v26, s29, v204
	v_rndne_f32_e32 v23, v23
	v_cvt_i32_f32_e32 v24, v24
	v_rndne_f32_e32 v25, v25
	v_rndne_f32_e32 v26, v26
	v_cvt_i32_f32_e32 v23, v23
	v_cvt_i32_f32_sdwa v25, v25 dst_sel:WORD_1 dst_unused:UNUSED_PAD src0_sel:DWORD
	v_cvt_i32_f32_e32 v26, v26
	v_lshlrev_b32_e32 v24, 8, v24
	v_and_b32_e32 v24, 0xff00, v24
	v_and_b32_e32 v25, 0xff0000, v25
	v_perm_b32 v23, v26, v23, s30
	s_nop 0
	v_cvt_pk_bf16_f32 v20, v14, v15
	v_or3_b32 v23, v23, v24, v25
	v_bfe_u32 v24, v20, 7, 8
	s_nop 0
	v_cvt_pk_bf16_f32 v21, v12, v13
	global_store_dwordx2 v190, v[20:21], s[26:27]
	global_store_dword v191, v23, s[24:25] offset:3328
	v_lshlrev_b32_e32 v23, 16, v20
	v_lshlrev_b32_e32 v25, 23, v24
	v_sub_u32_e32 v25, 0x82800000, v25
	v_add_u32_e32 v24, -16, v24
	v_sub_f32_e32 v14, v14, v23
	v_and_b32_e32 v23, 0xffff0000, v20
	v_bfe_u32 v20, v20, 23, 8
	v_mul_f32_e32 v14, v14, v25
	v_cmp_gt_u32_e32 vcc, s31, v24
	v_lshlrev_b32_e32 v24, 23, v20
	v_mul_f32_e32 v14, 0x437e0000, v14
	v_sub_u32_e32 v24, 0x82800000, v24
	v_add_u32_e32 v20, -16, v20
	v_sub_f32_e32 v15, v15, v23
	v_cndmask_b32_e32 v14, 0, v14, vcc
	v_mul_f32_e32 v15, v15, v24
	v_cmp_gt_u32_e32 vcc, s31, v20
	v_lshlrev_b32_e32 v20, 16, v21
	v_bfe_u32 v23, v21, 7, 8
	v_mul_f32_e32 v15, 0x437e0000, v15
	v_lshlrev_b32_e32 v24, 23, v23
	v_add_u32_e32 v23, -16, v23
	v_sub_f32_e32 v12, v12, v20
	v_and_b32_e32 v20, 0xffff0000, v21
	v_bfe_u32 v21, v21, 23, 8
	v_cndmask_b32_e32 v15, 0, v15, vcc
	v_sub_u32_e32 v24, 0x82800000, v24
	v_cmp_gt_u32_e32 vcc, s31, v23
	v_lshlrev_b32_e32 v23, 23, v21
	v_mul_f32_e32 v12, v12, v24
	v_sub_u32_e32 v23, 0x82800000, v23
	v_sub_f32_e32 v13, v13, v20
	v_mul_f32_e32 v12, 0x437e0000, v12
	v_add_u32_e32 v21, -16, v21
	v_mul_f32_e32 v13, v13, v23
	v_cndmask_b32_e32 v12, 0, v12, vcc
	v_mul_f32_e32 v13, 0x437e0000, v13
	v_cmp_gt_u32_e32 vcc, s31, v21
	v_med3_f32 v15, v15, s29, v204
	v_med3_f32 v14, v14, s29, v204
	v_cndmask_b32_e32 v13, 0, v13, vcc
	v_rndne_f32_e32 v15, v15
	v_med3_f32 v12, v12, s29, v204
	v_rndne_f32_e32 v14, v14
	v_cvt_i32_f32_e32 v15, v15
	v_rndne_f32_e32 v12, v12
	v_med3_f32 v13, v13, s29, v204
	v_cvt_i32_f32_e32 v14, v14
	v_cvt_i32_f32_sdwa v12, v12 dst_sel:WORD_1 dst_unused:UNUSED_PAD src0_sel:DWORD
	v_rndne_f32_e32 v13, v13
	v_cvt_i32_f32_sdwa v13, v13 dst_sel:BYTE_3 dst_unused:UNUSED_PAD src0_sel:DWORD
	v_lshlrev_b32_e32 v15, 8, v15
	v_perm_b32 v14, v15, v14, s33
	v_and_b32_e32 v12, 0xff0000, v12
	v_or3_b32 v12, v14, v13, v12
	global_store_dword v191, v12, s[22:23] offset:3328
	v_pk_mul_f32 v[12:13], v[102:103], v[22:23] op_sel_hi:[1,0]
	v_pk_mul_f32 v[8:9], v[8:9], v[22:23] op_sel_hi:[1,0]
	s_waitcnt vmcnt(20)
	v_pk_fma_f32 v[12:13], v[12:13], v[34:35], v[44:45]
	v_pk_fma_f32 v[8:9], v[8:9], v[36:37], v[46:47]
	v_mul_f32_e32 v21, 0x41fe0000, v13
	v_mul_f32_e32 v20, 0x41fe0000, v12
	v_mul_f32_e32 v23, 0x41fe0000, v8
	v_mul_f32_e32 v24, 0x41fe0000, v9
	v_med3_f32 v21, v21, s29, v204
	v_med3_f32 v20, v20, s29, v204
	v_rndne_f32_e32 v21, v21
	v_med3_f32 v23, v23, s29, v204
	v_med3_f32 v24, v24, s29, v204
	v_rndne_f32_e32 v20, v20
	v_cvt_i32_f32_e32 v21, v21
	v_rndne_f32_e32 v23, v23
	v_rndne_f32_e32 v24, v24
	v_cvt_i32_f32_e32 v20, v20
	v_cvt_i32_f32_sdwa v23, v23 dst_sel:WORD_1 dst_unused:UNUSED_PAD src0_sel:DWORD
	v_cvt_i32_f32_e32 v24, v24
	v_lshlrev_b32_e32 v21, 8, v21
	v_and_b32_e32 v21, 0xff00, v21
	v_and_b32_e32 v23, 0xff0000, v23
	v_perm_b32 v20, v24, v20, s30
	s_nop 0
	v_cvt_pk_bf16_f32 v14, v12, v13
	v_or3_b32 v20, v20, v21, v23
	v_bfe_u32 v21, v14, 7, 8
	s_nop 0
	v_cvt_pk_bf16_f32 v15, v8, v9
	global_store_dwordx2 v188, v[14:15], s[26:27]
	global_store_dword v191, v20, s[24:25] offset:3584
	v_lshlrev_b32_e32 v20, 16, v14
	v_lshlrev_b32_e32 v23, 23, v21
	v_sub_u32_e32 v23, 0x82800000, v23
	v_add_u32_e32 v21, -16, v21
	v_sub_f32_e32 v12, v12, v20
	v_and_b32_e32 v20, 0xffff0000, v14
	v_bfe_u32 v14, v14, 23, 8
	v_mul_f32_e32 v12, v12, v23
	v_cmp_gt_u32_e32 vcc, s31, v21
	v_lshlrev_b32_e32 v21, 23, v14
	v_mul_f32_e32 v12, 0x437e0000, v12
	v_sub_u32_e32 v21, 0x82800000, v21
	v_add_u32_e32 v14, -16, v14
	v_sub_f32_e32 v13, v13, v20
	v_cndmask_b32_e32 v12, 0, v12, vcc
	v_mul_f32_e32 v13, v13, v21
	v_cmp_gt_u32_e32 vcc, s31, v14
	v_lshlrev_b32_e32 v14, 16, v15
	v_bfe_u32 v20, v15, 7, 8
	v_mul_f32_e32 v13, 0x437e0000, v13
	v_lshlrev_b32_e32 v21, 23, v20
	v_add_u32_e32 v20, -16, v20
	v_sub_f32_e32 v8, v8, v14
	v_and_b32_e32 v14, 0xffff0000, v15
	v_bfe_u32 v15, v15, 23, 8
	v_cndmask_b32_e32 v13, 0, v13, vcc
	v_sub_u32_e32 v21, 0x82800000, v21
	v_cmp_gt_u32_e32 vcc, s31, v20
	v_lshlrev_b32_e32 v20, 23, v15
	v_mul_f32_e32 v8, v8, v21
	v_sub_u32_e32 v20, 0x82800000, v20
	v_sub_f32_e32 v9, v9, v14
	v_mul_f32_e32 v8, 0x437e0000, v8
	v_add_u32_e32 v15, -16, v15
	v_mul_f32_e32 v9, v9, v20
	v_cndmask_b32_e32 v8, 0, v8, vcc
	v_mul_f32_e32 v9, 0x437e0000, v9
	v_cmp_gt_u32_e32 vcc, s31, v15
	v_med3_f32 v13, v13, s29, v204
	v_med3_f32 v12, v12, s29, v204
	v_cndmask_b32_e32 v9, 0, v9, vcc
	v_rndne_f32_e32 v13, v13
	v_med3_f32 v8, v8, s29, v204
	v_rndne_f32_e32 v12, v12
	v_cvt_i32_f32_e32 v13, v13
	v_rndne_f32_e32 v8, v8
	v_med3_f32 v9, v9, s29, v204
	v_cvt_i32_f32_e32 v12, v12
	v_cvt_i32_f32_sdwa v8, v8 dst_sel:WORD_1 dst_unused:UNUSED_PAD src0_sel:DWORD
	v_rndne_f32_e32 v9, v9
	v_cvt_i32_f32_sdwa v9, v9 dst_sel:BYTE_3 dst_unused:UNUSED_PAD src0_sel:DWORD
	v_lshlrev_b32_e32 v13, 8, v13
	v_perm_b32 v12, v13, v12, s33
	v_and_b32_e32 v8, 0xff0000, v8
	v_or3_b32 v8, v12, v9, v8
	v_pk_mul_f32 v[2:3], v[2:3], v[22:23] op_sel_hi:[1,0]
	global_store_dword v191, v8, s[22:23] offset:3584
	v_pk_mul_f32 v[8:9], v[10:11], v[22:23] op_sel_hi:[1,0]
	s_waitcnt vmcnt(21)
	v_pk_fma_f32 v[2:3], v[2:3], v[4:5], v[16:17]
	v_pk_fma_f32 v[6:7], v[8:9], v[6:7], v[18:19]
	v_mul_f32_e32 v9, 0x41fe0000, v3
	v_mul_f32_e32 v8, 0x41fe0000, v2
	v_mul_f32_e32 v10, 0x41fe0000, v6
	v_mul_f32_e32 v11, 0x41fe0000, v7
	v_med3_f32 v9, v9, s29, v204
	v_med3_f32 v8, v8, s29, v204
	v_rndne_f32_e32 v9, v9
	v_med3_f32 v10, v10, s29, v204
	v_med3_f32 v11, v11, s29, v204
	v_rndne_f32_e32 v8, v8
	v_cvt_i32_f32_e32 v9, v9
	v_rndne_f32_e32 v10, v10
	v_rndne_f32_e32 v11, v11
	v_cvt_i32_f32_e32 v8, v8
	v_cvt_i32_f32_sdwa v10, v10 dst_sel:WORD_1 dst_unused:UNUSED_PAD src0_sel:DWORD
	v_cvt_i32_f32_e32 v11, v11
	v_lshlrev_b32_e32 v9, 8, v9
	v_and_b32_e32 v9, 0xff00, v9
	v_and_b32_e32 v10, 0xff0000, v10
	v_perm_b32 v8, v11, v8, s30
	s_nop 0
	v_cvt_pk_bf16_f32 v4, v2, v3
	v_or3_b32 v8, v8, v9, v10
	v_bfe_u32 v9, v4, 7, 8
	s_nop 0
	v_cvt_pk_bf16_f32 v5, v6, v7
	global_store_dwordx2 v201, v[4:5], s[26:27]
	global_store_dword v186, v8, s[24:25]
	v_lshlrev_b32_e32 v8, 16, v4
	v_lshlrev_b32_e32 v10, 23, v9
	v_sub_u32_e32 v10, 0x82800000, v10
	v_add_u32_e32 v9, -16, v9
	v_sub_f32_e32 v2, v2, v8
	v_and_b32_e32 v8, 0xffff0000, v4
	v_bfe_u32 v4, v4, 23, 8
	v_mul_f32_e32 v2, v2, v10
	v_cmp_gt_u32_e32 vcc, s31, v9
	v_lshlrev_b32_e32 v9, 23, v4
	v_mul_f32_e32 v2, 0x437e0000, v2
	v_sub_u32_e32 v9, 0x82800000, v9
	v_add_u32_e32 v4, -16, v4
	v_sub_f32_e32 v3, v3, v8
	v_cndmask_b32_e32 v2, 0, v2, vcc
	v_mul_f32_e32 v3, v3, v9
	v_cmp_gt_u32_e32 vcc, s31, v4
	v_lshlrev_b32_e32 v4, 16, v5
	v_bfe_u32 v8, v5, 7, 8
	v_mul_f32_e32 v3, 0x437e0000, v3
	v_lshlrev_b32_e32 v9, 23, v8
	v_add_u32_e32 v8, -16, v8
	v_sub_f32_e32 v4, v6, v4
	v_and_b32_e32 v6, 0xffff0000, v5
	v_bfe_u32 v5, v5, 23, 8
	v_cndmask_b32_e32 v3, 0, v3, vcc
	v_sub_u32_e32 v9, 0x82800000, v9
	v_cmp_gt_u32_e32 vcc, s31, v8
	v_lshlrev_b32_e32 v8, 23, v5
	v_mul_f32_e32 v4, v4, v9
	v_sub_u32_e32 v8, 0x82800000, v8
	v_sub_f32_e32 v6, v7, v6
	v_mul_f32_e32 v4, 0x437e0000, v4
	v_add_u32_e32 v5, -16, v5
	v_mul_f32_e32 v6, v6, v8
	v_cndmask_b32_e32 v4, 0, v4, vcc
	v_mul_f32_e32 v6, 0x437e0000, v6
	v_cmp_gt_u32_e32 vcc, s31, v5
	v_med3_f32 v3, v3, s29, v204
	v_med3_f32 v2, v2, s29, v204
	v_cndmask_b32_e32 v5, 0, v6, vcc
	v_rndne_f32_e32 v3, v3
	v_med3_f32 v4, v4, s29, v204
	v_rndne_f32_e32 v2, v2
	v_cvt_i32_f32_e32 v3, v3
	v_rndne_f32_e32 v4, v4
	v_med3_f32 v5, v5, s29, v204
	v_cvt_i32_f32_e32 v2, v2
	v_cvt_i32_f32_sdwa v4, v4 dst_sel:WORD_1 dst_unused:UNUSED_PAD src0_sel:DWORD
	v_rndne_f32_e32 v5, v5
	v_cvt_i32_f32_sdwa v5, v5 dst_sel:BYTE_3 dst_unused:UNUSED_PAD src0_sel:DWORD
	v_lshlrev_b32_e32 v3, 8, v3
	v_perm_b32 v2, v3, v2, s33
	v_and_b32_e32 v3, 0xff0000, v4
	v_or3_b32 v2, v2, v5, v3
	global_store_dword v186, v2, s[22:23]
	s_branch .LBB0_228
